# SGU unit4 phase1: preload the 16 row-chunk loads and batch ln_g/ln_b loads (was 80 serialized vmcnt(0) round trips), both layers
# speedup vs baseline: 1.0065x; 1.0065x over previous
.LBB0_402:
	s_or_b64 exec, exec, s[8:9]
	v_mov_b32_e32 v108, v224
	s_waitcnt vmcnt(0)
	s_barrier
	s_load_dwordx8 s[8:15], s[36:37], 0x40
	s_movk_i32 s16, 0x80
	v_readfirstlane_b32 s39, v108
	s_ashr_i32 s41, s39, 7
	s_cmp_eq_u32 s41, 2
	s_cselect_b32 s16, s16, 0x100
	s_cmp_lg_u32 s41, 1
	s_cselect_b32 s16, s16, 0
	s_cmpk_gt_u32 s39, 0x7f
	s_cselect_b32 s16, s16, 0xffffff80
	s_add_i32 s16, s16, s64
	s_mov_b32 s17, 0
	s_lshr_b32 s16, s16, 2
	v_and_b32_e32 v109, 0x7f, v108
	s_lshl_b64 s[18:19], s[16:17], 7
	v_or_b32_e32 v2, s18, v109
	s_movk_i32 s16, 0x1400
	v_mov_b64_e32 v[0:1], s[22:23]
	v_mad_u64_u32 v[0:1], s[26:27], v2, s16, v[0:1]
	s_lshl_b32 s16, s64, 7
	v_mov_b32_e32 v2, 0x1400
	s_and_b32 s37, s16, 0x180
	v_mad_u32_u24 v1, s19, v2, v1
	s_lshl_b32 s16, s37, 1
	v_lshl_add_u64 v[4:5], v[0:1], 0, s[16:17]
	s_movk_i32 s17, 0x1000
	v_add_co_u32_e32 v0, vcc, s17, v4
	s_mov_b32 s38, 0x3d372713
	s_nop 0
	v_addc_co_u32_e32 v1, vcc, 0, v5, vcc
	global_load_dwordx4 v[0:3], v[0:1], off
	s_mov_b32 s36, 0xc0135761
	s_mov_b64 s[26:27], 0x1000
	v_lshl_add_u64 v[4:5], v[4:5], 0, s[26:27]
	global_load_dwordx4 v[172:175], v[4:5], off offset:16
	global_load_dwordx4 v[176:179], v[4:5], off offset:32
	global_load_dwordx4 v[180:183], v[4:5], off offset:48
	global_load_dwordx4 v[184:187], v[4:5], off offset:64
	global_load_dwordx4 v[188:191], v[4:5], off offset:80
	global_load_dwordx4 v[192:195], v[4:5], off offset:96
	global_load_dwordx4 v[196:199], v[4:5], off offset:112
	global_load_dwordx4 v[200:203], v[4:5], off offset:128
	global_load_dwordx4 v[204:207], v[4:5], off offset:144
	global_load_dwordx4 v[208:211], v[4:5], off offset:160
	global_load_dwordx4 v[212:215], v[4:5], off offset:176
	global_load_dwordx4 v[216:219], v[4:5], off offset:192
	global_load_dwordx4 v[220:223], v[4:5], off offset:208
	global_load_dwordx4 v[228:231], v[4:5], off offset:224
	global_load_dwordx4 v[232:235], v[4:5], off offset:240
	s_lshl_b32 s17, s37, 2
	s_brev_b32 s40, 60
	s_waitcnt vmcnt(15)
	v_lshlrev_b32_e32 v6, 16, v0
	v_and_b32_e32 v7, 0xffff0000, v0
	v_lshlrev_b32_e32 v0, 16, v1
	v_and_b32_e32 v1, 0xffff0000, v1
	v_lshlrev_b32_e32 v8, 16, v2
	v_and_b32_e32 v9, 0xffff0000, v2
	v_lshlrev_b32_e32 v2, 16, v3
	v_and_b32_e32 v3, 0xffff0000, v3
	v_pk_mul_f32 v[10:11], v[6:7], v[6:7]
	v_pk_mul_f32 v[12:13], v[0:1], v[0:1]
	v_pk_mul_f32 v[14:15], v[8:9], v[8:9]
	v_pk_mul_f32 v[16:17], v[2:3], v[2:3]
	v_pk_fma_f32 v[10:11], v[10:11], s[38:39], 1.0 op_sel_hi:[1,0,0]
	v_pk_fma_f32 v[12:13], v[12:13], s[38:39], 1.0 op_sel_hi:[1,0,0]
	v_pk_fma_f32 v[14:15], v[14:15], s[38:39], 1.0 op_sel_hi:[1,0,0]
	v_pk_fma_f32 v[16:17], v[16:17], s[38:39], 1.0 op_sel_hi:[1,0,0]
	v_pk_mul_f32 v[10:11], v[10:11], v[6:7]
	v_pk_mul_f32 v[12:13], v[12:13], v[0:1]
	v_pk_mul_f32 v[14:15], v[14:15], v[8:9]
	v_pk_mul_f32 v[16:17], v[16:17], v[2:3]
	v_pk_mul_f32 v[10:11], v[10:11], s[36:37] op_sel_hi:[1,0]
	v_pk_mul_f32 v[12:13], v[12:13], s[36:37] op_sel_hi:[1,0]
	v_pk_mul_f32 v[14:15], v[14:15], s[36:37] op_sel_hi:[1,0]
	v_pk_mul_f32 v[16:17], v[16:17], s[36:37] op_sel_hi:[1,0]
	v_exp_f32_e32 v10, v10
	v_exp_f32_e32 v11, v11
	v_exp_f32_e32 v12, v12
	v_exp_f32_e32 v13, v13
	v_exp_f32_e32 v14, v14
	v_exp_f32_e32 v15, v15
	v_exp_f32_e32 v16, v16
	v_exp_f32_e32 v17, v17
	v_pk_add_f32 v[10:11], v[10:11], 1.0 op_sel_hi:[1,0]
	v_pk_add_f32 v[12:13], v[12:13], 1.0 op_sel_hi:[1,0]
	v_pk_add_f32 v[18:19], v[14:15], 1.0 op_sel_hi:[1,0]
	v_pk_add_f32 v[16:17], v[16:17], 1.0 op_sel_hi:[1,0]
	v_rcp_f32_e32 v14, v10
	v_rcp_f32_e32 v15, v11
	v_rcp_f32_e32 v10, v12
	v_rcp_f32_e32 v11, v13
	v_rcp_f32_e32 v12, v18
	v_rcp_f32_e32 v13, v19
	v_rcp_f32_e32 v18, v16
	v_rcp_f32_e32 v19, v17
	v_pk_mul_f32 v[16:17], v[14:15], v[6:7]
	v_pk_mul_f32 v[10:11], v[10:11], v[0:1]
	v_pk_mul_f32 v[8:9], v[12:13], v[8:9]
	v_pk_mul_f32 v[12:13], v[18:19], v[2:3]
	v_cvt_pk_bf16_f32 v114, v16, v17
	v_cvt_pk_bf16_f32 v112, v10, v11
	v_cvt_pk_bf16_f32 v111, v8, v9
	v_pk_fma_f32 v[6:7], v[14:15], v[6:7], v[16:17] op_sel_hi:[1,1,0]
	v_cvt_pk_bf16_f32 v110, v12, v13
	v_pk_mul_f32 v[14:15], v[16:17], v[16:17]
	v_pk_mul_f32 v[16:17], v[10:11], v[10:11]
	v_mov_b32_e32 v165, v10
	v_mov_b32_e32 v164, v14
	v_mov_b32_e32 v10, v15
	v_mov_b32_e32 v6, v16
	v_mov_b32_e32 v167, v8
	v_pk_add_f32 v[10:11], v[164:165], v[10:11]
	v_pk_mul_f32 v[162:163], v[12:13], v[12:13]
	v_mov_b32_e32 v169, v12
	v_mov_b32_e32 v168, v162
	v_mov_b32_e32 v12, v163
	v_pk_add_f32 v[12:13], v[168:169], v[12:13]
	s_waitcnt vmcnt(14)
	v_mov_b32_e32 v0, v172
	v_mov_b32_e32 v1, v173
	v_mov_b32_e32 v2, v174
	v_mov_b32_e32 v3, v175
	v_lshlrev_b32_e32 v18, 16, v0
	v_and_b32_e32 v19, 0xffff0000, v0
	v_lshlrev_b32_e32 v0, 16, v1
	v_and_b32_e32 v1, 0xffff0000, v1
	v_lshlrev_b32_e32 v24, 16, v2
	v_and_b32_e32 v25, 0xffff0000, v2
	v_lshlrev_b32_e32 v2, 16, v3
	v_and_b32_e32 v3, 0xffff0000, v3
	v_pk_mul_f32 v[20:21], v[18:19], v[18:19]
	v_pk_mul_f32 v[22:23], v[0:1], v[0:1]
	v_pk_mul_f32 v[26:27], v[24:25], v[24:25]
	v_pk_mul_f32 v[28:29], v[2:3], v[2:3]
	v_pk_fma_f32 v[20:21], v[20:21], s[38:39], 1.0 op_sel_hi:[1,0,0]
	v_pk_fma_f32 v[22:23], v[22:23], s[38:39], 1.0 op_sel_hi:[1,0,0]
	v_pk_fma_f32 v[26:27], v[26:27], s[38:39], 1.0 op_sel_hi:[1,0,0]
	v_pk_fma_f32 v[28:29], v[28:29], s[38:39], 1.0 op_sel_hi:[1,0,0]
	v_pk_mul_f32 v[20:21], v[20:21], v[18:19]
	v_pk_mul_f32 v[22:23], v[22:23], v[0:1]
	v_pk_mul_f32 v[26:27], v[26:27], v[24:25]
	v_pk_mul_f32 v[28:29], v[28:29], v[2:3]
	v_pk_mul_f32 v[20:21], v[20:21], s[36:37] op_sel_hi:[1,0]
	v_pk_mul_f32 v[22:23], v[22:23], s[36:37] op_sel_hi:[1,0]
	v_pk_mul_f32 v[26:27], v[26:27], s[36:37] op_sel_hi:[1,0]
	v_pk_mul_f32 v[28:29], v[28:29], s[36:37] op_sel_hi:[1,0]
	v_exp_f32_e32 v20, v20
	v_exp_f32_e32 v21, v21
	v_exp_f32_e32 v22, v22
	v_exp_f32_e32 v23, v23
	v_exp_f32_e32 v26, v26
	v_exp_f32_e32 v27, v27
	v_exp_f32_e32 v28, v28
	v_exp_f32_e32 v29, v29
	v_pk_add_f32 v[20:21], v[20:21], 1.0 op_sel_hi:[1,0]
	v_pk_add_f32 v[22:23], v[22:23], 1.0 op_sel_hi:[1,0]
	v_pk_add_f32 v[26:27], v[26:27], 1.0 op_sel_hi:[1,0]
	v_pk_add_f32 v[28:29], v[28:29], 1.0 op_sel_hi:[1,0]
	v_rcp_f32_e32 v20, v20
	v_rcp_f32_e32 v21, v21
	v_rcp_f32_e32 v30, v22
	v_rcp_f32_e32 v31, v23
	v_rcp_f32_e32 v26, v26
	v_rcp_f32_e32 v27, v27
	v_rcp_f32_e32 v28, v28
	v_rcp_f32_e32 v29, v29
	v_pk_mul_f32 v[22:23], v[20:21], v[18:19]
	v_pk_mul_f32 v[20:21], v[30:31], v[0:1]
	v_pk_mul_f32 v[18:19], v[26:27], v[24:25]
	v_pk_mul_f32 v[24:25], v[28:29], v[2:3]
	v_cvt_pk_bf16_f32 v117, v22, v23
	v_cvt_pk_bf16_f32 v116, v20, v21
	v_cvt_pk_bf16_f32 v115, v18, v19
	v_mov_b32_e32 v163, v18
	v_cvt_pk_bf16_f32 v113, v24, v25
	v_pk_mul_f32 v[14:15], v[24:25], v[24:25]
	v_mov_b32_e32 v165, v24
	v_mov_b32_e32 v164, v14
	v_mov_b32_e32 v24, v15
	v_pk_add_f32 v[14:15], v[164:165], v[24:25]
	s_waitcnt vmcnt(13)
	v_mov_b32_e32 v0, v176
	v_mov_b32_e32 v1, v177
	v_mov_b32_e32 v2, v178
	v_mov_b32_e32 v3, v179
	v_lshlrev_b32_e32 v26, 16, v0
	v_and_b32_e32 v27, 0xffff0000, v0
	v_lshlrev_b32_e32 v0, 16, v1
	v_and_b32_e32 v1, 0xffff0000, v1
	v_lshlrev_b32_e32 v32, 16, v2
	v_and_b32_e32 v33, 0xffff0000, v2
	v_lshlrev_b32_e32 v2, 16, v3
	v_and_b32_e32 v3, 0xffff0000, v3
	v_pk_mul_f32 v[28:29], v[26:27], v[26:27]
	v_pk_mul_f32 v[30:31], v[0:1], v[0:1]
	v_pk_mul_f32 v[34:35], v[32:33], v[32:33]
	v_pk_mul_f32 v[36:37], v[2:3], v[2:3]
	v_pk_fma_f32 v[28:29], v[28:29], s[38:39], 1.0 op_sel_hi:[1,0,0]
	v_pk_fma_f32 v[30:31], v[30:31], s[38:39], 1.0 op_sel_hi:[1,0,0]
	v_pk_fma_f32 v[34:35], v[34:35], s[38:39], 1.0 op_sel_hi:[1,0,0]
	v_pk_fma_f32 v[36:37], v[36:37], s[38:39], 1.0 op_sel_hi:[1,0,0]
	v_pk_mul_f32 v[28:29], v[28:29], v[26:27]
	v_pk_mul_f32 v[30:31], v[30:31], v[0:1]
	v_pk_mul_f32 v[34:35], v[34:35], v[32:33]
	v_pk_mul_f32 v[36:37], v[36:37], v[2:3]
	v_pk_mul_f32 v[28:29], v[28:29], s[36:37] op_sel_hi:[1,0]
	v_pk_mul_f32 v[30:31], v[30:31], s[36:37] op_sel_hi:[1,0]
	v_pk_mul_f32 v[34:35], v[34:35], s[36:37] op_sel_hi:[1,0]
	v_pk_mul_f32 v[36:37], v[36:37], s[36:37] op_sel_hi:[1,0]
	v_exp_f32_e32 v28, v28
	v_exp_f32_e32 v29, v29
	v_exp_f32_e32 v30, v30
	v_exp_f32_e32 v31, v31
	v_exp_f32_e32 v34, v34
	v_exp_f32_e32 v35, v35
	v_exp_f32_e32 v36, v36
	v_exp_f32_e32 v37, v37
	v_pk_add_f32 v[28:29], v[28:29], 1.0 op_sel_hi:[1,0]
	v_pk_add_f32 v[30:31], v[30:31], 1.0 op_sel_hi:[1,0]
	v_pk_add_f32 v[34:35], v[34:35], 1.0 op_sel_hi:[1,0]
	v_pk_add_f32 v[36:37], v[36:37], 1.0 op_sel_hi:[1,0]
	v_rcp_f32_e32 v28, v28
	v_rcp_f32_e32 v29, v29
	v_rcp_f32_e32 v38, v30
	v_rcp_f32_e32 v39, v31
	v_rcp_f32_e32 v34, v34
	v_rcp_f32_e32 v35, v35
	v_rcp_f32_e32 v36, v36
	v_rcp_f32_e32 v37, v37
	v_pk_mul_f32 v[30:31], v[28:29], v[26:27]
	v_pk_mul_f32 v[28:29], v[38:39], v[0:1]
	v_pk_mul_f32 v[26:27], v[34:35], v[32:33]
	v_pk_mul_f32 v[32:33], v[36:37], v[2:3]
	v_cvt_pk_bf16_f32 v122, v30, v31
	v_cvt_pk_bf16_f32 v120, v28, v29
	v_cvt_pk_bf16_f32 v119, v26, v27
	s_nop 0
	v_cvt_pk_bf16_f32 v118, v32, v33
	s_waitcnt vmcnt(12)
	v_mov_b32_e32 v0, v180
	v_mov_b32_e32 v1, v181
	v_mov_b32_e32 v2, v182
	v_mov_b32_e32 v3, v183
	v_lshlrev_b32_e32 v34, 16, v0
	v_and_b32_e32 v35, 0xffff0000, v0
	v_lshlrev_b32_e32 v0, 16, v1
	v_and_b32_e32 v1, 0xffff0000, v1
	v_lshlrev_b32_e32 v40, 16, v2
	v_and_b32_e32 v41, 0xffff0000, v2
	v_lshlrev_b32_e32 v2, 16, v3
	v_and_b32_e32 v3, 0xffff0000, v3
	v_pk_mul_f32 v[36:37], v[34:35], v[34:35]
	v_pk_mul_f32 v[38:39], v[0:1], v[0:1]
	v_pk_mul_f32 v[42:43], v[40:41], v[40:41]
	v_pk_mul_f32 v[44:45], v[2:3], v[2:3]
	v_pk_fma_f32 v[36:37], v[36:37], s[38:39], 1.0 op_sel_hi:[1,0,0]
	v_pk_fma_f32 v[38:39], v[38:39], s[38:39], 1.0 op_sel_hi:[1,0,0]
	v_pk_fma_f32 v[42:43], v[42:43], s[38:39], 1.0 op_sel_hi:[1,0,0]
	v_pk_fma_f32 v[44:45], v[44:45], s[38:39], 1.0 op_sel_hi:[1,0,0]
	v_pk_mul_f32 v[36:37], v[36:37], v[34:35]
	v_pk_mul_f32 v[38:39], v[38:39], v[0:1]
	v_pk_mul_f32 v[42:43], v[42:43], v[40:41]
	v_pk_mul_f32 v[44:45], v[44:45], v[2:3]
	v_pk_mul_f32 v[36:37], v[36:37], s[36:37] op_sel_hi:[1,0]
	v_pk_mul_f32 v[38:39], v[38:39], s[36:37] op_sel_hi:[1,0]
	v_pk_mul_f32 v[42:43], v[42:43], s[36:37] op_sel_hi:[1,0]
	v_pk_mul_f32 v[44:45], v[44:45], s[36:37] op_sel_hi:[1,0]
	v_exp_f32_e32 v36, v36
	v_exp_f32_e32 v37, v37
	v_exp_f32_e32 v38, v38
	v_exp_f32_e32 v39, v39
	v_exp_f32_e32 v42, v42
	v_exp_f32_e32 v43, v43
	v_exp_f32_e32 v44, v44
	v_exp_f32_e32 v45, v45
	v_pk_add_f32 v[36:37], v[36:37], 1.0 op_sel_hi:[1,0]
	v_pk_add_f32 v[38:39], v[38:39], 1.0 op_sel_hi:[1,0]
	v_pk_add_f32 v[42:43], v[42:43], 1.0 op_sel_hi:[1,0]
	v_pk_add_f32 v[44:45], v[44:45], 1.0 op_sel_hi:[1,0]
	v_rcp_f32_e32 v36, v36
	v_rcp_f32_e32 v37, v37
	v_rcp_f32_e32 v46, v38
	v_rcp_f32_e32 v47, v39
	v_rcp_f32_e32 v42, v42
	v_rcp_f32_e32 v43, v43
	v_rcp_f32_e32 v44, v44
	v_rcp_f32_e32 v45, v45
	v_pk_mul_f32 v[38:39], v[36:37], v[34:35]
	v_pk_mul_f32 v[36:37], v[46:47], v[0:1]
	v_pk_mul_f32 v[34:35], v[42:43], v[40:41]
	v_pk_mul_f32 v[40:41], v[44:45], v[2:3]
	v_cvt_pk_bf16_f32 v126, v38, v39
	v_cvt_pk_bf16_f32 v124, v36, v37
	v_cvt_pk_bf16_f32 v123, v34, v35
	v_pk_mul_f32 v[24:25], v[36:37], v[36:37]
	v_cvt_pk_bf16_f32 v121, v40, v41
	s_waitcnt vmcnt(11)
	v_mov_b32_e32 v0, v184
	v_mov_b32_e32 v1, v185
	v_mov_b32_e32 v2, v186
	v_mov_b32_e32 v3, v187
	v_lshlrev_b32_e32 v42, 16, v0
	v_and_b32_e32 v43, 0xffff0000, v0
	v_lshlrev_b32_e32 v0, 16, v1
	v_and_b32_e32 v1, 0xffff0000, v1
	v_lshlrev_b32_e32 v48, 16, v2
	v_and_b32_e32 v49, 0xffff0000, v2
	v_lshlrev_b32_e32 v2, 16, v3
	v_and_b32_e32 v3, 0xffff0000, v3
	v_pk_mul_f32 v[44:45], v[42:43], v[42:43]
	v_pk_mul_f32 v[46:47], v[0:1], v[0:1]
	v_pk_mul_f32 v[50:51], v[48:49], v[48:49]
	v_pk_mul_f32 v[52:53], v[2:3], v[2:3]
	v_pk_fma_f32 v[44:45], v[44:45], s[38:39], 1.0 op_sel_hi:[1,0,0]
	v_pk_fma_f32 v[46:47], v[46:47], s[38:39], 1.0 op_sel_hi:[1,0,0]
	v_pk_fma_f32 v[50:51], v[50:51], s[38:39], 1.0 op_sel_hi:[1,0,0]
	v_pk_fma_f32 v[52:53], v[52:53], s[38:39], 1.0 op_sel_hi:[1,0,0]
	v_pk_mul_f32 v[44:45], v[44:45], v[42:43]
	v_pk_mul_f32 v[46:47], v[46:47], v[0:1]
	v_pk_mul_f32 v[50:51], v[50:51], v[48:49]
	v_pk_mul_f32 v[52:53], v[52:53], v[2:3]
	v_pk_mul_f32 v[44:45], v[44:45], s[36:37] op_sel_hi:[1,0]
	v_pk_mul_f32 v[46:47], v[46:47], s[36:37] op_sel_hi:[1,0]
	v_pk_mul_f32 v[50:51], v[50:51], s[36:37] op_sel_hi:[1,0]
	v_pk_mul_f32 v[52:53], v[52:53], s[36:37] op_sel_hi:[1,0]
	v_exp_f32_e32 v44, v44
	v_exp_f32_e32 v45, v45
	v_exp_f32_e32 v46, v46
	v_exp_f32_e32 v47, v47
	v_exp_f32_e32 v50, v50
	v_exp_f32_e32 v51, v51
	v_exp_f32_e32 v52, v52
	v_exp_f32_e32 v53, v53
	v_pk_add_f32 v[44:45], v[44:45], 1.0 op_sel_hi:[1,0]
	v_pk_add_f32 v[46:47], v[46:47], 1.0 op_sel_hi:[1,0]
	v_pk_add_f32 v[50:51], v[50:51], 1.0 op_sel_hi:[1,0]
	v_pk_add_f32 v[52:53], v[52:53], 1.0 op_sel_hi:[1,0]
	v_rcp_f32_e32 v44, v44
	v_rcp_f32_e32 v45, v45
	v_rcp_f32_e32 v54, v46
	v_rcp_f32_e32 v55, v47
	v_rcp_f32_e32 v50, v50
	v_rcp_f32_e32 v51, v51
	v_rcp_f32_e32 v52, v52
	v_rcp_f32_e32 v53, v53
	v_pk_mul_f32 v[46:47], v[44:45], v[42:43]
	v_pk_mul_f32 v[44:45], v[54:55], v[0:1]
	v_pk_mul_f32 v[42:43], v[50:51], v[48:49]
	v_pk_mul_f32 v[48:49], v[52:53], v[2:3]
	v_cvt_pk_bf16_f32 v129, v46, v47
	v_cvt_pk_bf16_f32 v128, v44, v45
	v_cvt_pk_bf16_f32 v127, v42, v43
	s_nop 0
	v_cvt_pk_bf16_f32 v125, v48, v49
	s_waitcnt vmcnt(10)
	v_mov_b32_e32 v0, v188
	v_mov_b32_e32 v1, v189
	v_mov_b32_e32 v2, v190
	v_mov_b32_e32 v3, v191
	v_lshlrev_b32_e32 v50, 16, v0
	v_and_b32_e32 v51, 0xffff0000, v0
	v_lshlrev_b32_e32 v0, 16, v1
	v_and_b32_e32 v1, 0xffff0000, v1
	v_lshlrev_b32_e32 v56, 16, v2
	v_and_b32_e32 v57, 0xffff0000, v2
	v_lshlrev_b32_e32 v2, 16, v3
	v_and_b32_e32 v3, 0xffff0000, v3
	v_pk_mul_f32 v[52:53], v[50:51], v[50:51]
	v_pk_mul_f32 v[54:55], v[0:1], v[0:1]
	v_pk_mul_f32 v[58:59], v[56:57], v[56:57]
	v_pk_mul_f32 v[60:61], v[2:3], v[2:3]
	v_pk_fma_f32 v[52:53], v[52:53], s[38:39], 1.0 op_sel_hi:[1,0,0]
	v_pk_fma_f32 v[54:55], v[54:55], s[38:39], 1.0 op_sel_hi:[1,0,0]
	v_pk_fma_f32 v[58:59], v[58:59], s[38:39], 1.0 op_sel_hi:[1,0,0]
	v_pk_fma_f32 v[60:61], v[60:61], s[38:39], 1.0 op_sel_hi:[1,0,0]
	v_pk_mul_f32 v[52:53], v[52:53], v[50:51]
	v_pk_mul_f32 v[54:55], v[54:55], v[0:1]
	v_pk_mul_f32 v[58:59], v[58:59], v[56:57]
	v_pk_mul_f32 v[60:61], v[60:61], v[2:3]
	v_pk_mul_f32 v[52:53], v[52:53], s[36:37] op_sel_hi:[1,0]
	v_pk_mul_f32 v[54:55], v[54:55], s[36:37] op_sel_hi:[1,0]
	v_pk_mul_f32 v[58:59], v[58:59], s[36:37] op_sel_hi:[1,0]
	v_pk_mul_f32 v[60:61], v[60:61], s[36:37] op_sel_hi:[1,0]
	v_exp_f32_e32 v52, v52
	v_exp_f32_e32 v53, v53
	v_exp_f32_e32 v54, v54
	v_exp_f32_e32 v55, v55
	v_exp_f32_e32 v58, v58
	v_exp_f32_e32 v59, v59
	v_exp_f32_e32 v60, v60
	v_exp_f32_e32 v61, v61
	v_pk_add_f32 v[52:53], v[52:53], 1.0 op_sel_hi:[1,0]
	v_pk_add_f32 v[54:55], v[54:55], 1.0 op_sel_hi:[1,0]
	v_pk_add_f32 v[58:59], v[58:59], 1.0 op_sel_hi:[1,0]
	v_pk_add_f32 v[60:61], v[60:61], 1.0 op_sel_hi:[1,0]
	v_rcp_f32_e32 v52, v52
	v_rcp_f32_e32 v53, v53
	v_rcp_f32_e32 v62, v54
	v_rcp_f32_e32 v63, v55
	v_rcp_f32_e32 v58, v58
	v_rcp_f32_e32 v59, v59
	v_rcp_f32_e32 v60, v60
	v_rcp_f32_e32 v61, v61
	v_pk_mul_f32 v[54:55], v[52:53], v[50:51]
	v_pk_mul_f32 v[52:53], v[62:63], v[0:1]
	v_pk_mul_f32 v[50:51], v[58:59], v[56:57]
	v_pk_mul_f32 v[56:57], v[60:61], v[2:3]
	v_cvt_pk_bf16_f32 v134, v54, v55
	v_cvt_pk_bf16_f32 v132, v52, v53
	v_cvt_pk_bf16_f32 v131, v50, v51
	s_nop 0
	v_cvt_pk_bf16_f32 v130, v56, v57
	s_waitcnt vmcnt(9)
	v_mov_b32_e32 v0, v192
	v_mov_b32_e32 v1, v193
	v_mov_b32_e32 v2, v194
	v_mov_b32_e32 v3, v195
	v_lshlrev_b32_e32 v58, 16, v0
	v_and_b32_e32 v59, 0xffff0000, v0
	v_lshlrev_b32_e32 v0, 16, v1
	v_and_b32_e32 v1, 0xffff0000, v1
	v_lshlrev_b32_e32 v64, 16, v2
	v_and_b32_e32 v65, 0xffff0000, v2
	v_lshlrev_b32_e32 v2, 16, v3
	v_and_b32_e32 v3, 0xffff0000, v3
	v_pk_mul_f32 v[60:61], v[58:59], v[58:59]
	v_pk_mul_f32 v[62:63], v[0:1], v[0:1]
	v_pk_mul_f32 v[66:67], v[64:65], v[64:65]
	v_pk_mul_f32 v[68:69], v[2:3], v[2:3]
	v_pk_fma_f32 v[60:61], v[60:61], s[38:39], 1.0 op_sel_hi:[1,0,0]
	v_pk_fma_f32 v[62:63], v[62:63], s[38:39], 1.0 op_sel_hi:[1,0,0]
	v_pk_fma_f32 v[66:67], v[66:67], s[38:39], 1.0 op_sel_hi:[1,0,0]
	v_pk_fma_f32 v[68:69], v[68:69], s[38:39], 1.0 op_sel_hi:[1,0,0]
	v_pk_mul_f32 v[60:61], v[60:61], v[58:59]
	v_pk_mul_f32 v[62:63], v[62:63], v[0:1]
	v_pk_mul_f32 v[66:67], v[66:67], v[64:65]
	v_pk_mul_f32 v[68:69], v[68:69], v[2:3]
	v_pk_mul_f32 v[60:61], v[60:61], s[36:37] op_sel_hi:[1,0]
	v_pk_mul_f32 v[62:63], v[62:63], s[36:37] op_sel_hi:[1,0]
	v_pk_mul_f32 v[66:67], v[66:67], s[36:37] op_sel_hi:[1,0]
	v_pk_mul_f32 v[68:69], v[68:69], s[36:37] op_sel_hi:[1,0]
	v_exp_f32_e32 v60, v60
	v_exp_f32_e32 v61, v61
	v_exp_f32_e32 v62, v62
	v_exp_f32_e32 v63, v63
	v_exp_f32_e32 v66, v66
	v_exp_f32_e32 v67, v67
	v_exp_f32_e32 v68, v68
	v_exp_f32_e32 v69, v69
	v_pk_add_f32 v[60:61], v[60:61], 1.0 op_sel_hi:[1,0]
	v_pk_add_f32 v[62:63], v[62:63], 1.0 op_sel_hi:[1,0]
	v_pk_add_f32 v[66:67], v[66:67], 1.0 op_sel_hi:[1,0]
	v_pk_add_f32 v[68:69], v[68:69], 1.0 op_sel_hi:[1,0]
	v_rcp_f32_e32 v60, v60
	v_rcp_f32_e32 v61, v61
	v_rcp_f32_e32 v70, v62
	v_rcp_f32_e32 v71, v63
	v_rcp_f32_e32 v66, v66
	v_rcp_f32_e32 v67, v67
	v_rcp_f32_e32 v68, v68
	v_rcp_f32_e32 v69, v69
	v_pk_mul_f32 v[62:63], v[60:61], v[58:59]
	v_pk_mul_f32 v[60:61], v[70:71], v[0:1]
	v_pk_mul_f32 v[58:59], v[66:67], v[64:65]
	v_pk_mul_f32 v[64:65], v[68:69], v[2:3]
	v_cvt_pk_bf16_f32 v137, v62, v63
	v_cvt_pk_bf16_f32 v136, v60, v61
	v_cvt_pk_bf16_f32 v135, v58, v59
	s_nop 0
	v_cvt_pk_bf16_f32 v133, v64, v65
	s_waitcnt vmcnt(8)
	v_mov_b32_e32 v0, v196
	v_mov_b32_e32 v1, v197
	v_mov_b32_e32 v2, v198
	v_mov_b32_e32 v3, v199
	v_lshlrev_b32_e32 v66, 16, v0
	v_and_b32_e32 v67, 0xffff0000, v0
	v_lshlrev_b32_e32 v0, 16, v1
	v_and_b32_e32 v1, 0xffff0000, v1
	v_lshlrev_b32_e32 v72, 16, v2
	v_and_b32_e32 v73, 0xffff0000, v2
	v_lshlrev_b32_e32 v2, 16, v3
	v_and_b32_e32 v3, 0xffff0000, v3
	v_pk_mul_f32 v[68:69], v[66:67], v[66:67]
	v_pk_mul_f32 v[70:71], v[0:1], v[0:1]
	v_pk_mul_f32 v[74:75], v[72:73], v[72:73]
	v_pk_mul_f32 v[76:77], v[2:3], v[2:3]
	v_pk_fma_f32 v[68:69], v[68:69], s[38:39], 1.0 op_sel_hi:[1,0,0]
	v_pk_fma_f32 v[70:71], v[70:71], s[38:39], 1.0 op_sel_hi:[1,0,0]
	v_pk_fma_f32 v[74:75], v[74:75], s[38:39], 1.0 op_sel_hi:[1,0,0]
	v_pk_fma_f32 v[76:77], v[76:77], s[38:39], 1.0 op_sel_hi:[1,0,0]
	v_pk_mul_f32 v[68:69], v[68:69], v[66:67]
	v_pk_mul_f32 v[70:71], v[70:71], v[0:1]
	v_pk_mul_f32 v[74:75], v[74:75], v[72:73]
	v_pk_mul_f32 v[76:77], v[76:77], v[2:3]
	v_pk_mul_f32 v[68:69], v[68:69], s[36:37] op_sel_hi:[1,0]
	v_pk_mul_f32 v[70:71], v[70:71], s[36:37] op_sel_hi:[1,0]
	v_pk_mul_f32 v[74:75], v[74:75], s[36:37] op_sel_hi:[1,0]
	v_pk_mul_f32 v[76:77], v[76:77], s[36:37] op_sel_hi:[1,0]
	v_exp_f32_e32 v68, v68
	v_exp_f32_e32 v69, v69
	v_exp_f32_e32 v70, v70
	v_exp_f32_e32 v71, v71
	v_exp_f32_e32 v74, v74
	v_exp_f32_e32 v75, v75
	v_exp_f32_e32 v76, v76
	v_exp_f32_e32 v77, v77
	v_pk_add_f32 v[68:69], v[68:69], 1.0 op_sel_hi:[1,0]
	v_pk_add_f32 v[70:71], v[70:71], 1.0 op_sel_hi:[1,0]
	v_pk_add_f32 v[74:75], v[74:75], 1.0 op_sel_hi:[1,0]
	v_pk_add_f32 v[76:77], v[76:77], 1.0 op_sel_hi:[1,0]
	v_rcp_f32_e32 v68, v68
	v_rcp_f32_e32 v69, v69
	v_rcp_f32_e32 v78, v70
	v_rcp_f32_e32 v79, v71
	v_rcp_f32_e32 v74, v74
	v_rcp_f32_e32 v75, v75
	v_rcp_f32_e32 v76, v76
	v_rcp_f32_e32 v77, v77
	v_pk_mul_f32 v[70:71], v[68:69], v[66:67]
	v_pk_mul_f32 v[68:69], v[78:79], v[0:1]
	v_pk_mul_f32 v[66:67], v[74:75], v[72:73]
	v_pk_mul_f32 v[72:73], v[76:77], v[2:3]
	v_cvt_pk_bf16_f32 v142, v70, v71
	v_cvt_pk_bf16_f32 v140, v68, v69
	v_cvt_pk_bf16_f32 v139, v66, v67
	s_nop 0
	v_cvt_pk_bf16_f32 v138, v72, v73
	s_waitcnt vmcnt(7)
	v_mov_b32_e32 v0, v200
	v_mov_b32_e32 v1, v201
	v_mov_b32_e32 v2, v202
	v_mov_b32_e32 v3, v203
	v_lshlrev_b32_e32 v74, 16, v0
	v_and_b32_e32 v75, 0xffff0000, v0
	v_lshlrev_b32_e32 v0, 16, v1
	v_and_b32_e32 v1, 0xffff0000, v1
	v_lshlrev_b32_e32 v80, 16, v2
	v_and_b32_e32 v81, 0xffff0000, v2
	v_lshlrev_b32_e32 v2, 16, v3
	v_and_b32_e32 v3, 0xffff0000, v3
	v_pk_mul_f32 v[76:77], v[74:75], v[74:75]
	v_pk_mul_f32 v[78:79], v[0:1], v[0:1]
	v_pk_mul_f32 v[82:83], v[80:81], v[80:81]
	v_pk_mul_f32 v[84:85], v[2:3], v[2:3]
	v_pk_fma_f32 v[76:77], v[76:77], s[38:39], 1.0 op_sel_hi:[1,0,0]
	v_pk_fma_f32 v[78:79], v[78:79], s[38:39], 1.0 op_sel_hi:[1,0,0]
	v_pk_fma_f32 v[82:83], v[82:83], s[38:39], 1.0 op_sel_hi:[1,0,0]
	v_pk_fma_f32 v[84:85], v[84:85], s[38:39], 1.0 op_sel_hi:[1,0,0]
	v_pk_mul_f32 v[76:77], v[76:77], v[74:75]
	v_pk_mul_f32 v[78:79], v[78:79], v[0:1]
	v_pk_mul_f32 v[82:83], v[82:83], v[80:81]
	v_pk_mul_f32 v[84:85], v[84:85], v[2:3]
	v_pk_mul_f32 v[76:77], v[76:77], s[36:37] op_sel_hi:[1,0]
	v_pk_mul_f32 v[78:79], v[78:79], s[36:37] op_sel_hi:[1,0]
	v_pk_mul_f32 v[82:83], v[82:83], s[36:37] op_sel_hi:[1,0]
	v_pk_mul_f32 v[84:85], v[84:85], s[36:37] op_sel_hi:[1,0]
	v_exp_f32_e32 v76, v76
	v_exp_f32_e32 v77, v77
	v_exp_f32_e32 v78, v78
	v_exp_f32_e32 v79, v79
	v_exp_f32_e32 v82, v82
	v_exp_f32_e32 v83, v83
	v_exp_f32_e32 v84, v84
	v_exp_f32_e32 v85, v85
	v_pk_add_f32 v[76:77], v[76:77], 1.0 op_sel_hi:[1,0]
	v_pk_add_f32 v[78:79], v[78:79], 1.0 op_sel_hi:[1,0]
	v_pk_add_f32 v[82:83], v[82:83], 1.0 op_sel_hi:[1,0]
	v_pk_add_f32 v[84:85], v[84:85], 1.0 op_sel_hi:[1,0]
	v_rcp_f32_e32 v76, v76
	v_rcp_f32_e32 v77, v77
	v_rcp_f32_e32 v86, v78
	v_rcp_f32_e32 v87, v79
	v_rcp_f32_e32 v82, v82
	v_rcp_f32_e32 v83, v83
	v_rcp_f32_e32 v84, v84
	v_rcp_f32_e32 v85, v85
	v_pk_mul_f32 v[78:79], v[76:77], v[74:75]
	v_pk_mul_f32 v[76:77], v[86:87], v[0:1]
	v_pk_mul_f32 v[74:75], v[82:83], v[80:81]
	v_pk_mul_f32 v[80:81], v[84:85], v[2:3]
	v_cvt_pk_bf16_f32 v146, v78, v79
	v_cvt_pk_bf16_f32 v144, v76, v77
	v_cvt_pk_bf16_f32 v143, v74, v75
	s_nop 0
	v_cvt_pk_bf16_f32 v141, v80, v81
	s_waitcnt vmcnt(6)
	v_mov_b32_e32 v0, v204
	v_mov_b32_e32 v1, v205
	v_mov_b32_e32 v2, v206
	v_mov_b32_e32 v3, v207
	v_lshlrev_b32_e32 v82, 16, v0
	v_and_b32_e32 v83, 0xffff0000, v0
	v_lshlrev_b32_e32 v0, 16, v1
	v_and_b32_e32 v1, 0xffff0000, v1
	v_lshlrev_b32_e32 v84, 16, v2
	v_and_b32_e32 v85, 0xffff0000, v2
	v_lshlrev_b32_e32 v2, 16, v3
	v_and_b32_e32 v3, 0xffff0000, v3
	v_pk_mul_f32 v[86:87], v[82:83], v[82:83]
	v_pk_mul_f32 v[88:89], v[0:1], v[0:1]
	v_pk_mul_f32 v[90:91], v[84:85], v[84:85]
	v_pk_mul_f32 v[92:93], v[2:3], v[2:3]
	v_pk_fma_f32 v[86:87], v[86:87], s[38:39], 1.0 op_sel_hi:[1,0,0]
	v_pk_fma_f32 v[88:89], v[88:89], s[38:39], 1.0 op_sel_hi:[1,0,0]
	v_pk_fma_f32 v[90:91], v[90:91], s[38:39], 1.0 op_sel_hi:[1,0,0]
	v_pk_fma_f32 v[92:93], v[92:93], s[38:39], 1.0 op_sel_hi:[1,0,0]
	v_pk_mul_f32 v[86:87], v[86:87], v[82:83]
	v_pk_mul_f32 v[88:89], v[88:89], v[0:1]
	v_pk_mul_f32 v[90:91], v[90:91], v[84:85]
	v_pk_mul_f32 v[92:93], v[92:93], v[2:3]
	v_pk_mul_f32 v[86:87], v[86:87], s[36:37] op_sel_hi:[1,0]
	v_pk_mul_f32 v[88:89], v[88:89], s[36:37] op_sel_hi:[1,0]
	v_pk_mul_f32 v[90:91], v[90:91], s[36:37] op_sel_hi:[1,0]
	v_pk_mul_f32 v[92:93], v[92:93], s[36:37] op_sel_hi:[1,0]
	v_exp_f32_e32 v86, v86
	v_exp_f32_e32 v87, v87
	v_exp_f32_e32 v88, v88
	v_exp_f32_e32 v89, v89
	v_exp_f32_e32 v90, v90
	v_exp_f32_e32 v91, v91
	v_exp_f32_e32 v92, v92
	v_exp_f32_e32 v93, v93
	v_pk_add_f32 v[86:87], v[86:87], 1.0 op_sel_hi:[1,0]
	v_pk_add_f32 v[88:89], v[88:89], 1.0 op_sel_hi:[1,0]
	v_pk_add_f32 v[90:91], v[90:91], 1.0 op_sel_hi:[1,0]
	v_pk_add_f32 v[92:93], v[92:93], 1.0 op_sel_hi:[1,0]
	v_rcp_f32_e32 v86, v86
	v_rcp_f32_e32 v87, v87
	v_rcp_f32_e32 v88, v88
	v_rcp_f32_e32 v89, v89
	v_rcp_f32_e32 v94, v90
	v_rcp_f32_e32 v95, v91
	v_rcp_f32_e32 v92, v92
	v_rcp_f32_e32 v93, v93
	v_pk_mul_f32 v[90:91], v[86:87], v[82:83]
	v_pk_mul_f32 v[86:87], v[88:89], v[0:1]
	v_pk_mul_f32 v[84:85], v[94:95], v[84:85]
	v_pk_mul_f32 v[82:83], v[92:93], v[2:3]
	v_cvt_pk_bf16_f32 v149, v90, v91
	v_cvt_pk_bf16_f32 v148, v86, v87
	v_cvt_pk_bf16_f32 v147, v84, v85
	s_nop 0
	v_cvt_pk_bf16_f32 v145, v82, v83
	s_waitcnt vmcnt(5)
	v_mov_b32_e32 v0, v208
	v_mov_b32_e32 v1, v209
	v_mov_b32_e32 v2, v210
	v_mov_b32_e32 v3, v211
	v_lshlrev_b32_e32 v88, 16, v0
	v_and_b32_e32 v89, 0xffff0000, v0
	v_lshlrev_b32_e32 v0, 16, v1
	v_and_b32_e32 v1, 0xffff0000, v1
	v_lshlrev_b32_e32 v92, 16, v2
	v_and_b32_e32 v93, 0xffff0000, v2
	v_lshlrev_b32_e32 v2, 16, v3
	v_and_b32_e32 v3, 0xffff0000, v3
	v_pk_mul_f32 v[94:95], v[88:89], v[88:89]
	v_pk_mul_f32 v[96:97], v[0:1], v[0:1]
	v_pk_mul_f32 v[98:99], v[92:93], v[92:93]
	v_pk_mul_f32 v[100:101], v[2:3], v[2:3]
	v_pk_fma_f32 v[94:95], v[94:95], s[38:39], 1.0 op_sel_hi:[1,0,0]
	v_pk_fma_f32 v[96:97], v[96:97], s[38:39], 1.0 op_sel_hi:[1,0,0]
	v_pk_fma_f32 v[98:99], v[98:99], s[38:39], 1.0 op_sel_hi:[1,0,0]
	v_pk_fma_f32 v[100:101], v[100:101], s[38:39], 1.0 op_sel_hi:[1,0,0]
	v_pk_mul_f32 v[94:95], v[94:95], v[88:89]
	v_pk_mul_f32 v[96:97], v[96:97], v[0:1]
	v_pk_mul_f32 v[98:99], v[98:99], v[92:93]
	v_pk_mul_f32 v[100:101], v[100:101], v[2:3]
	v_pk_mul_f32 v[94:95], v[94:95], s[36:37] op_sel_hi:[1,0]
	v_pk_mul_f32 v[96:97], v[96:97], s[36:37] op_sel_hi:[1,0]
	v_pk_mul_f32 v[98:99], v[98:99], s[36:37] op_sel_hi:[1,0]
	v_pk_mul_f32 v[100:101], v[100:101], s[36:37] op_sel_hi:[1,0]
	v_exp_f32_e32 v94, v94
	v_exp_f32_e32 v95, v95
	v_exp_f32_e32 v96, v96
	v_exp_f32_e32 v97, v97
	v_exp_f32_e32 v98, v98
	v_exp_f32_e32 v99, v99
	v_exp_f32_e32 v100, v100
	v_exp_f32_e32 v101, v101
	v_pk_add_f32 v[94:95], v[94:95], 1.0 op_sel_hi:[1,0]
	v_pk_add_f32 v[96:97], v[96:97], 1.0 op_sel_hi:[1,0]
	v_pk_add_f32 v[98:99], v[98:99], 1.0 op_sel_hi:[1,0]
	v_pk_add_f32 v[100:101], v[100:101], 1.0 op_sel_hi:[1,0]
	v_rcp_f32_e32 v94, v94
	v_rcp_f32_e32 v95, v95
	v_rcp_f32_e32 v102, v96
	v_rcp_f32_e32 v103, v97
	v_rcp_f32_e32 v98, v98
	v_rcp_f32_e32 v99, v99
	v_rcp_f32_e32 v100, v100
	v_rcp_f32_e32 v101, v101
	v_pk_mul_f32 v[96:97], v[94:95], v[88:89]
	v_pk_mul_f32 v[94:95], v[102:103], v[0:1]
	v_pk_mul_f32 v[92:93], v[98:99], v[92:93]
	v_pk_mul_f32 v[98:99], v[100:101], v[2:3]
	v_cvt_pk_bf16_f32 v154, v96, v97
	v_cvt_pk_bf16_f32 v152, v94, v95
	v_cvt_pk_bf16_f32 v151, v92, v93
	v_mov_b32_e32 v89, 0
	v_cvt_pk_bf16_f32 v150, v98, v99
	v_mov_b32_e32 v88, v17
	v_pk_add_f32 v[6:7], v[6:7], v[88:89]
	v_mov_b32_e32 v17, v22
	v_pk_add_f32 v[6:7], v[10:11], v[6:7]
	v_pk_mul_f32 v[10:11], v[20:21], v[20:21]
	s_waitcnt vmcnt(4)
	v_mov_b32_e32 v0, v212
	v_mov_b32_e32 v1, v213
	v_mov_b32_e32 v2, v214
	v_mov_b32_e32 v3, v215
	v_lshlrev_b32_e32 v100, 16, v0
	v_and_b32_e32 v101, 0xffff0000, v0
	v_lshlrev_b32_e32 v0, 16, v1
	v_and_b32_e32 v1, 0xffff0000, v1
	v_lshlrev_b32_e32 v106, 16, v2
	v_and_b32_e32 v107, 0xffff0000, v2
	v_lshlrev_b32_e32 v2, 16, v3
	v_and_b32_e32 v3, 0xffff0000, v3
	v_pk_mul_f32 v[102:103], v[100:101], v[100:101]
	v_pk_mul_f32 v[104:105], v[0:1], v[0:1]
	v_pk_mul_f32 v[156:157], v[106:107], v[106:107]
	v_pk_mul_f32 v[158:159], v[2:3], v[2:3]
	v_pk_fma_f32 v[102:103], v[102:103], s[38:39], 1.0 op_sel_hi:[1,0,0]
	v_pk_fma_f32 v[104:105], v[104:105], s[38:39], 1.0 op_sel_hi:[1,0,0]
	v_pk_fma_f32 v[156:157], v[156:157], s[38:39], 1.0 op_sel_hi:[1,0,0]
	v_pk_fma_f32 v[158:159], v[158:159], s[38:39], 1.0 op_sel_hi:[1,0,0]
	v_pk_mul_f32 v[102:103], v[102:103], v[100:101]
	v_pk_mul_f32 v[104:105], v[104:105], v[0:1]
	v_pk_mul_f32 v[156:157], v[156:157], v[106:107]
	v_pk_mul_f32 v[158:159], v[158:159], v[2:3]
	v_pk_mul_f32 v[102:103], v[102:103], s[36:37] op_sel_hi:[1,0]
	v_pk_mul_f32 v[104:105], v[104:105], s[36:37] op_sel_hi:[1,0]
	v_pk_mul_f32 v[156:157], v[156:157], s[36:37] op_sel_hi:[1,0]
	v_pk_mul_f32 v[158:159], v[158:159], s[36:37] op_sel_hi:[1,0]
	v_exp_f32_e32 v102, v102
	v_exp_f32_e32 v103, v103
	v_exp_f32_e32 v104, v104
	v_exp_f32_e32 v105, v105
	v_exp_f32_e32 v156, v156
	v_exp_f32_e32 v157, v157
	v_exp_f32_e32 v158, v158
	v_exp_f32_e32 v159, v159
	v_pk_add_f32 v[102:103], v[102:103], 1.0 op_sel_hi:[1,0]
	v_pk_add_f32 v[104:105], v[104:105], 1.0 op_sel_hi:[1,0]
	v_pk_add_f32 v[156:157], v[156:157], 1.0 op_sel_hi:[1,0]
	v_pk_add_f32 v[158:159], v[158:159], 1.0 op_sel_hi:[1,0]
	v_rcp_f32_e32 v102, v102
	v_rcp_f32_e32 v103, v103
	v_rcp_f32_e32 v160, v104
	v_rcp_f32_e32 v161, v105
	v_rcp_f32_e32 v156, v156
	v_rcp_f32_e32 v157, v157
	v_rcp_f32_e32 v158, v158
	v_rcp_f32_e32 v159, v159
	v_pk_mul_f32 v[104:105], v[102:103], v[100:101]
	v_pk_mul_f32 v[102:103], v[160:161], v[0:1]
	v_pk_mul_f32 v[100:101], v[156:157], v[106:107]
	v_pk_mul_f32 v[106:107], v[158:159], v[2:3]
	v_cvt_pk_bf16_f32 v157, v104, v105
	v_cvt_pk_bf16_f32 v156, v102, v103
	v_cvt_pk_bf16_f32 v155, v100, v101
	v_pk_mul_f32 v[160:161], v[8:9], v[8:9]
	v_cvt_pk_bf16_f32 v153, v106, v107
	v_mov_b32_e32 v166, v160
	v_mov_b32_e32 v8, v161
	v_pk_add_f32 v[8:9], v[166:167], v[8:9]
	v_mov_b32_e32 v161, v20
	v_pk_add_f32 v[6:7], v[8:9], v[6:7]
	v_pk_mul_f32 v[8:9], v[22:23], v[22:23]
	v_pk_add_f32 v[6:7], v[12:13], v[6:7]
	v_mov_b32_e32 v16, v8
	v_mov_b32_e32 v22, v9
	v_pk_mul_f32 v[12:13], v[18:19], v[18:19]
	v_mov_b32_e32 v160, v10
	v_mov_b32_e32 v20, v11
	v_pk_add_f32 v[8:9], v[16:17], v[22:23]
	v_mov_b32_e32 v162, v12
	v_mov_b32_e32 v18, v13
	v_pk_add_f32 v[10:11], v[160:161], v[20:21]
	v_pk_add_f32 v[6:7], v[6:7], v[8:9]
	v_pk_add_f32 v[12:13], v[162:163], v[18:19]
	v_pk_add_f32 v[6:7], v[10:11], v[6:7]
	v_pk_mul_f32 v[8:9], v[30:31], v[30:31]
	v_pk_add_f32 v[6:7], v[12:13], v[6:7]
	v_mov_b32_e32 v11, v30
	v_pk_mul_f32 v[12:13], v[28:29], v[28:29]
	v_mov_b32_e32 v10, v8
	v_mov_b32_e32 v30, v9
	v_pk_add_f32 v[6:7], v[14:15], v[6:7]
	v_mov_b32_e32 v15, v28
	v_pk_mul_f32 v[16:17], v[26:27], v[26:27]
	v_mov_b32_e32 v14, v12
	v_mov_b32_e32 v28, v13
	v_pk_add_f32 v[8:9], v[10:11], v[30:31]
	v_pk_mul_f32 v[18:19], v[32:33], v[32:33]
	v_mov_b32_e32 v21, v26
	v_mov_b32_e32 v20, v16
	v_mov_b32_e32 v26, v17
	v_pk_add_f32 v[10:11], v[14:15], v[28:29]
	v_pk_add_f32 v[6:7], v[6:7], v[8:9]
	v_mov_b32_e32 v23, v32
	v_mov_b32_e32 v22, v18
	v_mov_b32_e32 v32, v19
	v_pk_add_f32 v[12:13], v[20:21], v[26:27]
	v_pk_add_f32 v[6:7], v[10:11], v[6:7]
	v_pk_add_f32 v[14:15], v[22:23], v[32:33]
	v_pk_add_f32 v[6:7], v[12:13], v[6:7]
	v_pk_mul_f32 v[16:17], v[38:39], v[38:39]
	v_pk_add_f32 v[14:15], v[14:15], v[6:7]
	v_mov_b32_e32 v31, v38
	v_mov_b32_e32 v30, v16
	v_mov_b32_e32 v38, v17
	v_pk_mul_f32 v[26:27], v[34:35], v[34:35]
	v_mov_b32_e32 v33, v36
	v_mov_b32_e32 v32, v24
	v_mov_b32_e32 v36, v25
	v_pk_add_f32 v[16:17], v[30:31], v[38:39]
	v_pk_mul_f32 v[28:29], v[40:41], v[40:41]
	v_mov_b32_e32 v161, v34
	v_mov_b32_e32 v160, v26
	v_mov_b32_e32 v34, v27
	v_pk_add_f32 v[24:25], v[32:33], v[36:37]
	v_pk_add_f32 v[14:15], v[14:15], v[16:17]
	v_mov_b32_e32 v163, v40
	v_mov_b32_e32 v162, v28
	v_mov_b32_e32 v40, v29
	v_pk_add_f32 v[26:27], v[160:161], v[34:35]
	v_pk_add_f32 v[14:15], v[24:25], v[14:15]
	v_pk_mul_f32 v[16:17], v[46:47], v[46:47]
	v_pk_add_f32 v[28:29], v[162:163], v[40:41]
	v_pk_add_f32 v[14:15], v[26:27], v[14:15]
	v_pk_mul_f32 v[24:25], v[44:45], v[44:45]
	v_mov_b32_e32 v31, v46
	v_mov_b32_e32 v30, v16
	v_mov_b32_e32 v46, v17
	v_pk_add_f32 v[14:15], v[28:29], v[14:15]
	v_pk_mul_f32 v[26:27], v[42:43], v[42:43]
	v_mov_b32_e32 v33, v44
	v_mov_b32_e32 v32, v24
	v_mov_b32_e32 v44, v25
	v_pk_add_f32 v[16:17], v[30:31], v[46:47]
	v_pk_mul_f32 v[28:29], v[48:49], v[48:49]
	s_waitcnt vmcnt(3)
	v_mov_b32_e32 v0, v216
	v_mov_b32_e32 v1, v217
	v_mov_b32_e32 v2, v218
	v_mov_b32_e32 v3, v219
	v_lshlrev_b32_e32 v6, 16, v0
	v_and_b32_e32 v7, 0xffff0000, v0
	v_lshlrev_b32_e32 v0, 16, v1
	v_and_b32_e32 v1, 0xffff0000, v1
	v_lshlrev_b32_e32 v10, 16, v2
	v_and_b32_e32 v11, 0xffff0000, v2
	v_lshlrev_b32_e32 v12, 16, v3
	v_and_b32_e32 v13, 0xffff0000, v3
	v_pk_mul_f32 v[2:3], v[6:7], v[6:7]
	v_pk_mul_f32 v[8:9], v[0:1], v[0:1]
	v_pk_mul_f32 v[18:19], v[10:11], v[10:11]
	v_pk_mul_f32 v[20:21], v[12:13], v[12:13]
	v_pk_fma_f32 v[2:3], v[2:3], s[38:39], 1.0 op_sel_hi:[1,0,0]
	v_pk_fma_f32 v[8:9], v[8:9], s[38:39], 1.0 op_sel_hi:[1,0,0]
	v_pk_fma_f32 v[18:19], v[18:19], s[38:39], 1.0 op_sel_hi:[1,0,0]
	v_pk_fma_f32 v[20:21], v[20:21], s[38:39], 1.0 op_sel_hi:[1,0,0]
	v_pk_mul_f32 v[2:3], v[2:3], v[6:7]
	v_pk_mul_f32 v[8:9], v[8:9], v[0:1]
	v_pk_mul_f32 v[18:19], v[18:19], v[10:11]
	v_pk_mul_f32 v[20:21], v[20:21], v[12:13]
	v_pk_mul_f32 v[2:3], v[2:3], s[36:37] op_sel_hi:[1,0]
	v_pk_mul_f32 v[8:9], v[8:9], s[36:37] op_sel_hi:[1,0]
	v_pk_mul_f32 v[18:19], v[18:19], s[36:37] op_sel_hi:[1,0]
	v_pk_mul_f32 v[20:21], v[20:21], s[36:37] op_sel_hi:[1,0]
	v_exp_f32_e32 v2, v2
	v_exp_f32_e32 v3, v3
	v_exp_f32_e32 v8, v8
	v_exp_f32_e32 v9, v9
	v_exp_f32_e32 v18, v18
	v_exp_f32_e32 v19, v19
	v_exp_f32_e32 v20, v20
	v_exp_f32_e32 v21, v21
	v_pk_add_f32 v[2:3], v[2:3], 1.0 op_sel_hi:[1,0]
	v_pk_add_f32 v[8:9], v[8:9], 1.0 op_sel_hi:[1,0]
	v_pk_add_f32 v[18:19], v[18:19], 1.0 op_sel_hi:[1,0]
	v_pk_add_f32 v[20:21], v[20:21], 1.0 op_sel_hi:[1,0]
	v_rcp_f32_e32 v2, v2
	v_rcp_f32_e32 v3, v3
	v_rcp_f32_e32 v22, v8
	v_rcp_f32_e32 v23, v9
	v_rcp_f32_e32 v18, v18
	v_rcp_f32_e32 v19, v19
	v_rcp_f32_e32 v20, v20
	v_rcp_f32_e32 v21, v21
	v_pk_mul_f32 v[8:9], v[2:3], v[6:7]
	v_pk_mul_f32 v[6:7], v[22:23], v[0:1]
	v_pk_mul_f32 v[2:3], v[18:19], v[10:11]
	v_pk_mul_f32 v[0:1], v[20:21], v[12:13]
	v_cvt_pk_bf16_f32 v22, v8, v9
	v_cvt_pk_bf16_f32 v20, v6, v7
	v_cvt_pk_bf16_f32 v19, v2, v3
	v_mov_b32_e32 v35, v42
	v_cvt_pk_bf16_f32 v18, v0, v1
	v_mov_b32_e32 v34, v26
	v_mov_b32_e32 v42, v27
	v_pk_add_f32 v[24:25], v[32:33], v[44:45]
	v_pk_add_f32 v[14:15], v[14:15], v[16:17]
	v_mov_b32_e32 v37, v48
	v_mov_b32_e32 v36, v28
	v_mov_b32_e32 v48, v29
	v_pk_add_f32 v[26:27], v[34:35], v[42:43]
	v_pk_add_f32 v[14:15], v[24:25], v[14:15]
	v_pk_mul_f32 v[16:17], v[54:55], v[54:55]
	v_pk_add_f32 v[28:29], v[36:37], v[48:49]
	v_pk_add_f32 v[14:15], v[26:27], v[14:15]
	v_mov_b32_e32 v25, v54
	v_pk_mul_f32 v[26:27], v[52:53], v[52:53]
	v_mov_b32_e32 v24, v16
	v_mov_b32_e32 v54, v17
	v_pk_add_f32 v[14:15], v[28:29], v[14:15]
	v_pk_mul_f32 v[28:29], v[50:51], v[50:51]
	v_mov_b32_e32 v33, v52
	v_mov_b32_e32 v32, v26
	v_mov_b32_e32 v52, v27
	v_pk_add_f32 v[16:17], v[24:25], v[54:55]
	v_pk_mul_f32 v[30:31], v[56:57], v[56:57]
	v_mov_b32_e32 v35, v50
	v_mov_b32_e32 v34, v28
	v_mov_b32_e32 v50, v29
	v_pk_add_f32 v[24:25], v[32:33], v[52:53]
	v_pk_add_f32 v[14:15], v[14:15], v[16:17]
	v_mov_b32_e32 v37, v56
	v_mov_b32_e32 v36, v30
	v_mov_b32_e32 v56, v31
	v_pk_add_f32 v[26:27], v[34:35], v[50:51]
	v_pk_add_f32 v[14:15], v[24:25], v[14:15]
	v_pk_add_f32 v[28:29], v[36:37], v[56:57]
	v_pk_add_f32 v[14:15], v[26:27], v[14:15]
	v_pk_mul_f32 v[16:17], v[60:61], v[60:61]
	v_pk_add_f32 v[32:33], v[28:29], v[14:15]
	v_pk_mul_f32 v[14:15], v[62:63], v[62:63]
	v_mov_b32_e32 v39, v62
	v_mov_b32_e32 v38, v14
	v_mov_b32_e32 v62, v15
	v_mov_b32_e32 v41, v60
	v_mov_b32_e32 v40, v16
	v_mov_b32_e32 v60, v17
	v_pk_mul_f32 v[34:35], v[58:59], v[58:59]
	v_pk_mul_f32 v[36:37], v[64:65], v[64:65]
	v_mov_b32_e32 v43, v58
	v_mov_b32_e32 v42, v34
	v_mov_b32_e32 v58, v35
	v_pk_add_f32 v[34:35], v[38:39], v[62:63]
	v_mov_b32_e32 v45, v64
	v_mov_b32_e32 v44, v36
	v_mov_b32_e32 v64, v37
	v_pk_add_f32 v[36:37], v[40:41], v[60:61]
	v_pk_add_f32 v[32:33], v[32:33], v[34:35]
	v_pk_add_f32 v[38:39], v[42:43], v[58:59]
	v_pk_add_f32 v[32:33], v[36:37], v[32:33]
	v_pk_add_f32 v[40:41], v[44:45], v[64:65]
	v_pk_add_f32 v[32:33], v[38:39], v[32:33]
	v_pk_mul_f32 v[34:35], v[70:71], v[70:71]
	v_pk_add_f32 v[32:33], v[40:41], v[32:33]
	v_pk_mul_f32 v[36:37], v[68:69], v[68:69]
	v_mov_b32_e32 v41, v70
	v_mov_b32_e32 v40, v34
	v_mov_b32_e32 v70, v35
	v_pk_mul_f32 v[38:39], v[66:67], v[66:67]
	v_mov_b32_e32 v43, v68
	v_mov_b32_e32 v42, v36
	v_mov_b32_e32 v68, v37
	v_pk_add_f32 v[34:35], v[40:41], v[70:71]
	v_mov_b32_e32 v45, v66
	v_mov_b32_e32 v44, v38
	v_mov_b32_e32 v66, v39
	v_pk_add_f32 v[36:37], v[42:43], v[68:69]
	v_pk_add_f32 v[32:33], v[32:33], v[34:35]
	v_mov_b32_e32 v49, v72
	v_pk_add_f32 v[38:39], v[44:45], v[66:67]
	v_pk_add_f32 v[32:33], v[36:37], v[32:33]
	v_pk_mul_f32 v[34:35], v[78:79], v[78:79]
	s_waitcnt vmcnt(2)
	v_mov_b32_e32 v10, v220
	v_mov_b32_e32 v11, v221
	v_mov_b32_e32 v12, v222
	v_mov_b32_e32 v13, v223
	v_lshlrev_b32_e32 v14, 16, v10
	v_and_b32_e32 v15, 0xffff0000, v10
	v_lshlrev_b32_e32 v10, 16, v11
	v_and_b32_e32 v11, 0xffff0000, v11
	v_lshlrev_b32_e32 v24, 16, v12
	v_and_b32_e32 v25, 0xffff0000, v12
	v_lshlrev_b32_e32 v26, 16, v13
	v_and_b32_e32 v27, 0xffff0000, v13
	v_pk_mul_f32 v[12:13], v[14:15], v[14:15]
	v_pk_mul_f32 v[16:17], v[10:11], v[10:11]
	v_pk_mul_f32 v[28:29], v[24:25], v[24:25]
	v_pk_mul_f32 v[30:31], v[26:27], v[26:27]
	v_pk_fma_f32 v[12:13], v[12:13], s[38:39], 1.0 op_sel_hi:[1,0,0]
	v_pk_fma_f32 v[16:17], v[16:17], s[38:39], 1.0 op_sel_hi:[1,0,0]
	v_pk_fma_f32 v[28:29], v[28:29], s[38:39], 1.0 op_sel_hi:[1,0,0]
	v_pk_fma_f32 v[30:31], v[30:31], s[38:39], 1.0 op_sel_hi:[1,0,0]
	v_pk_mul_f32 v[12:13], v[12:13], v[14:15]
	v_pk_mul_f32 v[16:17], v[16:17], v[10:11]
	v_pk_mul_f32 v[28:29], v[28:29], v[24:25]
	v_pk_mul_f32 v[30:31], v[30:31], v[26:27]
	v_pk_mul_f32 v[12:13], v[12:13], s[36:37] op_sel_hi:[1,0]
	v_pk_mul_f32 v[16:17], v[16:17], s[36:37] op_sel_hi:[1,0]
	v_pk_mul_f32 v[28:29], v[28:29], s[36:37] op_sel_hi:[1,0]
	v_pk_mul_f32 v[30:31], v[30:31], s[36:37] op_sel_hi:[1,0]
	v_exp_f32_e32 v12, v12
	v_exp_f32_e32 v13, v13
	v_exp_f32_e32 v16, v16
	v_exp_f32_e32 v17, v17
	v_exp_f32_e32 v28, v28
	v_exp_f32_e32 v29, v29
	v_exp_f32_e32 v30, v30
	v_exp_f32_e32 v31, v31
	v_pk_add_f32 v[12:13], v[12:13], 1.0 op_sel_hi:[1,0]
	v_pk_add_f32 v[16:17], v[16:17], 1.0 op_sel_hi:[1,0]
	v_pk_add_f32 v[28:29], v[28:29], 1.0 op_sel_hi:[1,0]
	v_pk_add_f32 v[30:31], v[30:31], 1.0 op_sel_hi:[1,0]
	v_rcp_f32_e32 v12, v12
	v_rcp_f32_e32 v13, v13
	v_rcp_f32_e32 v46, v16
	v_rcp_f32_e32 v47, v17
	v_rcp_f32_e32 v28, v28
	v_rcp_f32_e32 v29, v29
	v_rcp_f32_e32 v30, v30
	v_rcp_f32_e32 v31, v31
	v_pk_mul_f32 v[16:17], v[12:13], v[14:15]
	v_pk_mul_f32 v[14:15], v[46:47], v[10:11]
	v_pk_mul_f32 v[12:13], v[28:29], v[24:25]
	v_pk_mul_f32 v[10:11], v[30:31], v[26:27]
	v_cvt_pk_bf16_f32 v26, v16, v17
	v_cvt_pk_bf16_f32 v24, v14, v15
	v_cvt_pk_bf16_f32 v23, v12, v13
	v_pk_mul_f32 v[46:47], v[72:73], v[72:73]
	v_cvt_pk_bf16_f32 v21, v10, v11
	v_mov_b32_e32 v48, v46
	v_mov_b32_e32 v72, v47
	v_pk_add_f32 v[40:41], v[48:49], v[72:73]
	v_pk_add_f32 v[32:33], v[38:39], v[32:33]
	v_pk_mul_f32 v[36:37], v[76:77], v[76:77]
	v_mov_b32_e32 v43, v78
	v_mov_b32_e32 v42, v34
	v_mov_b32_e32 v78, v35
	v_pk_add_f32 v[32:33], v[40:41], v[32:33]
	v_pk_mul_f32 v[38:39], v[74:75], v[74:75]
	v_mov_b32_e32 v45, v76
	v_mov_b32_e32 v44, v36
	v_mov_b32_e32 v76, v37
	v_pk_add_f32 v[34:35], v[42:43], v[78:79]
	v_pk_mul_f32 v[40:41], v[80:81], v[80:81]
	v_mov_b32_e32 v47, v74
	v_mov_b32_e32 v46, v38
	v_mov_b32_e32 v74, v39
	v_pk_add_f32 v[36:37], v[44:45], v[76:77]
	v_pk_add_f32 v[32:33], v[32:33], v[34:35]
	v_mov_b32_e32 v49, v80
	v_mov_b32_e32 v48, v40
	v_mov_b32_e32 v80, v41
	v_pk_add_f32 v[38:39], v[46:47], v[74:75]
	v_pk_add_f32 v[32:33], v[36:37], v[32:33]
	v_pk_add_f32 v[40:41], v[48:49], v[80:81]
	v_pk_add_f32 v[32:33], v[38:39], v[32:33]
	v_pk_mul_f32 v[36:37], v[86:87], v[86:87]
	v_pk_add_f32 v[34:35], v[40:41], v[32:33]
	v_pk_mul_f32 v[32:33], v[90:91], v[90:91]
	v_pk_mul_f32 v[38:39], v[84:85], v[84:85]
	v_mov_b32_e32 v43, v90
	v_mov_b32_e32 v42, v32
	v_mov_b32_e32 v90, v33
	v_pk_mul_f32 v[40:41], v[82:83], v[82:83]
	v_mov_b32_e32 v45, v86
	v_mov_b32_e32 v47, v84
	v_mov_b32_e32 v44, v36
	v_mov_b32_e32 v86, v37
	v_mov_b32_e32 v46, v38
	v_mov_b32_e32 v84, v39
	v_pk_add_f32 v[36:37], v[42:43], v[90:91]
	v_mov_b32_e32 v49, v82
	v_mov_b32_e32 v48, v40
	v_mov_b32_e32 v82, v41
	v_pk_add_f32 v[38:39], v[44:45], v[86:87]
	v_pk_add_f32 v[40:41], v[46:47], v[84:85]
	v_pk_add_f32 v[34:35], v[34:35], v[36:37]
	v_pk_mul_f32 v[36:37], v[94:95], v[94:95]
	v_pk_add_f32 v[34:35], v[38:39], v[34:35]
	v_mov_b32_e32 v39, v96
	v_pk_add_f32 v[34:35], v[40:41], v[34:35]
	v_mov_b32_e32 v41, v94
	v_mov_b32_e32 v40, v36
	v_mov_b32_e32 v94, v37
	v_pk_mul_f32 v[54:55], v[98:99], v[98:99]
	v_pk_add_f32 v[36:37], v[40:41], v[94:95]
	v_mov_b32_e32 v57, v98
	v_mov_b32_e32 v56, v54
	v_mov_b32_e32 v98, v55
	v_pk_add_f32 v[40:41], v[56:57], v[98:99]
	v_mov_b32_e32 v55, v100
	v_mov_b32_e32 v57, v106
	v_mov_b32_e32 v158, s17
	v_pk_mul_f32 v[58:59], v[10:11], v[10:11]
	v_mov_b32_e32 v61, v12
	v_mov_b32_e32 v63, v10
	v_mov_b32_e32 v62, v58
	v_mov_b32_e32 v10, v59
	v_pk_add_f32 v[10:11], v[62:63], v[10:11]
	v_mov_b32_e32 v76, 0
	v_mov_b32_e32 v77, 0
	v_mov_b32_e32 v78, 0
	v_mov_b32_e32 v79, 0
	v_mov_b32_e32 v72, 0
	v_mov_b32_e32 v73, 0
	v_mov_b32_e32 v74, 0
	v_mov_b32_e32 v75, 0
	s_waitcnt vmcnt(1)
	v_mov_b32_e32 v28, v228
	v_mov_b32_e32 v29, v229
	v_mov_b32_e32 v30, v230
	v_mov_b32_e32 v31, v231
	v_lshlrev_b32_e32 v32, 16, v28
	v_and_b32_e32 v33, 0xffff0000, v28
	v_lshlrev_b32_e32 v28, 16, v29
	v_and_b32_e32 v29, 0xffff0000, v29
	v_lshlrev_b32_e32 v42, 16, v30
	v_and_b32_e32 v43, 0xffff0000, v30
	v_lshlrev_b32_e32 v30, 16, v31
	v_and_b32_e32 v31, 0xffff0000, v31
	v_pk_mul_f32 v[44:45], v[32:33], v[32:33]
	v_pk_mul_f32 v[46:47], v[28:29], v[28:29]
	v_pk_mul_f32 v[50:51], v[42:43], v[42:43]
	v_pk_mul_f32 v[52:53], v[30:31], v[30:31]
	v_pk_fma_f32 v[44:45], v[44:45], s[38:39], 1.0 op_sel_hi:[1,0,0]
	v_pk_fma_f32 v[46:47], v[46:47], s[38:39], 1.0 op_sel_hi:[1,0,0]
	v_pk_fma_f32 v[50:51], v[50:51], s[38:39], 1.0 op_sel_hi:[1,0,0]
	v_pk_fma_f32 v[52:53], v[52:53], s[38:39], 1.0 op_sel_hi:[1,0,0]
	v_pk_mul_f32 v[44:45], v[44:45], v[32:33]
	v_pk_mul_f32 v[46:47], v[46:47], v[28:29]
	v_pk_mul_f32 v[50:51], v[50:51], v[42:43]
	v_pk_mul_f32 v[52:53], v[52:53], v[30:31]
	v_pk_mul_f32 v[44:45], v[44:45], s[36:37] op_sel_hi:[1,0]
	v_pk_mul_f32 v[46:47], v[46:47], s[36:37] op_sel_hi:[1,0]
	v_pk_mul_f32 v[50:51], v[50:51], s[36:37] op_sel_hi:[1,0]
	v_pk_mul_f32 v[52:53], v[52:53], s[36:37] op_sel_hi:[1,0]
	v_exp_f32_e32 v44, v44
	v_exp_f32_e32 v45, v45
	v_exp_f32_e32 v46, v46
	v_exp_f32_e32 v47, v47
	v_exp_f32_e32 v50, v50
	v_exp_f32_e32 v51, v51
	v_exp_f32_e32 v52, v52
	v_exp_f32_e32 v53, v53
	v_pk_add_f32 v[44:45], v[44:45], 1.0 op_sel_hi:[1,0]
	v_pk_add_f32 v[46:47], v[46:47], 1.0 op_sel_hi:[1,0]
	v_pk_add_f32 v[50:51], v[50:51], 1.0 op_sel_hi:[1,0]
	v_pk_add_f32 v[52:53], v[52:53], 1.0 op_sel_hi:[1,0]
	v_rcp_f32_e32 v44, v44
	v_rcp_f32_e32 v45, v45
	v_rcp_f32_e32 v46, v46
	v_rcp_f32_e32 v47, v47
	v_rcp_f32_e32 v50, v50
	v_rcp_f32_e32 v51, v51
	v_rcp_f32_e32 v52, v52
	v_rcp_f32_e32 v53, v53
	v_pk_mul_f32 v[44:45], v[44:45], v[32:33]
	v_pk_mul_f32 v[46:47], v[46:47], v[28:29]
	v_pk_mul_f32 v[42:43], v[50:51], v[42:43]
	v_pk_mul_f32 v[50:51], v[52:53], v[30:31]
	v_cvt_pk_bf16_f32 v29, v44, v45
	v_cvt_pk_bf16_f32 v28, v46, v47
	v_cvt_pk_bf16_f32 v27, v42, v43
	v_mov_b32_e32 v53, v92
	v_cvt_pk_bf16_f32 v25, v50, v51
	v_pk_add_f32 v[4:5], v[48:49], v[82:83]
	v_pk_mul_f32 v[48:49], v[92:93], v[92:93]
	v_pk_add_f32 v[4:5], v[4:5], v[34:35]
	v_pk_mul_f32 v[34:35], v[96:97], v[96:97]
	v_mov_b32_e32 v52, v48
	v_mov_b32_e32 v38, v34
	v_mov_b32_e32 v96, v35
	v_pk_add_f32 v[34:35], v[38:39], v[96:97]
	v_mov_b32_e32 v92, v49
	v_pk_add_f32 v[4:5], v[4:5], v[34:35]
	v_pk_add_f32 v[38:39], v[52:53], v[92:93]
	v_pk_add_f32 v[4:5], v[36:37], v[4:5]
	v_pk_mul_f32 v[34:35], v[104:105], v[104:105]
	v_pk_add_f32 v[4:5], v[38:39], v[4:5]
	v_pk_mul_f32 v[36:37], v[102:103], v[102:103]
	v_mov_b32_e32 v49, v104
	v_mov_b32_e32 v48, v34
	v_mov_b32_e32 v104, v35
	v_pk_add_f32 v[4:5], v[40:41], v[4:5]
	v_pk_mul_f32 v[38:39], v[100:101], v[100:101]
	v_mov_b32_e32 v53, v102
	v_mov_b32_e32 v52, v36
	v_mov_b32_e32 v102, v37
	v_pk_add_f32 v[34:35], v[48:49], v[104:105]
	v_pk_mul_f32 v[40:41], v[106:107], v[106:107]
	v_mov_b32_e32 v54, v38
	v_mov_b32_e32 v100, v39
	v_pk_add_f32 v[36:37], v[52:53], v[102:103]
	v_pk_add_f32 v[4:5], v[4:5], v[34:35]
	v_mov_b32_e32 v56, v40
	v_mov_b32_e32 v106, v41
	v_pk_add_f32 v[38:39], v[54:55], v[100:101]
	v_pk_add_f32 v[4:5], v[36:37], v[4:5]
	v_pk_mul_f32 v[34:35], v[8:9], v[8:9]
	v_pk_add_f32 v[40:41], v[56:57], v[106:107]
	v_pk_add_f32 v[4:5], v[38:39], v[4:5]
	v_pk_mul_f32 v[36:37], v[6:7], v[6:7]
	v_mov_b32_e32 v49, v8
	v_mov_b32_e32 v48, v34
	v_mov_b32_e32 v8, v35
	v_pk_add_f32 v[4:5], v[40:41], v[4:5]
	v_pk_mul_f32 v[38:39], v[2:3], v[2:3]
	v_mov_b32_e32 v53, v6
	v_mov_b32_e32 v52, v36
	v_mov_b32_e32 v6, v37
	v_pk_add_f32 v[8:9], v[48:49], v[8:9]
	v_pk_mul_f32 v[40:41], v[0:1], v[0:1]
	v_mov_b32_e32 v55, v2
	v_mov_b32_e32 v54, v38
	v_mov_b32_e32 v2, v39
	v_pk_add_f32 v[6:7], v[52:53], v[6:7]
	v_pk_add_f32 v[4:5], v[4:5], v[8:9]
	v_mov_b32_e32 v57, v0
	v_mov_b32_e32 v56, v40
	v_mov_b32_e32 v0, v41
	v_pk_add_f32 v[2:3], v[54:55], v[2:3]
	v_pk_add_f32 v[4:5], v[6:7], v[4:5]
	v_pk_add_f32 v[0:1], v[56:57], v[0:1]
	v_pk_add_f32 v[2:3], v[2:3], v[4:5]
	v_pk_mul_f32 v[8:9], v[16:17], v[16:17]
	v_pk_add_f32 v[0:1], v[0:1], v[2:3]
	v_mov_b32_e32 v35, v16
	v_pk_mul_f32 v[52:53], v[14:15], v[14:15]
	v_mov_b32_e32 v34, v8
	v_mov_b32_e32 v16, v9
	v_mov_b32_e32 v55, v14
	v_pk_mul_f32 v[56:57], v[12:13], v[12:13]
	v_mov_b32_e32 v54, v52
	v_mov_b32_e32 v14, v53
	v_pk_add_f32 v[8:9], v[34:35], v[16:17]
	v_mov_b32_e32 v60, v56
	v_mov_b32_e32 v12, v57
	v_pk_add_f32 v[14:15], v[54:55], v[14:15]
	v_pk_add_f32 v[0:1], v[0:1], v[8:9]
	v_pk_add_f32 v[12:13], v[60:61], v[12:13]
	v_pk_add_f32 v[0:1], v[14:15], v[0:1]
	v_pk_mul_f32 v[8:9], v[44:45], v[44:45]
	v_pk_add_f32 v[0:1], v[12:13], v[0:1]
	v_mov_b32_e32 v17, v44
	s_waitcnt vmcnt(0)
	v_mov_b32_e32 v30, v232
	v_mov_b32_e32 v31, v233
	v_mov_b32_e32 v32, v234
	v_mov_b32_e32 v33, v235
	v_lshlrev_b32_e32 v2, 16, v30
	v_and_b32_e32 v3, 0xffff0000, v30
	v_lshlrev_b32_e32 v4, 16, v31
	v_and_b32_e32 v5, 0xffff0000, v31
	v_lshlrev_b32_e32 v6, 16, v32
	v_and_b32_e32 v7, 0xffff0000, v32
	v_lshlrev_b32_e32 v30, 16, v33
	v_and_b32_e32 v31, 0xffff0000, v33
	v_pk_mul_f32 v[32:33], v[2:3], v[2:3]
	v_pk_mul_f32 v[36:37], v[4:5], v[4:5]
	v_pk_mul_f32 v[38:39], v[6:7], v[6:7]
	v_pk_mul_f32 v[40:41], v[30:31], v[30:31]
	v_pk_fma_f32 v[32:33], v[32:33], s[38:39], 1.0 op_sel_hi:[1,0,0]
	v_pk_fma_f32 v[36:37], v[36:37], s[38:39], 1.0 op_sel_hi:[1,0,0]
	v_pk_fma_f32 v[38:39], v[38:39], s[38:39], 1.0 op_sel_hi:[1,0,0]
	v_pk_fma_f32 v[40:41], v[40:41], s[38:39], 1.0 op_sel_hi:[1,0,0]
	v_pk_mul_f32 v[32:33], v[32:33], v[2:3]
	v_pk_mul_f32 v[36:37], v[36:37], v[4:5]
	v_pk_mul_f32 v[38:39], v[38:39], v[6:7]
	v_pk_mul_f32 v[40:41], v[40:41], v[30:31]
	v_pk_mul_f32 v[32:33], v[32:33], s[36:37] op_sel_hi:[1,0]
	v_pk_mul_f32 v[36:37], v[36:37], s[36:37] op_sel_hi:[1,0]
	v_pk_mul_f32 v[38:39], v[38:39], s[36:37] op_sel_hi:[1,0]
	v_pk_mul_f32 v[40:41], v[40:41], s[36:37] op_sel_hi:[1,0]
	v_exp_f32_e32 v32, v32
	v_exp_f32_e32 v33, v33
	v_exp_f32_e32 v36, v36
	v_exp_f32_e32 v37, v37
	v_exp_f32_e32 v38, v38
	v_exp_f32_e32 v39, v39
	v_exp_f32_e32 v40, v40
	v_exp_f32_e32 v41, v41
	v_pk_add_f32 v[32:33], v[32:33], 1.0 op_sel_hi:[1,0]
	v_pk_add_f32 v[36:37], v[36:37], 1.0 op_sel_hi:[1,0]
	v_pk_add_f32 v[38:39], v[38:39], 1.0 op_sel_hi:[1,0]
	v_pk_add_f32 v[40:41], v[40:41], 1.0 op_sel_hi:[1,0]
	v_rcp_f32_e32 v32, v32
	v_rcp_f32_e32 v33, v33
	v_rcp_f32_e32 v36, v36
	v_rcp_f32_e32 v37, v37
	v_rcp_f32_e32 v38, v38
	v_rcp_f32_e32 v39, v39
	v_rcp_f32_e32 v40, v40
	v_rcp_f32_e32 v41, v41
	v_pk_mul_f32 v[32:33], v[32:33], v[2:3]
	v_pk_mul_f32 v[36:37], v[36:37], v[4:5]
	v_pk_mul_f32 v[38:39], v[38:39], v[6:7]
	v_pk_mul_f32 v[30:31], v[40:41], v[30:31]
	v_cvt_pk_bf16_f32 v6, v32, v33
	v_cvt_pk_bf16_f32 v5, v36, v37
	v_cvt_pk_bf16_f32 v4, v38, v39
	v_pk_add_f32 v[0:1], v[10:11], v[0:1]
	v_cvt_pk_bf16_f32 v3, v30, v31
	s_waitcnt lgkmcnt(0)
	global_load_dwordx2 v[172:173], v158, s[8:9]
	global_load_dwordx2 v[174:175], v158, s[10:11]
	global_load_dwordx2 v[176:177], v158, s[8:9] offset:8
	global_load_dwordx2 v[178:179], v158, s[10:11] offset:8
	global_load_dwordx2 v[180:181], v158, s[8:9] offset:16
	global_load_dwordx2 v[182:183], v158, s[10:11] offset:16
	global_load_dwordx2 v[184:185], v158, s[8:9] offset:24
	global_load_dwordx2 v[186:187], v158, s[10:11] offset:24
	global_load_dwordx2 v[188:189], v158, s[8:9] offset:32
	global_load_dwordx2 v[190:191], v158, s[10:11] offset:32
	global_load_dwordx2 v[192:193], v158, s[8:9] offset:40
	global_load_dwordx2 v[194:195], v158, s[10:11] offset:40
	global_load_dwordx2 v[196:197], v158, s[8:9] offset:48
	global_load_dwordx2 v[198:199], v158, s[10:11] offset:48
	global_load_dwordx2 v[200:201], v158, s[8:9] offset:56
	global_load_dwordx2 v[202:203], v158, s[10:11] offset:56
	global_load_dwordx2 v[204:205], v158, s[8:9] offset:64
	global_load_dwordx2 v[206:207], v158, s[10:11] offset:64
	global_load_dwordx2 v[208:209], v158, s[8:9] offset:72
	global_load_dwordx2 v[210:211], v158, s[10:11] offset:72
	global_load_dwordx2 v[212:213], v158, s[8:9] offset:80
	global_load_dwordx2 v[214:215], v158, s[10:11] offset:80
	global_load_dwordx2 v[216:217], v158, s[8:9] offset:88
	global_load_dwordx2 v[218:219], v158, s[10:11] offset:88
	global_load_dwordx2 v[220:221], v158, s[8:9] offset:96
	global_load_dwordx2 v[222:223], v158, s[10:11] offset:96
	global_load_dwordx2 v[228:229], v158, s[8:9] offset:104
	global_load_dwordx2 v[230:231], v158, s[10:11] offset:104
	global_load_dwordx2 v[232:233], v158, s[8:9] offset:112
	global_load_dwordx2 v[234:235], v158, s[10:11] offset:112
	global_load_dwordx2 v[236:237], v158, s[8:9] offset:120
	global_load_dwordx2 v[238:239], v158, s[10:11] offset:120
	v_pk_mul_f32 v[10:11], v[46:47], v[46:47]
	v_mov_b32_e32 v16, v8
	v_mov_b32_e32 v44, v9
	v_pk_mul_f32 v[12:13], v[42:43], v[42:43]
	v_mov_b32_e32 v35, v46
	v_mov_b32_e32 v34, v10
	v_mov_b32_e32 v46, v11
	v_pk_add_f32 v[8:9], v[16:17], v[44:45]
	v_pk_mul_f32 v[14:15], v[50:51], v[50:51]
	v_mov_b32_e32 v53, v42
	v_mov_b32_e32 v52, v12
	v_mov_b32_e32 v42, v13
	v_pk_add_f32 v[10:11], v[34:35], v[46:47]
	v_pk_add_f32 v[0:1], v[0:1], v[8:9]
	v_mov_b32_e32 v55, v50
	v_mov_b32_e32 v54, v14
	v_mov_b32_e32 v50, v15
	v_pk_add_f32 v[12:13], v[52:53], v[42:43]
	v_pk_add_f32 v[0:1], v[10:11], v[0:1]
	v_pk_mul_f32 v[8:9], v[32:33], v[32:33]
	v_pk_add_f32 v[14:15], v[54:55], v[50:51]
	v_pk_add_f32 v[0:1], v[12:13], v[0:1]
	v_pk_mul_f32 v[10:11], v[36:37], v[36:37]
	v_mov_b32_e32 v17, v32
	v_mov_b32_e32 v16, v8
	v_mov_b32_e32 v32, v9
	v_pk_add_f32 v[0:1], v[14:15], v[0:1]
	v_pk_mul_f32 v[12:13], v[38:39], v[38:39]
	v_mov_b32_e32 v35, v36
	v_mov_b32_e32 v34, v10
	v_mov_b32_e32 v36, v11
	v_pk_add_f32 v[8:9], v[16:17], v[32:33]
	v_pk_mul_f32 v[14:15], v[30:31], v[30:31]
	v_mov_b32_e32 v43, v38
	v_mov_b32_e32 v42, v12
	v_mov_b32_e32 v38, v13
	v_pk_add_f32 v[10:11], v[34:35], v[36:37]
	v_pk_add_f32 v[0:1], v[0:1], v[8:9]
	v_mov_b32_e32 v45, v30
	v_mov_b32_e32 v44, v14
	v_mov_b32_e32 v30, v15
	v_pk_add_f32 v[12:13], v[42:43], v[38:39]
	v_pk_add_f32 v[0:1], v[10:11], v[0:1]
	v_pk_add_f32 v[14:15], v[44:45], v[30:31]
	v_pk_add_f32 v[0:1], v[12:13], v[0:1]
	v_lshlrev_b32_e32 v8, 16, v114
	v_pk_add_f32 v[0:1], v[14:15], v[0:1]
	v_and_b32_e32 v9, 0xffff0000, v114
	v_pk_mul_f32 v[0:1], v[0:1], s[40:41] op_sel_hi:[1,0]
	v_lshlrev_b32_e32 v12, 16, v112
	v_fma_f32 v2, -v1, v1, v0
	v_max_f32_e32 v2, 0, v2
	v_add_f32_e32 v2, 0x3727c5ac, v2
	v_rsq_f32_e32 v2, v2
	v_pk_add_f32 v[8:9], v[8:9], v[0:1] op_sel:[0,1] neg_lo:[0,1] neg_hi:[0,1]
	v_and_b32_e32 v13, 0xffff0000, v112
	s_mul_i32 s41, s41, 0x8a00
	v_pk_mul_f32 v[8:9], v[8:9], v[2:3] op_sel_hi:[1,0]
	v_pk_add_f32 v[12:13], v[12:13], v[0:1] op_sel:[0,1] neg_lo:[0,1] neg_hi:[0,1]
	s_add_i32 s17, s41, 0
	v_pk_mul_f32 v[12:13], v[12:13], v[2:3] op_sel_hi:[1,0]
	v_lshl_add_u32 v7, v109, 1, s17
	v_and_b32_e32 v15, 0xffff0000, v3
	s_waitcnt vmcnt(30)
	v_pk_fma_f32 v[8:9], v[172:173], v[8:9], v[174:175]
	s_nop 0
	v_cvt_pk_bf16_f32 v14, v8, v9
	ds_write_b16 v7, v14
	ds_write_b16_d16_hi v7, v14 offset:272
	s_waitcnt vmcnt(28)
	v_pk_fma_f32 v[8:9], v[176:177], v[12:13], v[178:179]
	s_nop 0
	v_cvt_pk_bf16_f32 v14, v8, v9
	v_lshlrev_b32_e32 v12, 16, v111
	v_and_b32_e32 v13, 0xffff0000, v111
	v_pk_add_f32 v[12:13], v[12:13], v[0:1] op_sel:[0,1] neg_lo:[0,1] neg_hi:[0,1]
	ds_write_b16 v7, v14 offset:544
	ds_write_b16_d16_hi v7, v14 offset:816
	v_pk_mul_f32 v[12:13], v[12:13], v[2:3] op_sel_hi:[1,0]
	s_waitcnt vmcnt(26)
	v_pk_fma_f32 v[8:9], v[180:181], v[12:13], v[182:183]
	s_nop 0
	v_cvt_pk_bf16_f32 v14, v8, v9
	v_lshlrev_b32_e32 v12, 16, v110
	v_and_b32_e32 v13, 0xffff0000, v110
	v_pk_add_f32 v[12:13], v[12:13], v[0:1] op_sel:[0,1] neg_lo:[0,1] neg_hi:[0,1]
	ds_write_b16 v7, v14 offset:1088
	ds_write_b16_d16_hi v7, v14 offset:1360
	v_pk_mul_f32 v[12:13], v[12:13], v[2:3] op_sel_hi:[1,0]
	s_waitcnt vmcnt(24)
	v_pk_fma_f32 v[8:9], v[184:185], v[12:13], v[186:187]
	s_nop 0
	v_cvt_pk_bf16_f32 v14, v8, v9
	v_lshlrev_b32_e32 v12, 16, v117
	v_and_b32_e32 v13, 0xffff0000, v117
	v_pk_add_f32 v[12:13], v[12:13], v[0:1] op_sel:[0,1] neg_lo:[0,1] neg_hi:[0,1]
	ds_write_b16 v7, v14 offset:1632
	ds_write_b16_d16_hi v7, v14 offset:1904
	v_pk_mul_f32 v[12:13], v[12:13], v[2:3] op_sel_hi:[1,0]
	s_waitcnt vmcnt(22)
	v_pk_fma_f32 v[8:9], v[188:189], v[12:13], v[190:191]
	s_nop 0
	v_cvt_pk_bf16_f32 v14, v8, v9
	v_lshlrev_b32_e32 v12, 16, v116
	v_and_b32_e32 v13, 0xffff0000, v116
	v_pk_add_f32 v[12:13], v[12:13], v[0:1] op_sel:[0,1] neg_lo:[0,1] neg_hi:[0,1]
	ds_write_b16 v7, v14 offset:2176
	ds_write_b16_d16_hi v7, v14 offset:2448
	v_pk_mul_f32 v[12:13], v[12:13], v[2:3] op_sel_hi:[1,0]
	s_waitcnt vmcnt(20)
	v_pk_fma_f32 v[8:9], v[12:13], v[192:193], v[194:195]
	s_nop 0
	v_cvt_pk_bf16_f32 v14, v8, v9
	v_lshlrev_b32_e32 v12, 16, v115
	v_and_b32_e32 v13, 0xffff0000, v115
	v_pk_add_f32 v[12:13], v[12:13], v[0:1] op_sel:[0,1] neg_lo:[0,1] neg_hi:[0,1]
	ds_write_b16 v7, v14 offset:2720
	ds_write_b16_d16_hi v7, v14 offset:2992
	v_pk_mul_f32 v[12:13], v[12:13], v[2:3] op_sel_hi:[1,0]
	v_bfe_u32 v115, v108, 5, 1
	v_lshlrev_b32_e32 v88, 5, v115
	v_lshl_add_u64 v[90:91], s[12:13], 0, v[88:89]
	s_waitcnt vmcnt(18)
	v_pk_fma_f32 v[8:9], v[12:13], v[196:197], v[198:199]
	s_nop 0
	v_cvt_pk_bf16_f32 v14, v8, v9
	v_lshlrev_b32_e32 v12, 16, v113
	v_and_b32_e32 v13, 0xffff0000, v113
	v_pk_add_f32 v[12:13], v[12:13], v[0:1] op_sel:[0,1] neg_lo:[0,1] neg_hi:[0,1]
	ds_write_b16 v7, v14 offset:3264
	ds_write_b16_d16_hi v7, v14 offset:3536
	v_pk_mul_f32 v[12:13], v[12:13], v[2:3] op_sel_hi:[1,0]
	s_waitcnt vmcnt(16)
	v_pk_fma_f32 v[8:9], v[12:13], v[200:201], v[202:203]
	s_nop 0
	v_cvt_pk_bf16_f32 v14, v8, v9
	global_load_dwordx2 v[172:173], v158, s[8:9] offset:128
	global_load_dwordx2 v[174:175], v158, s[10:11] offset:128
	global_load_dwordx2 v[176:177], v158, s[8:9] offset:136
	global_load_dwordx2 v[178:179], v158, s[10:11] offset:136
	global_load_dwordx2 v[180:181], v158, s[8:9] offset:144
	global_load_dwordx2 v[182:183], v158, s[10:11] offset:144
	global_load_dwordx2 v[184:185], v158, s[8:9] offset:152
	global_load_dwordx2 v[186:187], v158, s[10:11] offset:152
	global_load_dwordx2 v[188:189], v158, s[8:9] offset:160
	global_load_dwordx2 v[190:191], v158, s[10:11] offset:160
	global_load_dwordx2 v[192:193], v158, s[8:9] offset:168
	global_load_dwordx2 v[194:195], v158, s[10:11] offset:168
	global_load_dwordx2 v[196:197], v158, s[8:9] offset:176
	global_load_dwordx2 v[198:199], v158, s[10:11] offset:176
	global_load_dwordx2 v[200:201], v158, s[8:9] offset:184
	global_load_dwordx2 v[202:203], v158, s[10:11] offset:184
	v_lshlrev_b32_e32 v12, 16, v122
	v_and_b32_e32 v13, 0xffff0000, v122
	v_pk_add_f32 v[12:13], v[12:13], v[0:1] op_sel:[0,1] neg_lo:[0,1] neg_hi:[0,1]
	ds_write_b16 v7, v14 offset:3808
	ds_write_b16_d16_hi v7, v14 offset:4080
	v_pk_mul_f32 v[12:13], v[12:13], v[2:3] op_sel_hi:[1,0]
	s_waitcnt vmcnt(30)
	v_pk_fma_f32 v[8:9], v[12:13], v[204:205], v[206:207]
	s_nop 0
	v_cvt_pk_bf16_f32 v14, v8, v9
	v_lshlrev_b32_e32 v12, 16, v120
	v_and_b32_e32 v13, 0xffff0000, v120
	v_pk_add_f32 v[12:13], v[12:13], v[0:1] op_sel:[0,1] neg_lo:[0,1] neg_hi:[0,1]
	ds_write_b16 v7, v14 offset:4352
	ds_write_b16_d16_hi v7, v14 offset:4624
	v_pk_mul_f32 v[12:13], v[12:13], v[2:3] op_sel_hi:[1,0]
	s_waitcnt vmcnt(28)
	v_pk_fma_f32 v[8:9], v[12:13], v[208:209], v[210:211]
	s_nop 0
	v_cvt_pk_bf16_f32 v14, v8, v9
	v_lshlrev_b32_e32 v12, 16, v119
	v_and_b32_e32 v13, 0xffff0000, v119
	v_pk_add_f32 v[12:13], v[12:13], v[0:1] op_sel:[0,1] neg_lo:[0,1] neg_hi:[0,1]
	ds_write_b16 v7, v14 offset:4896
	ds_write_b16_d16_hi v7, v14 offset:5168
	v_pk_mul_f32 v[12:13], v[12:13], v[2:3] op_sel_hi:[1,0]
	s_waitcnt vmcnt(26)
	v_pk_fma_f32 v[8:9], v[12:13], v[212:213], v[214:215]
	s_nop 0
	v_cvt_pk_bf16_f32 v14, v8, v9
	v_lshlrev_b32_e32 v12, 16, v118
	v_and_b32_e32 v13, 0xffff0000, v118
	v_pk_add_f32 v[12:13], v[12:13], v[0:1] op_sel:[0,1] neg_lo:[0,1] neg_hi:[0,1]
	ds_write_b16 v7, v14 offset:5440
	ds_write_b16_d16_hi v7, v14 offset:5712
	v_pk_mul_f32 v[12:13], v[12:13], v[2:3] op_sel_hi:[1,0]
	v_and_b32_e32 v118, 31, v108
	s_waitcnt vmcnt(24)
	v_pk_fma_f32 v[8:9], v[12:13], v[216:217], v[218:219]
	s_nop 0
	v_cvt_pk_bf16_f32 v14, v8, v9
	v_lshlrev_b32_e32 v12, 16, v126
	v_and_b32_e32 v13, 0xffff0000, v126
	v_pk_add_f32 v[12:13], v[12:13], v[0:1] op_sel:[0,1] neg_lo:[0,1] neg_hi:[0,1]
	ds_write_b16 v7, v14 offset:5984
	ds_write_b16_d16_hi v7, v14 offset:6256
	v_pk_mul_f32 v[12:13], v[12:13], v[2:3] op_sel_hi:[1,0]
	s_waitcnt vmcnt(22)
	v_pk_fma_f32 v[8:9], v[12:13], v[220:221], v[222:223]
	s_nop 0
	v_cvt_pk_bf16_f32 v14, v8, v9
	v_lshlrev_b32_e32 v12, 16, v124
	v_and_b32_e32 v13, 0xffff0000, v124
	v_pk_add_f32 v[12:13], v[12:13], v[0:1] op_sel:[0,1] neg_lo:[0,1] neg_hi:[0,1]
	ds_write_b16 v7, v14 offset:6528
	ds_write_b16_d16_hi v7, v14 offset:6800
	v_pk_mul_f32 v[12:13], v[12:13], v[2:3] op_sel_hi:[1,0]
	s_waitcnt vmcnt(20)
	v_pk_fma_f32 v[8:9], v[12:13], v[228:229], v[230:231]
	s_nop 0
	v_cvt_pk_bf16_f32 v14, v8, v9
	v_lshlrev_b32_e32 v12, 16, v123
	v_and_b32_e32 v13, 0xffff0000, v123
	v_pk_add_f32 v[12:13], v[12:13], v[0:1] op_sel:[0,1] neg_lo:[0,1] neg_hi:[0,1]
	ds_write_b16 v7, v14 offset:7072
	ds_write_b16_d16_hi v7, v14 offset:7344
	v_pk_mul_f32 v[12:13], v[12:13], v[2:3] op_sel_hi:[1,0]
	s_waitcnt vmcnt(18)
	v_pk_fma_f32 v[8:9], v[12:13], v[232:233], v[234:235]
	s_nop 0
	v_cvt_pk_bf16_f32 v14, v8, v9
	v_lshlrev_b32_e32 v12, 16, v121
	v_and_b32_e32 v13, 0xffff0000, v121
	v_pk_add_f32 v[12:13], v[12:13], v[0:1] op_sel:[0,1] neg_lo:[0,1] neg_hi:[0,1]
	ds_write_b16 v7, v14 offset:7616
	ds_write_b16_d16_hi v7, v14 offset:7888
	v_pk_mul_f32 v[12:13], v[12:13], v[2:3] op_sel_hi:[1,0]
	s_waitcnt vmcnt(16)
	v_pk_fma_f32 v[8:9], v[12:13], v[236:237], v[238:239]
	s_nop 0
	v_cvt_pk_bf16_f32 v14, v8, v9
	global_load_dwordx2 v[204:205], v158, s[8:9] offset:192
	global_load_dwordx2 v[206:207], v158, s[10:11] offset:192
	global_load_dwordx2 v[208:209], v158, s[8:9] offset:200
	global_load_dwordx2 v[210:211], v158, s[10:11] offset:200
	global_load_dwordx2 v[212:213], v158, s[8:9] offset:208
	global_load_dwordx2 v[214:215], v158, s[10:11] offset:208
	global_load_dwordx2 v[216:217], v158, s[8:9] offset:216
	global_load_dwordx2 v[218:219], v158, s[10:11] offset:216
	global_load_dwordx2 v[220:221], v158, s[8:9] offset:224
	global_load_dwordx2 v[222:223], v158, s[10:11] offset:224
	global_load_dwordx2 v[228:229], v158, s[8:9] offset:232
	global_load_dwordx2 v[230:231], v158, s[10:11] offset:232
	global_load_dwordx2 v[232:233], v158, s[8:9] offset:240
	global_load_dwordx2 v[234:235], v158, s[10:11] offset:240
	global_load_dwordx2 v[236:237], v158, s[8:9] offset:248
	global_load_dwordx2 v[238:239], v158, s[10:11] offset:248
	v_lshlrev_b32_e32 v12, 16, v129
	v_and_b32_e32 v13, 0xffff0000, v129
	v_pk_add_f32 v[12:13], v[12:13], v[0:1] op_sel:[0,1] neg_lo:[0,1] neg_hi:[0,1]
	ds_write_b16 v7, v14 offset:8160
	ds_write_b16_d16_hi v7, v14 offset:8432
	v_pk_mul_f32 v[12:13], v[12:13], v[2:3] op_sel_hi:[1,0]
	s_waitcnt vmcnt(30)
	v_pk_fma_f32 v[8:9], v[12:13], v[172:173], v[174:175]
	s_nop 0
	v_cvt_pk_bf16_f32 v14, v8, v9
	v_lshlrev_b32_e32 v12, 16, v128
	v_and_b32_e32 v13, 0xffff0000, v128
	v_pk_add_f32 v[12:13], v[12:13], v[0:1] op_sel:[0,1] neg_lo:[0,1] neg_hi:[0,1]
	ds_write_b16 v7, v14 offset:8704
	ds_write_b16_d16_hi v7, v14 offset:8976
	v_pk_mul_f32 v[12:13], v[12:13], v[2:3] op_sel_hi:[1,0]
	s_waitcnt vmcnt(28)
	v_pk_fma_f32 v[8:9], v[12:13], v[176:177], v[178:179]
	s_nop 0
	v_cvt_pk_bf16_f32 v14, v8, v9
	v_lshlrev_b32_e32 v12, 16, v127
	v_and_b32_e32 v13, 0xffff0000, v127
	v_pk_add_f32 v[12:13], v[12:13], v[0:1] op_sel:[0,1] neg_lo:[0,1] neg_hi:[0,1]
	ds_write_b16 v7, v14 offset:9248
	ds_write_b16_d16_hi v7, v14 offset:9520
	v_pk_mul_f32 v[12:13], v[12:13], v[2:3] op_sel_hi:[1,0]
	s_waitcnt vmcnt(26)
	v_pk_fma_f32 v[8:9], v[12:13], v[180:181], v[182:183]
	s_nop 0
	v_cvt_pk_bf16_f32 v14, v8, v9
	v_lshlrev_b32_e32 v12, 16, v125
	v_and_b32_e32 v13, 0xffff0000, v125
	v_pk_add_f32 v[12:13], v[12:13], v[0:1] op_sel:[0,1] neg_lo:[0,1] neg_hi:[0,1]
	ds_write_b16 v7, v14 offset:9792
	ds_write_b16_d16_hi v7, v14 offset:10064
	v_pk_mul_f32 v[12:13], v[12:13], v[2:3] op_sel_hi:[1,0]
	s_waitcnt vmcnt(24)
	v_pk_fma_f32 v[8:9], v[12:13], v[184:185], v[186:187]
	s_nop 0
	v_cvt_pk_bf16_f32 v14, v8, v9
	v_lshlrev_b32_e32 v12, 16, v134
	v_and_b32_e32 v13, 0xffff0000, v134
	v_pk_add_f32 v[12:13], v[12:13], v[0:1] op_sel:[0,1] neg_lo:[0,1] neg_hi:[0,1]
	ds_write_b16 v7, v14 offset:10336
	ds_write_b16_d16_hi v7, v14 offset:10608
	v_pk_mul_f32 v[12:13], v[12:13], v[2:3] op_sel_hi:[1,0]
	s_waitcnt vmcnt(22)
	v_pk_fma_f32 v[8:9], v[12:13], v[188:189], v[190:191]
	s_nop 0
	v_cvt_pk_bf16_f32 v14, v8, v9
	v_lshlrev_b32_e32 v12, 16, v132
	v_and_b32_e32 v13, 0xffff0000, v132
	v_pk_add_f32 v[12:13], v[12:13], v[0:1] op_sel:[0,1] neg_lo:[0,1] neg_hi:[0,1]
	ds_write_b16 v7, v14 offset:10880
	ds_write_b16_d16_hi v7, v14 offset:11152
	v_pk_mul_f32 v[12:13], v[12:13], v[2:3] op_sel_hi:[1,0]
	s_waitcnt vmcnt(20)
	v_pk_fma_f32 v[8:9], v[12:13], v[192:193], v[194:195]
	s_nop 0
	v_cvt_pk_bf16_f32 v14, v8, v9
	v_lshlrev_b32_e32 v12, 16, v131
	v_and_b32_e32 v13, 0xffff0000, v131
	v_pk_add_f32 v[12:13], v[12:13], v[0:1] op_sel:[0,1] neg_lo:[0,1] neg_hi:[0,1]
	ds_write_b16 v7, v14 offset:11424
	ds_write_b16_d16_hi v7, v14 offset:11696
	v_pk_mul_f32 v[12:13], v[12:13], v[2:3] op_sel_hi:[1,0]
	s_waitcnt vmcnt(18)
	v_pk_fma_f32 v[8:9], v[12:13], v[196:197], v[198:199]
	s_nop 0
	v_cvt_pk_bf16_f32 v14, v8, v9
	v_lshlrev_b32_e32 v12, 16, v130
	v_and_b32_e32 v13, 0xffff0000, v130
	v_pk_add_f32 v[12:13], v[12:13], v[0:1] op_sel:[0,1] neg_lo:[0,1] neg_hi:[0,1]
	ds_write_b16 v7, v14 offset:11968
	ds_write_b16_d16_hi v7, v14 offset:12240
	v_pk_mul_f32 v[12:13], v[12:13], v[2:3] op_sel_hi:[1,0]
	s_waitcnt vmcnt(16)
	v_pk_fma_f32 v[8:9], v[12:13], v[200:201], v[202:203]
	s_nop 0
	v_cvt_pk_bf16_f32 v14, v8, v9
	global_load_dwordx2 v[172:173], v158, s[8:9] offset:256
	global_load_dwordx2 v[174:175], v158, s[10:11] offset:256
	global_load_dwordx2 v[176:177], v158, s[8:9] offset:264
	global_load_dwordx2 v[178:179], v158, s[10:11] offset:264
	global_load_dwordx2 v[180:181], v158, s[8:9] offset:272
	global_load_dwordx2 v[182:183], v158, s[10:11] offset:272
	global_load_dwordx2 v[184:185], v158, s[8:9] offset:280
	global_load_dwordx2 v[186:187], v158, s[10:11] offset:280
	global_load_dwordx2 v[188:189], v158, s[8:9] offset:288
	global_load_dwordx2 v[190:191], v158, s[10:11] offset:288
	global_load_dwordx2 v[192:193], v158, s[8:9] offset:296
	global_load_dwordx2 v[194:195], v158, s[10:11] offset:296
	global_load_dwordx2 v[196:197], v158, s[8:9] offset:304
	global_load_dwordx2 v[198:199], v158, s[10:11] offset:304
	global_load_dwordx2 v[200:201], v158, s[8:9] offset:312
	global_load_dwordx2 v[202:203], v158, s[10:11] offset:312
	v_lshlrev_b32_e32 v12, 16, v137
	v_and_b32_e32 v13, 0xffff0000, v137
	v_pk_add_f32 v[12:13], v[12:13], v[0:1] op_sel:[0,1] neg_lo:[0,1] neg_hi:[0,1]
	ds_write_b16 v7, v14 offset:12512
	ds_write_b16_d16_hi v7, v14 offset:12784
	v_pk_mul_f32 v[12:13], v[12:13], v[2:3] op_sel_hi:[1,0]
	s_waitcnt vmcnt(30)
	v_pk_fma_f32 v[8:9], v[12:13], v[204:205], v[206:207]
	s_nop 0
	v_cvt_pk_bf16_f32 v14, v8, v9
	v_lshlrev_b32_e32 v12, 16, v136
	v_and_b32_e32 v13, 0xffff0000, v136
	v_pk_add_f32 v[12:13], v[12:13], v[0:1] op_sel:[0,1] neg_lo:[0,1] neg_hi:[0,1]
	ds_write_b16 v7, v14 offset:13056
	ds_write_b16_d16_hi v7, v14 offset:13328
	v_pk_mul_f32 v[12:13], v[12:13], v[2:3] op_sel_hi:[1,0]
	s_waitcnt vmcnt(28)
	v_pk_fma_f32 v[8:9], v[12:13], v[208:209], v[210:211]
	s_nop 0
	v_cvt_pk_bf16_f32 v14, v8, v9
	v_lshlrev_b32_e32 v12, 16, v135
	v_and_b32_e32 v13, 0xffff0000, v135
	v_pk_add_f32 v[12:13], v[12:13], v[0:1] op_sel:[0,1] neg_lo:[0,1] neg_hi:[0,1]
	ds_write_b16 v7, v14 offset:13600
	ds_write_b16_d16_hi v7, v14 offset:13872
	v_pk_mul_f32 v[12:13], v[12:13], v[2:3] op_sel_hi:[1,0]
	s_waitcnt vmcnt(26)
	v_pk_fma_f32 v[8:9], v[12:13], v[212:213], v[214:215]
	s_nop 0
	v_cvt_pk_bf16_f32 v14, v8, v9
	v_lshlrev_b32_e32 v12, 16, v133
	v_and_b32_e32 v13, 0xffff0000, v133
	v_pk_add_f32 v[12:13], v[12:13], v[0:1] op_sel:[0,1] neg_lo:[0,1] neg_hi:[0,1]
	ds_write_b16 v7, v14 offset:14144
	ds_write_b16_d16_hi v7, v14 offset:14416
	v_pk_mul_f32 v[12:13], v[12:13], v[2:3] op_sel_hi:[1,0]
	s_waitcnt vmcnt(24)
	v_pk_fma_f32 v[8:9], v[12:13], v[216:217], v[218:219]
	s_nop 0
	v_cvt_pk_bf16_f32 v14, v8, v9
	v_lshlrev_b32_e32 v12, 16, v142
	v_and_b32_e32 v13, 0xffff0000, v142
	v_pk_add_f32 v[12:13], v[12:13], v[0:1] op_sel:[0,1] neg_lo:[0,1] neg_hi:[0,1]
	ds_write_b16 v7, v14 offset:14688
	ds_write_b16_d16_hi v7, v14 offset:14960
	v_pk_mul_f32 v[12:13], v[12:13], v[2:3] op_sel_hi:[1,0]
	s_waitcnt vmcnt(22)
	v_pk_fma_f32 v[8:9], v[12:13], v[220:221], v[222:223]
	s_nop 0
	v_cvt_pk_bf16_f32 v14, v8, v9
	v_lshlrev_b32_e32 v12, 16, v140
	v_and_b32_e32 v13, 0xffff0000, v140
	v_pk_add_f32 v[12:13], v[12:13], v[0:1] op_sel:[0,1] neg_lo:[0,1] neg_hi:[0,1]
	ds_write_b16 v7, v14 offset:15232
	ds_write_b16_d16_hi v7, v14 offset:15504
	v_pk_mul_f32 v[12:13], v[12:13], v[2:3] op_sel_hi:[1,0]
	s_waitcnt vmcnt(20)
	v_pk_fma_f32 v[8:9], v[12:13], v[228:229], v[230:231]
	s_nop 0
	v_cvt_pk_bf16_f32 v14, v8, v9
	v_lshlrev_b32_e32 v12, 16, v139
	v_and_b32_e32 v13, 0xffff0000, v139
	v_pk_add_f32 v[12:13], v[12:13], v[0:1] op_sel:[0,1] neg_lo:[0,1] neg_hi:[0,1]
	ds_write_b16 v7, v14 offset:15776
	ds_write_b16_d16_hi v7, v14 offset:16048
	v_pk_mul_f32 v[12:13], v[12:13], v[2:3] op_sel_hi:[1,0]
	s_waitcnt vmcnt(18)
	v_pk_fma_f32 v[8:9], v[12:13], v[232:233], v[234:235]
	s_nop 0
	v_cvt_pk_bf16_f32 v14, v8, v9
	v_lshlrev_b32_e32 v12, 16, v138
	v_and_b32_e32 v13, 0xffff0000, v138
	v_pk_add_f32 v[12:13], v[12:13], v[0:1] op_sel:[0,1] neg_lo:[0,1] neg_hi:[0,1]
	ds_write_b16 v7, v14 offset:16320
	ds_write_b16_d16_hi v7, v14 offset:16592
	v_pk_mul_f32 v[12:13], v[12:13], v[2:3] op_sel_hi:[1,0]
	s_waitcnt vmcnt(16)
	v_pk_fma_f32 v[8:9], v[12:13], v[236:237], v[238:239]
	s_nop 0
	v_cvt_pk_bf16_f32 v14, v8, v9
	global_load_dwordx2 v[204:205], v158, s[8:9] offset:320
	global_load_dwordx2 v[206:207], v158, s[10:11] offset:320
	global_load_dwordx2 v[208:209], v158, s[8:9] offset:328
	global_load_dwordx2 v[210:211], v158, s[10:11] offset:328
	global_load_dwordx2 v[212:213], v158, s[8:9] offset:336
	global_load_dwordx2 v[214:215], v158, s[10:11] offset:336
	global_load_dwordx2 v[216:217], v158, s[8:9] offset:344
	global_load_dwordx2 v[218:219], v158, s[10:11] offset:344
	global_load_dwordx2 v[220:221], v158, s[8:9] offset:352
	global_load_dwordx2 v[222:223], v158, s[10:11] offset:352
	global_load_dwordx2 v[228:229], v158, s[8:9] offset:360
	global_load_dwordx2 v[230:231], v158, s[10:11] offset:360
	global_load_dwordx2 v[232:233], v158, s[8:9] offset:368
	global_load_dwordx2 v[234:235], v158, s[10:11] offset:368
	global_load_dwordx2 v[236:237], v158, s[8:9] offset:376
	global_load_dwordx2 v[238:239], v158, s[10:11] offset:376
	v_lshlrev_b32_e32 v12, 16, v146
	v_and_b32_e32 v13, 0xffff0000, v146
	v_pk_add_f32 v[12:13], v[12:13], v[0:1] op_sel:[0,1] neg_lo:[0,1] neg_hi:[0,1]
	ds_write_b16 v7, v14 offset:16864
	ds_write_b16_d16_hi v7, v14 offset:17136
	v_pk_mul_f32 v[12:13], v[12:13], v[2:3] op_sel_hi:[1,0]
	s_waitcnt vmcnt(30)
	v_pk_fma_f32 v[8:9], v[12:13], v[172:173], v[174:175]
	s_nop 0
	v_cvt_pk_bf16_f32 v14, v8, v9
	v_lshlrev_b32_e32 v12, 16, v144
	v_and_b32_e32 v13, 0xffff0000, v144
	v_pk_add_f32 v[12:13], v[12:13], v[0:1] op_sel:[0,1] neg_lo:[0,1] neg_hi:[0,1]
	ds_write_b16 v7, v14 offset:17408
	ds_write_b16_d16_hi v7, v14 offset:17680
	v_pk_mul_f32 v[12:13], v[12:13], v[2:3] op_sel_hi:[1,0]
	s_waitcnt vmcnt(28)
	v_pk_fma_f32 v[8:9], v[12:13], v[176:177], v[178:179]
	s_nop 0
	v_cvt_pk_bf16_f32 v14, v8, v9
	v_lshlrev_b32_e32 v12, 16, v143
	v_and_b32_e32 v13, 0xffff0000, v143
	v_pk_add_f32 v[12:13], v[12:13], v[0:1] op_sel:[0,1] neg_lo:[0,1] neg_hi:[0,1]
	ds_write_b16 v7, v14 offset:17952
	ds_write_b16_d16_hi v7, v14 offset:18224
	v_pk_mul_f32 v[12:13], v[12:13], v[2:3] op_sel_hi:[1,0]
	s_waitcnt vmcnt(26)
	v_pk_fma_f32 v[8:9], v[12:13], v[180:181], v[182:183]
	s_nop 0
	v_cvt_pk_bf16_f32 v14, v8, v9
	v_lshlrev_b32_e32 v12, 16, v141
	v_and_b32_e32 v13, 0xffff0000, v141
	v_pk_add_f32 v[12:13], v[12:13], v[0:1] op_sel:[0,1] neg_lo:[0,1] neg_hi:[0,1]
	ds_write_b16 v7, v14 offset:18496
	ds_write_b16_d16_hi v7, v14 offset:18768
	v_pk_mul_f32 v[12:13], v[12:13], v[2:3] op_sel_hi:[1,0]
	s_waitcnt vmcnt(24)
	v_pk_fma_f32 v[8:9], v[12:13], v[184:185], v[186:187]
	s_nop 0
	v_cvt_pk_bf16_f32 v14, v8, v9
	v_lshlrev_b32_e32 v12, 16, v149
	v_and_b32_e32 v13, 0xffff0000, v149
	v_pk_add_f32 v[12:13], v[12:13], v[0:1] op_sel:[0,1] neg_lo:[0,1] neg_hi:[0,1]
	ds_write_b16 v7, v14 offset:19040
	ds_write_b16_d16_hi v7, v14 offset:19312
	v_pk_mul_f32 v[12:13], v[12:13], v[2:3] op_sel_hi:[1,0]
	s_waitcnt vmcnt(22)
	v_pk_fma_f32 v[8:9], v[12:13], v[188:189], v[190:191]
	s_nop 0
	v_cvt_pk_bf16_f32 v14, v8, v9
	v_lshlrev_b32_e32 v12, 16, v148
	v_and_b32_e32 v13, 0xffff0000, v148
	v_pk_add_f32 v[12:13], v[12:13], v[0:1] op_sel:[0,1] neg_lo:[0,1] neg_hi:[0,1]
	ds_write_b16 v7, v14 offset:19584
	ds_write_b16_d16_hi v7, v14 offset:19856
	v_pk_mul_f32 v[12:13], v[12:13], v[2:3] op_sel_hi:[1,0]
	s_waitcnt vmcnt(20)
	v_pk_fma_f32 v[8:9], v[12:13], v[192:193], v[194:195]
	s_nop 0
	v_cvt_pk_bf16_f32 v14, v8, v9
	v_lshlrev_b32_e32 v12, 16, v147
	v_and_b32_e32 v13, 0xffff0000, v147
	v_pk_add_f32 v[12:13], v[12:13], v[0:1] op_sel:[0,1] neg_lo:[0,1] neg_hi:[0,1]
	ds_write_b16 v7, v14 offset:20128
	ds_write_b16_d16_hi v7, v14 offset:20400
	v_pk_mul_f32 v[12:13], v[12:13], v[2:3] op_sel_hi:[1,0]
	s_waitcnt vmcnt(18)
	v_pk_fma_f32 v[8:9], v[12:13], v[196:197], v[198:199]
	s_nop 0
	v_cvt_pk_bf16_f32 v14, v8, v9
	v_lshlrev_b32_e32 v12, 16, v145
	v_and_b32_e32 v13, 0xffff0000, v145
	v_pk_add_f32 v[12:13], v[12:13], v[0:1] op_sel:[0,1] neg_lo:[0,1] neg_hi:[0,1]
	ds_write_b16 v7, v14 offset:20672
	ds_write_b16_d16_hi v7, v14 offset:20944
	v_pk_mul_f32 v[12:13], v[12:13], v[2:3] op_sel_hi:[1,0]
	s_waitcnt vmcnt(16)
	v_pk_fma_f32 v[8:9], v[12:13], v[200:201], v[202:203]
	s_nop 0
	v_cvt_pk_bf16_f32 v14, v8, v9
	global_load_dwordx2 v[172:173], v158, s[8:9] offset:384
	global_load_dwordx2 v[174:175], v158, s[10:11] offset:384
	global_load_dwordx2 v[176:177], v158, s[8:9] offset:392
	global_load_dwordx2 v[178:179], v158, s[10:11] offset:392
	global_load_dwordx2 v[180:181], v158, s[8:9] offset:400
	global_load_dwordx2 v[182:183], v158, s[10:11] offset:400
	global_load_dwordx2 v[184:185], v158, s[8:9] offset:408
	global_load_dwordx2 v[186:187], v158, s[10:11] offset:408
	global_load_dwordx2 v[188:189], v158, s[8:9] offset:416
	global_load_dwordx2 v[190:191], v158, s[10:11] offset:416
	global_load_dwordx2 v[192:193], v158, s[8:9] offset:424
	global_load_dwordx2 v[194:195], v158, s[10:11] offset:424
	global_load_dwordx2 v[196:197], v158, s[8:9] offset:432
	global_load_dwordx2 v[198:199], v158, s[10:11] offset:432
	global_load_dwordx2 v[200:201], v158, s[8:9] offset:440
	global_load_dwordx2 v[202:203], v158, s[10:11] offset:440
	v_lshlrev_b32_e32 v12, 16, v154
	v_and_b32_e32 v13, 0xffff0000, v154
	v_pk_add_f32 v[12:13], v[12:13], v[0:1] op_sel:[0,1] neg_lo:[0,1] neg_hi:[0,1]
	ds_write_b16 v7, v14 offset:21216
	ds_write_b16_d16_hi v7, v14 offset:21488
	v_pk_mul_f32 v[12:13], v[12:13], v[2:3] op_sel_hi:[1,0]
	s_waitcnt vmcnt(30)
	v_pk_fma_f32 v[8:9], v[12:13], v[204:205], v[206:207]
	s_nop 0
	v_cvt_pk_bf16_f32 v14, v8, v9
	v_lshlrev_b32_e32 v12, 16, v152
	v_and_b32_e32 v13, 0xffff0000, v152
	v_pk_add_f32 v[12:13], v[12:13], v[0:1] op_sel:[0,1] neg_lo:[0,1] neg_hi:[0,1]
	ds_write_b16 v7, v14 offset:21760
	ds_write_b16_d16_hi v7, v14 offset:22032
	v_pk_mul_f32 v[12:13], v[12:13], v[2:3] op_sel_hi:[1,0]
	s_waitcnt vmcnt(28)
	v_pk_fma_f32 v[8:9], v[12:13], v[208:209], v[210:211]
	s_nop 0
	v_cvt_pk_bf16_f32 v14, v8, v9
	v_lshlrev_b32_e32 v12, 16, v151
	v_and_b32_e32 v13, 0xffff0000, v151
	v_pk_add_f32 v[12:13], v[12:13], v[0:1] op_sel:[0,1] neg_lo:[0,1] neg_hi:[0,1]
	ds_write_b16 v7, v14 offset:22304
	ds_write_b16_d16_hi v7, v14 offset:22576
	v_pk_mul_f32 v[12:13], v[12:13], v[2:3] op_sel_hi:[1,0]
	s_waitcnt vmcnt(26)
	v_pk_fma_f32 v[8:9], v[12:13], v[212:213], v[214:215]
	s_nop 0
	v_cvt_pk_bf16_f32 v14, v8, v9
	v_lshlrev_b32_e32 v12, 16, v150
	v_and_b32_e32 v13, 0xffff0000, v150
	v_pk_add_f32 v[12:13], v[12:13], v[0:1] op_sel:[0,1] neg_lo:[0,1] neg_hi:[0,1]
	ds_write_b16 v7, v14 offset:22848
	ds_write_b16_d16_hi v7, v14 offset:23120
	v_pk_mul_f32 v[12:13], v[12:13], v[2:3] op_sel_hi:[1,0]
	s_waitcnt vmcnt(24)
	v_pk_fma_f32 v[8:9], v[12:13], v[216:217], v[218:219]
	s_nop 0
	v_cvt_pk_bf16_f32 v14, v8, v9
	v_lshlrev_b32_e32 v12, 16, v157
	v_and_b32_e32 v13, 0xffff0000, v157
	v_pk_add_f32 v[12:13], v[12:13], v[0:1] op_sel:[0,1] neg_lo:[0,1] neg_hi:[0,1]
	ds_write_b16 v7, v14 offset:23392
	ds_write_b16_d16_hi v7, v14 offset:23664
	v_pk_mul_f32 v[12:13], v[12:13], v[2:3] op_sel_hi:[1,0]
	s_waitcnt vmcnt(22)
	v_pk_fma_f32 v[8:9], v[12:13], v[220:221], v[222:223]
	s_nop 0
	v_cvt_pk_bf16_f32 v14, v8, v9
	v_lshlrev_b32_e32 v12, 16, v156
	v_and_b32_e32 v13, 0xffff0000, v156
	v_pk_add_f32 v[12:13], v[12:13], v[0:1] op_sel:[0,1] neg_lo:[0,1] neg_hi:[0,1]
	ds_write_b16 v7, v14 offset:23936
	ds_write_b16_d16_hi v7, v14 offset:24208
	v_pk_mul_f32 v[12:13], v[12:13], v[2:3] op_sel_hi:[1,0]
	s_waitcnt vmcnt(20)
	v_pk_fma_f32 v[8:9], v[12:13], v[228:229], v[230:231]
	s_nop 0
	v_cvt_pk_bf16_f32 v14, v8, v9
	v_lshlrev_b32_e32 v12, 16, v155
	v_and_b32_e32 v13, 0xffff0000, v155
	v_pk_add_f32 v[12:13], v[12:13], v[0:1] op_sel:[0,1] neg_lo:[0,1] neg_hi:[0,1]
	ds_write_b16 v7, v14 offset:24480
	ds_write_b16_d16_hi v7, v14 offset:24752
	v_pk_mul_f32 v[12:13], v[12:13], v[2:3] op_sel_hi:[1,0]
	s_waitcnt vmcnt(18)
	v_pk_fma_f32 v[8:9], v[12:13], v[232:233], v[234:235]
	s_nop 0
	v_cvt_pk_bf16_f32 v14, v8, v9
	v_lshlrev_b32_e32 v12, 16, v153
	v_and_b32_e32 v13, 0xffff0000, v153
	v_pk_add_f32 v[12:13], v[12:13], v[0:1] op_sel:[0,1] neg_lo:[0,1] neg_hi:[0,1]
	ds_write_b16 v7, v14 offset:25024
	ds_write_b16_d16_hi v7, v14 offset:25296
	v_pk_mul_f32 v[12:13], v[12:13], v[2:3] op_sel_hi:[1,0]
	s_waitcnt vmcnt(16)
	v_pk_fma_f32 v[8:9], v[12:13], v[236:237], v[238:239]
	s_nop 0
	v_cvt_pk_bf16_f32 v14, v8, v9
	global_load_dwordx2 v[204:205], v158, s[8:9] offset:448
	global_load_dwordx2 v[206:207], v158, s[10:11] offset:448
	global_load_dwordx2 v[208:209], v158, s[8:9] offset:456
	global_load_dwordx2 v[210:211], v158, s[10:11] offset:456
	global_load_dwordx2 v[212:213], v158, s[8:9] offset:464
	global_load_dwordx2 v[214:215], v158, s[10:11] offset:464
	global_load_dwordx2 v[216:217], v158, s[8:9] offset:472
	global_load_dwordx2 v[218:219], v158, s[10:11] offset:472
	global_load_dwordx2 v[220:221], v158, s[8:9] offset:480
	global_load_dwordx2 v[222:223], v158, s[10:11] offset:480
	global_load_dwordx2 v[228:229], v158, s[8:9] offset:488
	global_load_dwordx2 v[230:231], v158, s[10:11] offset:488
	global_load_dwordx2 v[232:233], v158, s[8:9] offset:496
	global_load_dwordx2 v[234:235], v158, s[10:11] offset:496
	global_load_dwordx2 v[236:237], v158, s[8:9] offset:504
	global_load_dwordx2 v[238:239], v158, s[10:11] offset:504
	v_lshlrev_b32_e32 v12, 16, v22
	v_and_b32_e32 v13, 0xffff0000, v22
	v_pk_add_f32 v[12:13], v[12:13], v[0:1] op_sel:[0,1] neg_lo:[0,1] neg_hi:[0,1]
	ds_write_b16 v7, v14 offset:25568
	ds_write_b16_d16_hi v7, v14 offset:25840
	v_pk_mul_f32 v[12:13], v[12:13], v[2:3] op_sel_hi:[1,0]
	s_waitcnt vmcnt(30)
	v_pk_fma_f32 v[8:9], v[12:13], v[172:173], v[174:175]
	s_nop 0
	v_cvt_pk_bf16_f32 v14, v8, v9
	v_lshlrev_b32_e32 v12, 16, v20
	v_and_b32_e32 v13, 0xffff0000, v20
	v_pk_add_f32 v[12:13], v[12:13], v[0:1] op_sel:[0,1] neg_lo:[0,1] neg_hi:[0,1]
	ds_write_b16 v7, v14 offset:26112
	ds_write_b16_d16_hi v7, v14 offset:26384
	v_pk_mul_f32 v[12:13], v[12:13], v[2:3] op_sel_hi:[1,0]
	s_waitcnt vmcnt(28)
	v_pk_fma_f32 v[8:9], v[12:13], v[176:177], v[178:179]
	s_nop 0
	v_cvt_pk_bf16_f32 v14, v8, v9
	v_lshlrev_b32_e32 v12, 16, v19
	v_and_b32_e32 v13, 0xffff0000, v19
	v_pk_add_f32 v[12:13], v[12:13], v[0:1] op_sel:[0,1] neg_lo:[0,1] neg_hi:[0,1]
	ds_write_b16 v7, v14 offset:26656
	ds_write_b16_d16_hi v7, v14 offset:26928
	v_pk_mul_f32 v[12:13], v[12:13], v[2:3] op_sel_hi:[1,0]
	s_waitcnt vmcnt(26)
	v_pk_fma_f32 v[8:9], v[12:13], v[180:181], v[182:183]
	s_nop 0
	v_cvt_pk_bf16_f32 v14, v8, v9
	v_lshlrev_b32_e32 v12, 16, v18
	v_and_b32_e32 v13, 0xffff0000, v18
	v_pk_add_f32 v[12:13], v[12:13], v[0:1] op_sel:[0,1] neg_lo:[0,1] neg_hi:[0,1]
	ds_write_b16 v7, v14 offset:27200
	ds_write_b16_d16_hi v7, v14 offset:27472
	v_pk_mul_f32 v[12:13], v[12:13], v[2:3] op_sel_hi:[1,0]
	s_waitcnt vmcnt(24)
	v_pk_fma_f32 v[8:9], v[12:13], v[184:185], v[186:187]
	s_nop 0
	v_cvt_pk_bf16_f32 v14, v8, v9
	v_lshlrev_b32_e32 v12, 16, v26
	v_and_b32_e32 v13, 0xffff0000, v26
	v_pk_add_f32 v[12:13], v[12:13], v[0:1] op_sel:[0,1] neg_lo:[0,1] neg_hi:[0,1]
	ds_write_b16 v7, v14 offset:27744
	ds_write_b16_d16_hi v7, v14 offset:28016
	v_pk_mul_f32 v[12:13], v[12:13], v[2:3] op_sel_hi:[1,0]
	s_waitcnt vmcnt(22)
	v_pk_fma_f32 v[8:9], v[12:13], v[188:189], v[190:191]
	s_nop 0
	v_cvt_pk_bf16_f32 v14, v8, v9
	v_lshlrev_b32_e32 v12, 16, v24
	v_and_b32_e32 v13, 0xffff0000, v24
	v_pk_add_f32 v[12:13], v[12:13], v[0:1] op_sel:[0,1] neg_lo:[0,1] neg_hi:[0,1]
	ds_write_b16 v7, v14 offset:28288
	ds_write_b16_d16_hi v7, v14 offset:28560
	v_pk_mul_f32 v[12:13], v[12:13], v[2:3] op_sel_hi:[1,0]
	s_waitcnt vmcnt(20)
	v_pk_fma_f32 v[8:9], v[12:13], v[192:193], v[194:195]
	s_nop 0
	v_cvt_pk_bf16_f32 v14, v8, v9
	v_lshlrev_b32_e32 v12, 16, v23
	v_and_b32_e32 v13, 0xffff0000, v23
	v_pk_add_f32 v[12:13], v[12:13], v[0:1] op_sel:[0,1] neg_lo:[0,1] neg_hi:[0,1]
	ds_write_b16 v7, v14 offset:28832
	ds_write_b16_d16_hi v7, v14 offset:29104
	v_pk_mul_f32 v[12:13], v[12:13], v[2:3] op_sel_hi:[1,0]
	s_waitcnt vmcnt(18)
	v_pk_fma_f32 v[8:9], v[12:13], v[196:197], v[198:199]
	s_nop 0
	v_cvt_pk_bf16_f32 v14, v8, v9
	v_lshlrev_b32_e32 v12, 16, v21
	v_and_b32_e32 v13, 0xffff0000, v21
	v_pk_add_f32 v[12:13], v[12:13], v[0:1] op_sel:[0,1] neg_lo:[0,1] neg_hi:[0,1]
	ds_write_b16 v7, v14 offset:29376
	ds_write_b16_d16_hi v7, v14 offset:29648
	v_pk_mul_f32 v[12:13], v[12:13], v[2:3] op_sel_hi:[1,0]
	s_waitcnt vmcnt(16)
	v_pk_fma_f32 v[8:9], v[12:13], v[200:201], v[202:203]
	s_nop 0
	v_cvt_pk_bf16_f32 v14, v8, v9
	v_lshlrev_b32_e32 v12, 16, v29
	v_and_b32_e32 v13, 0xffff0000, v29
	v_pk_add_f32 v[12:13], v[12:13], v[0:1] op_sel:[0,1] neg_lo:[0,1] neg_hi:[0,1]
	ds_write_b16 v7, v14 offset:29920
	ds_write_b16_d16_hi v7, v14 offset:30192
	v_pk_mul_f32 v[12:13], v[12:13], v[2:3] op_sel_hi:[1,0]
	s_waitcnt vmcnt(14)
	v_pk_fma_f32 v[8:9], v[12:13], v[204:205], v[206:207]
	s_nop 0
	v_cvt_pk_bf16_f32 v14, v8, v9
	v_lshlrev_b32_e32 v12, 16, v28
	v_and_b32_e32 v13, 0xffff0000, v28
	v_pk_add_f32 v[12:13], v[12:13], v[0:1] op_sel:[0,1] neg_lo:[0,1] neg_hi:[0,1]
	ds_write_b16 v7, v14 offset:30464
	ds_write_b16_d16_hi v7, v14 offset:30736
	v_pk_mul_f32 v[12:13], v[12:13], v[2:3] op_sel_hi:[1,0]
	s_waitcnt vmcnt(12)
	v_pk_fma_f32 v[8:9], v[12:13], v[208:209], v[210:211]
	s_nop 0
	v_cvt_pk_bf16_f32 v14, v8, v9
	v_lshlrev_b32_e32 v12, 16, v27
	v_and_b32_e32 v13, 0xffff0000, v27
	v_pk_add_f32 v[12:13], v[12:13], v[0:1] op_sel:[0,1] neg_lo:[0,1] neg_hi:[0,1]
	ds_write_b16 v7, v14 offset:31008
	ds_write_b16_d16_hi v7, v14 offset:31280
	v_pk_mul_f32 v[12:13], v[12:13], v[2:3] op_sel_hi:[1,0]
	s_waitcnt vmcnt(10)
	v_pk_fma_f32 v[8:9], v[12:13], v[212:213], v[214:215]
	s_nop 0
	v_cvt_pk_bf16_f32 v14, v8, v9
	v_lshlrev_b32_e32 v12, 16, v25
	v_and_b32_e32 v13, 0xffff0000, v25
	v_pk_add_f32 v[12:13], v[12:13], v[0:1] op_sel:[0,1] neg_lo:[0,1] neg_hi:[0,1]
	ds_write_b16 v7, v14 offset:31552
	ds_write_b16_d16_hi v7, v14 offset:31824
	v_pk_mul_f32 v[12:13], v[12:13], v[2:3] op_sel_hi:[1,0]
	s_waitcnt vmcnt(8)
	v_pk_fma_f32 v[8:9], v[12:13], v[216:217], v[218:219]
	s_nop 0
	v_cvt_pk_bf16_f32 v14, v8, v9
	v_lshlrev_b32_e32 v12, 16, v6
	v_and_b32_e32 v13, 0xffff0000, v6
	v_pk_add_f32 v[12:13], v[12:13], v[0:1] op_sel:[0,1] neg_lo:[0,1] neg_hi:[0,1]
	ds_write_b16 v7, v14 offset:32096
	ds_write_b16_d16_hi v7, v14 offset:32368
	v_pk_mul_f32 v[12:13], v[12:13], v[2:3] op_sel_hi:[1,0]
	v_lshlrev_b32_e32 v14, 16, v3
	s_waitcnt vmcnt(6)
	v_pk_fma_f32 v[8:9], v[12:13], v[220:221], v[222:223]
	s_nop 0
	v_cvt_pk_bf16_f32 v6, v8, v9
	v_lshlrev_b32_e32 v12, 16, v5
	v_and_b32_e32 v13, 0xffff0000, v5
	v_pk_add_f32 v[12:13], v[12:13], v[0:1] op_sel:[0,1] neg_lo:[0,1] neg_hi:[0,1]
	ds_write_b16 v7, v6 offset:32640
	ds_write_b16_d16_hi v7, v6 offset:32912
	v_pk_mul_f32 v[12:13], v[12:13], v[2:3] op_sel_hi:[1,0]
	s_waitcnt vmcnt(4)
	v_pk_fma_f32 v[8:9], v[12:13], v[228:229], v[230:231]
	s_nop 0
	v_cvt_pk_bf16_f32 v6, v8, v9
	v_lshlrev_b32_e32 v12, 16, v4
	v_and_b32_e32 v13, 0xffff0000, v4
	v_pk_add_f32 v[4:5], v[12:13], v[0:1] op_sel:[0,1] neg_lo:[0,1] neg_hi:[0,1]
	ds_write_b16 v7, v6 offset:33184
	ds_write_b16_d16_hi v7, v6 offset:33456
	v_pk_mul_f32 v[4:5], v[4:5], v[2:3] op_sel_hi:[1,0]
	v_pk_add_f32 v[0:1], v[14:15], v[0:1] op_sel:[0,1] neg_lo:[0,1] neg_hi:[0,1]
	s_waitcnt vmcnt(2)
	v_pk_fma_f32 v[4:5], v[4:5], v[232:233], v[234:235]
	s_nop 0
	v_cvt_pk_bf16_f32 v6, v4, v5
	s_bfe_u32 s8, s39, 0x10006
	v_lshl_or_b32 v124, s8, 5, v118
	v_or_b32_e32 v10, s37, v124
	v_pk_mul_f32 v[0:1], v[0:1], v[2:3] op_sel_hi:[1,0]
	v_lshlrev_b32_e32 v88, 9, v10
	v_lshl_add_u64 v[8:9], v[90:91], 0, v[88:89]
	ds_write_b16 v7, v6 offset:33728
	ds_write_b16_d16_hi v7, v6 offset:34000
	s_and_b32 s9, 64, s39
	s_cmp_eq_u32 s8, 0
	s_cselect_b64 s[12:13], -1, 0
	s_cmp_lg_u32 s9, 0
	s_cselect_b64 s[10:11], -1, 0
	s_and_b64 vcc, exec, s[12:13]
	s_waitcnt vmcnt(0)
	v_pk_fma_f32 v[0:1], v[0:1], v[236:237], v[238:239]
	s_nop 0
	v_cvt_pk_bf16_f32 v0, v0, v1
	ds_write_b16 v7, v0 offset:34272
	ds_write_b16_d16_hi v7, v0 offset:34544
	s_waitcnt lgkmcnt(0)
	s_barrier
	global_load_dwordx4 v[0:3], v[8:9], off offset:16
	global_load_dwordx4 v[4:7], v[8:9], off
	global_load_dwordx4 v[80:83], v[8:9], off offset:80
	global_load_dwordx4 v[84:87], v[8:9], off offset:64
	s_cbranch_vccnz .LBB0_404
	global_load_dwordx4 v[76:79], v[8:9], off offset:128
	global_load_dwordx4 v[72:75], v[8:9], off offset:144

.LBB0_1272:
	s_or_b64 exec, exec, s[10:11]
	v_mov_b32_e32 v108, v224
	s_waitcnt vmcnt(0)
	s_barrier
	s_load_dwordx8 s[12:19], s[38:39], 0x40
	s_movk_i32 s10, 0x80
	v_readfirstlane_b32 s11, v108
	s_ashr_i32 s45, s11, 7
	s_cmp_eq_u32 s45, 2
	s_cselect_b32 s10, s10, 0x100
	s_cmp_lg_u32 s45, 1
	s_cselect_b32 s10, s10, 0
	s_cmpk_gt_u32 s11, 0x7f
	s_cselect_b32 s10, s10, 0xffffff80
	s_add_i32 s10, s10, s64
	s_mov_b32 s39, 0
	s_lshr_b32 s38, s10, 2
	v_and_b32_e32 v109, 0x7f, v108
	s_lshl_b64 s[40:41], s[38:39], 7
	v_or_b32_e32 v2, s40, v109
	s_movk_i32 s10, 0x1400
	v_mov_b64_e32 v[0:1], s[20:21]
	v_mad_u64_u32 v[0:1], s[22:23], v2, s10, v[0:1]
	s_lshl_b32 s10, s64, 7
	v_mov_b32_e32 v2, 0x1400
	s_and_b32 s43, s10, 0x180
	v_mad_u32_u24 v1, s41, v2, v1
	s_lshl_b32 s38, s43, 1
	v_lshl_add_u64 v[4:5], v[0:1], 0, s[38:39]
	s_movk_i32 s10, 0x1000
	v_add_co_u32_e32 v0, vcc, s10, v4
	s_mov_b32 s42, 0x3d372713
	s_nop 0
	v_addc_co_u32_e32 v1, vcc, 0, v5, vcc
	global_load_dwordx4 v[0:3], v[0:1], off
	s_mov_b32 s10, 0xc0135761
	s_mov_b64 s[22:23], 0x1000
	v_lshl_add_u64 v[4:5], v[4:5], 0, s[22:23]
	global_load_dwordx4 v[172:175], v[4:5], off offset:16
	global_load_dwordx4 v[176:179], v[4:5], off offset:32
	global_load_dwordx4 v[180:183], v[4:5], off offset:48
	global_load_dwordx4 v[184:187], v[4:5], off offset:64
	global_load_dwordx4 v[188:191], v[4:5], off offset:80
	global_load_dwordx4 v[192:195], v[4:5], off offset:96
	global_load_dwordx4 v[196:199], v[4:5], off offset:112
	global_load_dwordx4 v[200:203], v[4:5], off offset:128
	global_load_dwordx4 v[204:207], v[4:5], off offset:144
	global_load_dwordx4 v[208:211], v[4:5], off offset:160
	global_load_dwordx4 v[212:215], v[4:5], off offset:176
	global_load_dwordx4 v[216:219], v[4:5], off offset:192
	global_load_dwordx4 v[220:223], v[4:5], off offset:208
	global_load_dwordx4 v[228:231], v[4:5], off offset:224
	global_load_dwordx4 v[232:235], v[4:5], off offset:240
	s_lshl_b32 s22, s43, 2
	s_brev_b32 s44, 60
	s_waitcnt vmcnt(15)
	v_lshlrev_b32_e32 v6, 16, v0
	v_and_b32_e32 v7, 0xffff0000, v0
	v_lshlrev_b32_e32 v0, 16, v1
	v_and_b32_e32 v1, 0xffff0000, v1
	v_lshlrev_b32_e32 v8, 16, v2
	v_and_b32_e32 v9, 0xffff0000, v2
	v_lshlrev_b32_e32 v2, 16, v3
	v_and_b32_e32 v3, 0xffff0000, v3
	v_pk_mul_f32 v[10:11], v[6:7], v[6:7]
	v_pk_mul_f32 v[12:13], v[0:1], v[0:1]
	v_pk_mul_f32 v[14:15], v[8:9], v[8:9]
	v_pk_mul_f32 v[16:17], v[2:3], v[2:3]
	v_pk_fma_f32 v[10:11], v[10:11], s[42:43], 1.0 op_sel_hi:[1,0,0]
	v_pk_fma_f32 v[12:13], v[12:13], s[42:43], 1.0 op_sel_hi:[1,0,0]
	v_pk_fma_f32 v[14:15], v[14:15], s[42:43], 1.0 op_sel_hi:[1,0,0]
	v_pk_fma_f32 v[16:17], v[16:17], s[42:43], 1.0 op_sel_hi:[1,0,0]
	v_pk_mul_f32 v[10:11], v[10:11], v[6:7]
	v_pk_mul_f32 v[12:13], v[12:13], v[0:1]
	v_pk_mul_f32 v[14:15], v[14:15], v[8:9]
	v_pk_mul_f32 v[16:17], v[16:17], v[2:3]
	v_pk_mul_f32 v[10:11], v[10:11], s[10:11] op_sel_hi:[1,0]
	v_pk_mul_f32 v[12:13], v[12:13], s[10:11] op_sel_hi:[1,0]
	v_pk_mul_f32 v[14:15], v[14:15], s[10:11] op_sel_hi:[1,0]
	v_pk_mul_f32 v[16:17], v[16:17], s[10:11] op_sel_hi:[1,0]
	v_exp_f32_e32 v10, v10
	v_exp_f32_e32 v11, v11
	v_exp_f32_e32 v12, v12
	v_exp_f32_e32 v13, v13
	v_exp_f32_e32 v14, v14
	v_exp_f32_e32 v15, v15
	v_exp_f32_e32 v16, v16
	v_exp_f32_e32 v17, v17
	v_pk_add_f32 v[10:11], v[10:11], 1.0 op_sel_hi:[1,0]
	v_pk_add_f32 v[12:13], v[12:13], 1.0 op_sel_hi:[1,0]
	v_pk_add_f32 v[18:19], v[14:15], 1.0 op_sel_hi:[1,0]
	v_pk_add_f32 v[16:17], v[16:17], 1.0 op_sel_hi:[1,0]
	v_rcp_f32_e32 v14, v10
	v_rcp_f32_e32 v15, v11
	v_rcp_f32_e32 v10, v12
	v_rcp_f32_e32 v11, v13
	v_rcp_f32_e32 v12, v18
	v_rcp_f32_e32 v13, v19
	v_rcp_f32_e32 v18, v16
	v_rcp_f32_e32 v19, v17
	v_pk_mul_f32 v[16:17], v[14:15], v[6:7]
	v_pk_mul_f32 v[10:11], v[10:11], v[0:1]
	v_pk_mul_f32 v[8:9], v[12:13], v[8:9]
	v_pk_mul_f32 v[12:13], v[18:19], v[2:3]
	v_cvt_pk_bf16_f32 v114, v16, v17
	v_cvt_pk_bf16_f32 v112, v10, v11
	v_cvt_pk_bf16_f32 v111, v8, v9
	v_pk_fma_f32 v[6:7], v[14:15], v[6:7], v[16:17] op_sel_hi:[1,1,0]
	v_cvt_pk_bf16_f32 v110, v12, v13
	v_pk_mul_f32 v[14:15], v[16:17], v[16:17]
	v_pk_mul_f32 v[16:17], v[10:11], v[10:11]
	v_mov_b32_e32 v165, v10
	v_mov_b32_e32 v164, v14
	v_mov_b32_e32 v10, v15
	v_mov_b32_e32 v6, v16
	v_mov_b32_e32 v167, v8
	v_pk_add_f32 v[10:11], v[164:165], v[10:11]
	v_pk_mul_f32 v[162:163], v[12:13], v[12:13]
	v_mov_b32_e32 v169, v12
	v_mov_b32_e32 v168, v162
	v_mov_b32_e32 v12, v163
	v_pk_add_f32 v[12:13], v[168:169], v[12:13]
	s_waitcnt vmcnt(14)
	v_mov_b32_e32 v0, v172
	v_mov_b32_e32 v1, v173
	v_mov_b32_e32 v2, v174
	v_mov_b32_e32 v3, v175
	v_lshlrev_b32_e32 v18, 16, v0
	v_and_b32_e32 v19, 0xffff0000, v0
	v_lshlrev_b32_e32 v0, 16, v1
	v_and_b32_e32 v1, 0xffff0000, v1
	v_lshlrev_b32_e32 v24, 16, v2
	v_and_b32_e32 v25, 0xffff0000, v2
	v_lshlrev_b32_e32 v2, 16, v3
	v_and_b32_e32 v3, 0xffff0000, v3
	v_pk_mul_f32 v[20:21], v[18:19], v[18:19]
	v_pk_mul_f32 v[22:23], v[0:1], v[0:1]
	v_pk_mul_f32 v[26:27], v[24:25], v[24:25]
	v_pk_mul_f32 v[28:29], v[2:3], v[2:3]
	v_pk_fma_f32 v[20:21], v[20:21], s[42:43], 1.0 op_sel_hi:[1,0,0]
	v_pk_fma_f32 v[22:23], v[22:23], s[42:43], 1.0 op_sel_hi:[1,0,0]
	v_pk_fma_f32 v[26:27], v[26:27], s[42:43], 1.0 op_sel_hi:[1,0,0]
	v_pk_fma_f32 v[28:29], v[28:29], s[42:43], 1.0 op_sel_hi:[1,0,0]
	v_pk_mul_f32 v[20:21], v[20:21], v[18:19]
	v_pk_mul_f32 v[22:23], v[22:23], v[0:1]
	v_pk_mul_f32 v[26:27], v[26:27], v[24:25]
	v_pk_mul_f32 v[28:29], v[28:29], v[2:3]
	v_pk_mul_f32 v[20:21], v[20:21], s[10:11] op_sel_hi:[1,0]
	v_pk_mul_f32 v[22:23], v[22:23], s[10:11] op_sel_hi:[1,0]
	v_pk_mul_f32 v[26:27], v[26:27], s[10:11] op_sel_hi:[1,0]
	v_pk_mul_f32 v[28:29], v[28:29], s[10:11] op_sel_hi:[1,0]
	v_exp_f32_e32 v20, v20
	v_exp_f32_e32 v21, v21
	v_exp_f32_e32 v22, v22
	v_exp_f32_e32 v23, v23
	v_exp_f32_e32 v26, v26
	v_exp_f32_e32 v27, v27
	v_exp_f32_e32 v28, v28
	v_exp_f32_e32 v29, v29
	v_pk_add_f32 v[20:21], v[20:21], 1.0 op_sel_hi:[1,0]
	v_pk_add_f32 v[22:23], v[22:23], 1.0 op_sel_hi:[1,0]
	v_pk_add_f32 v[26:27], v[26:27], 1.0 op_sel_hi:[1,0]
	v_pk_add_f32 v[28:29], v[28:29], 1.0 op_sel_hi:[1,0]
	v_rcp_f32_e32 v20, v20
	v_rcp_f32_e32 v21, v21
	v_rcp_f32_e32 v30, v22
	v_rcp_f32_e32 v31, v23
	v_rcp_f32_e32 v26, v26
	v_rcp_f32_e32 v27, v27
	v_rcp_f32_e32 v28, v28
	v_rcp_f32_e32 v29, v29
	v_pk_mul_f32 v[22:23], v[20:21], v[18:19]
	v_pk_mul_f32 v[20:21], v[30:31], v[0:1]
	v_pk_mul_f32 v[18:19], v[26:27], v[24:25]
	v_pk_mul_f32 v[24:25], v[28:29], v[2:3]
	v_cvt_pk_bf16_f32 v117, v22, v23
	v_cvt_pk_bf16_f32 v116, v20, v21
	v_cvt_pk_bf16_f32 v115, v18, v19
	v_mov_b32_e32 v163, v18
	v_cvt_pk_bf16_f32 v113, v24, v25
	v_pk_mul_f32 v[14:15], v[24:25], v[24:25]
	v_mov_b32_e32 v165, v24
	v_mov_b32_e32 v164, v14
	v_mov_b32_e32 v24, v15
	v_pk_add_f32 v[14:15], v[164:165], v[24:25]
	s_waitcnt vmcnt(13)
	v_mov_b32_e32 v0, v176
	v_mov_b32_e32 v1, v177
	v_mov_b32_e32 v2, v178
	v_mov_b32_e32 v3, v179
	v_lshlrev_b32_e32 v26, 16, v0
	v_and_b32_e32 v27, 0xffff0000, v0
	v_lshlrev_b32_e32 v0, 16, v1
	v_and_b32_e32 v1, 0xffff0000, v1
	v_lshlrev_b32_e32 v32, 16, v2
	v_and_b32_e32 v33, 0xffff0000, v2
	v_lshlrev_b32_e32 v2, 16, v3
	v_and_b32_e32 v3, 0xffff0000, v3
	v_pk_mul_f32 v[28:29], v[26:27], v[26:27]
	v_pk_mul_f32 v[30:31], v[0:1], v[0:1]
	v_pk_mul_f32 v[34:35], v[32:33], v[32:33]
	v_pk_mul_f32 v[36:37], v[2:3], v[2:3]
	v_pk_fma_f32 v[28:29], v[28:29], s[42:43], 1.0 op_sel_hi:[1,0,0]
	v_pk_fma_f32 v[30:31], v[30:31], s[42:43], 1.0 op_sel_hi:[1,0,0]
	v_pk_fma_f32 v[34:35], v[34:35], s[42:43], 1.0 op_sel_hi:[1,0,0]
	v_pk_fma_f32 v[36:37], v[36:37], s[42:43], 1.0 op_sel_hi:[1,0,0]
	v_pk_mul_f32 v[28:29], v[28:29], v[26:27]
	v_pk_mul_f32 v[30:31], v[30:31], v[0:1]
	v_pk_mul_f32 v[34:35], v[34:35], v[32:33]
	v_pk_mul_f32 v[36:37], v[36:37], v[2:3]
	v_pk_mul_f32 v[28:29], v[28:29], s[10:11] op_sel_hi:[1,0]
	v_pk_mul_f32 v[30:31], v[30:31], s[10:11] op_sel_hi:[1,0]
	v_pk_mul_f32 v[34:35], v[34:35], s[10:11] op_sel_hi:[1,0]
	v_pk_mul_f32 v[36:37], v[36:37], s[10:11] op_sel_hi:[1,0]
	v_exp_f32_e32 v28, v28
	v_exp_f32_e32 v29, v29
	v_exp_f32_e32 v30, v30
	v_exp_f32_e32 v31, v31
	v_exp_f32_e32 v34, v34
	v_exp_f32_e32 v35, v35
	v_exp_f32_e32 v36, v36
	v_exp_f32_e32 v37, v37
	v_pk_add_f32 v[28:29], v[28:29], 1.0 op_sel_hi:[1,0]
	v_pk_add_f32 v[30:31], v[30:31], 1.0 op_sel_hi:[1,0]
	v_pk_add_f32 v[34:35], v[34:35], 1.0 op_sel_hi:[1,0]
	v_pk_add_f32 v[36:37], v[36:37], 1.0 op_sel_hi:[1,0]
	v_rcp_f32_e32 v28, v28
	v_rcp_f32_e32 v29, v29
	v_rcp_f32_e32 v38, v30
	v_rcp_f32_e32 v39, v31
	v_rcp_f32_e32 v34, v34
	v_rcp_f32_e32 v35, v35
	v_rcp_f32_e32 v36, v36
	v_rcp_f32_e32 v37, v37
	v_pk_mul_f32 v[30:31], v[28:29], v[26:27]
	v_pk_mul_f32 v[28:29], v[38:39], v[0:1]
	v_pk_mul_f32 v[26:27], v[34:35], v[32:33]
	v_pk_mul_f32 v[32:33], v[36:37], v[2:3]
	v_cvt_pk_bf16_f32 v122, v30, v31
	v_cvt_pk_bf16_f32 v120, v28, v29
	v_cvt_pk_bf16_f32 v119, v26, v27
	s_nop 0
	v_cvt_pk_bf16_f32 v118, v32, v33
	s_waitcnt vmcnt(12)
	v_mov_b32_e32 v0, v180
	v_mov_b32_e32 v1, v181
	v_mov_b32_e32 v2, v182
	v_mov_b32_e32 v3, v183
	v_lshlrev_b32_e32 v34, 16, v0
	v_and_b32_e32 v35, 0xffff0000, v0
	v_lshlrev_b32_e32 v0, 16, v1
	v_and_b32_e32 v1, 0xffff0000, v1
	v_lshlrev_b32_e32 v40, 16, v2
	v_and_b32_e32 v41, 0xffff0000, v2
	v_lshlrev_b32_e32 v2, 16, v3
	v_and_b32_e32 v3, 0xffff0000, v3
	v_pk_mul_f32 v[36:37], v[34:35], v[34:35]
	v_pk_mul_f32 v[38:39], v[0:1], v[0:1]
	v_pk_mul_f32 v[42:43], v[40:41], v[40:41]
	v_pk_mul_f32 v[44:45], v[2:3], v[2:3]
	v_pk_fma_f32 v[36:37], v[36:37], s[42:43], 1.0 op_sel_hi:[1,0,0]
	v_pk_fma_f32 v[38:39], v[38:39], s[42:43], 1.0 op_sel_hi:[1,0,0]
	v_pk_fma_f32 v[42:43], v[42:43], s[42:43], 1.0 op_sel_hi:[1,0,0]
	v_pk_fma_f32 v[44:45], v[44:45], s[42:43], 1.0 op_sel_hi:[1,0,0]
	v_pk_mul_f32 v[36:37], v[36:37], v[34:35]
	v_pk_mul_f32 v[38:39], v[38:39], v[0:1]
	v_pk_mul_f32 v[42:43], v[42:43], v[40:41]
	v_pk_mul_f32 v[44:45], v[44:45], v[2:3]
	v_pk_mul_f32 v[36:37], v[36:37], s[10:11] op_sel_hi:[1,0]
	v_pk_mul_f32 v[38:39], v[38:39], s[10:11] op_sel_hi:[1,0]
	v_pk_mul_f32 v[42:43], v[42:43], s[10:11] op_sel_hi:[1,0]
	v_pk_mul_f32 v[44:45], v[44:45], s[10:11] op_sel_hi:[1,0]
	v_exp_f32_e32 v36, v36
	v_exp_f32_e32 v37, v37
	v_exp_f32_e32 v38, v38
	v_exp_f32_e32 v39, v39
	v_exp_f32_e32 v42, v42
	v_exp_f32_e32 v43, v43
	v_exp_f32_e32 v44, v44
	v_exp_f32_e32 v45, v45
	v_pk_add_f32 v[36:37], v[36:37], 1.0 op_sel_hi:[1,0]
	v_pk_add_f32 v[38:39], v[38:39], 1.0 op_sel_hi:[1,0]
	v_pk_add_f32 v[42:43], v[42:43], 1.0 op_sel_hi:[1,0]
	v_pk_add_f32 v[44:45], v[44:45], 1.0 op_sel_hi:[1,0]
	v_rcp_f32_e32 v36, v36
	v_rcp_f32_e32 v37, v37
	v_rcp_f32_e32 v46, v38
	v_rcp_f32_e32 v47, v39
	v_rcp_f32_e32 v42, v42
	v_rcp_f32_e32 v43, v43
	v_rcp_f32_e32 v44, v44
	v_rcp_f32_e32 v45, v45
	v_pk_mul_f32 v[38:39], v[36:37], v[34:35]
	v_pk_mul_f32 v[36:37], v[46:47], v[0:1]
	v_pk_mul_f32 v[34:35], v[42:43], v[40:41]
	v_pk_mul_f32 v[40:41], v[44:45], v[2:3]
	v_cvt_pk_bf16_f32 v126, v38, v39
	v_cvt_pk_bf16_f32 v124, v36, v37
	v_cvt_pk_bf16_f32 v123, v34, v35
	v_pk_mul_f32 v[24:25], v[36:37], v[36:37]
	v_cvt_pk_bf16_f32 v121, v40, v41
	s_waitcnt vmcnt(11)
	v_mov_b32_e32 v0, v184
	v_mov_b32_e32 v1, v185
	v_mov_b32_e32 v2, v186
	v_mov_b32_e32 v3, v187
	v_lshlrev_b32_e32 v42, 16, v0
	v_and_b32_e32 v43, 0xffff0000, v0
	v_lshlrev_b32_e32 v0, 16, v1
	v_and_b32_e32 v1, 0xffff0000, v1
	v_lshlrev_b32_e32 v48, 16, v2
	v_and_b32_e32 v49, 0xffff0000, v2
	v_lshlrev_b32_e32 v2, 16, v3
	v_and_b32_e32 v3, 0xffff0000, v3
	v_pk_mul_f32 v[44:45], v[42:43], v[42:43]
	v_pk_mul_f32 v[46:47], v[0:1], v[0:1]
	v_pk_mul_f32 v[50:51], v[48:49], v[48:49]
	v_pk_mul_f32 v[52:53], v[2:3], v[2:3]
	v_pk_fma_f32 v[44:45], v[44:45], s[42:43], 1.0 op_sel_hi:[1,0,0]
	v_pk_fma_f32 v[46:47], v[46:47], s[42:43], 1.0 op_sel_hi:[1,0,0]
	v_pk_fma_f32 v[50:51], v[50:51], s[42:43], 1.0 op_sel_hi:[1,0,0]
	v_pk_fma_f32 v[52:53], v[52:53], s[42:43], 1.0 op_sel_hi:[1,0,0]
	v_pk_mul_f32 v[44:45], v[44:45], v[42:43]
	v_pk_mul_f32 v[46:47], v[46:47], v[0:1]
	v_pk_mul_f32 v[50:51], v[50:51], v[48:49]
	v_pk_mul_f32 v[52:53], v[52:53], v[2:3]
	v_pk_mul_f32 v[44:45], v[44:45], s[10:11] op_sel_hi:[1,0]
	v_pk_mul_f32 v[46:47], v[46:47], s[10:11] op_sel_hi:[1,0]
	v_pk_mul_f32 v[50:51], v[50:51], s[10:11] op_sel_hi:[1,0]
	v_pk_mul_f32 v[52:53], v[52:53], s[10:11] op_sel_hi:[1,0]
	v_exp_f32_e32 v44, v44
	v_exp_f32_e32 v45, v45
	v_exp_f32_e32 v46, v46
	v_exp_f32_e32 v47, v47
	v_exp_f32_e32 v50, v50
	v_exp_f32_e32 v51, v51
	v_exp_f32_e32 v52, v52
	v_exp_f32_e32 v53, v53
	v_pk_add_f32 v[44:45], v[44:45], 1.0 op_sel_hi:[1,0]
	v_pk_add_f32 v[46:47], v[46:47], 1.0 op_sel_hi:[1,0]
	v_pk_add_f32 v[50:51], v[50:51], 1.0 op_sel_hi:[1,0]
	v_pk_add_f32 v[52:53], v[52:53], 1.0 op_sel_hi:[1,0]
	v_rcp_f32_e32 v44, v44
	v_rcp_f32_e32 v45, v45
	v_rcp_f32_e32 v54, v46
	v_rcp_f32_e32 v55, v47
	v_rcp_f32_e32 v50, v50
	v_rcp_f32_e32 v51, v51
	v_rcp_f32_e32 v52, v52
	v_rcp_f32_e32 v53, v53
	v_pk_mul_f32 v[46:47], v[44:45], v[42:43]
	v_pk_mul_f32 v[44:45], v[54:55], v[0:1]
	v_pk_mul_f32 v[42:43], v[50:51], v[48:49]
	v_pk_mul_f32 v[48:49], v[52:53], v[2:3]
	v_cvt_pk_bf16_f32 v129, v46, v47
	v_cvt_pk_bf16_f32 v128, v44, v45
	v_cvt_pk_bf16_f32 v127, v42, v43
	s_nop 0
	v_cvt_pk_bf16_f32 v125, v48, v49
	s_waitcnt vmcnt(10)
	v_mov_b32_e32 v0, v188
	v_mov_b32_e32 v1, v189
	v_mov_b32_e32 v2, v190
	v_mov_b32_e32 v3, v191
	v_lshlrev_b32_e32 v50, 16, v0
	v_and_b32_e32 v51, 0xffff0000, v0
	v_lshlrev_b32_e32 v0, 16, v1
	v_and_b32_e32 v1, 0xffff0000, v1
	v_lshlrev_b32_e32 v56, 16, v2
	v_and_b32_e32 v57, 0xffff0000, v2
	v_lshlrev_b32_e32 v2, 16, v3
	v_and_b32_e32 v3, 0xffff0000, v3
	v_pk_mul_f32 v[52:53], v[50:51], v[50:51]
	v_pk_mul_f32 v[54:55], v[0:1], v[0:1]
	v_pk_mul_f32 v[58:59], v[56:57], v[56:57]
	v_pk_mul_f32 v[60:61], v[2:3], v[2:3]
	v_pk_fma_f32 v[52:53], v[52:53], s[42:43], 1.0 op_sel_hi:[1,0,0]
	v_pk_fma_f32 v[54:55], v[54:55], s[42:43], 1.0 op_sel_hi:[1,0,0]
	v_pk_fma_f32 v[58:59], v[58:59], s[42:43], 1.0 op_sel_hi:[1,0,0]
	v_pk_fma_f32 v[60:61], v[60:61], s[42:43], 1.0 op_sel_hi:[1,0,0]
	v_pk_mul_f32 v[52:53], v[52:53], v[50:51]
	v_pk_mul_f32 v[54:55], v[54:55], v[0:1]
	v_pk_mul_f32 v[58:59], v[58:59], v[56:57]
	v_pk_mul_f32 v[60:61], v[60:61], v[2:3]
	v_pk_mul_f32 v[52:53], v[52:53], s[10:11] op_sel_hi:[1,0]
	v_pk_mul_f32 v[54:55], v[54:55], s[10:11] op_sel_hi:[1,0]
	v_pk_mul_f32 v[58:59], v[58:59], s[10:11] op_sel_hi:[1,0]
	v_pk_mul_f32 v[60:61], v[60:61], s[10:11] op_sel_hi:[1,0]
	v_exp_f32_e32 v52, v52
	v_exp_f32_e32 v53, v53
	v_exp_f32_e32 v54, v54
	v_exp_f32_e32 v55, v55
	v_exp_f32_e32 v58, v58
	v_exp_f32_e32 v59, v59
	v_exp_f32_e32 v60, v60
	v_exp_f32_e32 v61, v61
	v_pk_add_f32 v[52:53], v[52:53], 1.0 op_sel_hi:[1,0]
	v_pk_add_f32 v[54:55], v[54:55], 1.0 op_sel_hi:[1,0]
	v_pk_add_f32 v[58:59], v[58:59], 1.0 op_sel_hi:[1,0]
	v_pk_add_f32 v[60:61], v[60:61], 1.0 op_sel_hi:[1,0]
	v_rcp_f32_e32 v52, v52
	v_rcp_f32_e32 v53, v53
	v_rcp_f32_e32 v62, v54
	v_rcp_f32_e32 v63, v55
	v_rcp_f32_e32 v58, v58
	v_rcp_f32_e32 v59, v59
	v_rcp_f32_e32 v60, v60
	v_rcp_f32_e32 v61, v61
	v_pk_mul_f32 v[54:55], v[52:53], v[50:51]
	v_pk_mul_f32 v[52:53], v[62:63], v[0:1]
	v_pk_mul_f32 v[50:51], v[58:59], v[56:57]
	v_pk_mul_f32 v[56:57], v[60:61], v[2:3]
	v_cvt_pk_bf16_f32 v134, v54, v55
	v_cvt_pk_bf16_f32 v132, v52, v53
	v_cvt_pk_bf16_f32 v131, v50, v51
	s_nop 0
	v_cvt_pk_bf16_f32 v130, v56, v57
	s_waitcnt vmcnt(9)
	v_mov_b32_e32 v0, v192
	v_mov_b32_e32 v1, v193
	v_mov_b32_e32 v2, v194
	v_mov_b32_e32 v3, v195
	v_lshlrev_b32_e32 v58, 16, v0
	v_and_b32_e32 v59, 0xffff0000, v0
	v_lshlrev_b32_e32 v0, 16, v1
	v_and_b32_e32 v1, 0xffff0000, v1
	v_lshlrev_b32_e32 v64, 16, v2
	v_and_b32_e32 v65, 0xffff0000, v2
	v_lshlrev_b32_e32 v2, 16, v3
	v_and_b32_e32 v3, 0xffff0000, v3
	v_pk_mul_f32 v[60:61], v[58:59], v[58:59]
	v_pk_mul_f32 v[62:63], v[0:1], v[0:1]
	v_pk_mul_f32 v[66:67], v[64:65], v[64:65]
	v_pk_mul_f32 v[68:69], v[2:3], v[2:3]
	v_pk_fma_f32 v[60:61], v[60:61], s[42:43], 1.0 op_sel_hi:[1,0,0]
	v_pk_fma_f32 v[62:63], v[62:63], s[42:43], 1.0 op_sel_hi:[1,0,0]
	v_pk_fma_f32 v[66:67], v[66:67], s[42:43], 1.0 op_sel_hi:[1,0,0]
	v_pk_fma_f32 v[68:69], v[68:69], s[42:43], 1.0 op_sel_hi:[1,0,0]
	v_pk_mul_f32 v[60:61], v[60:61], v[58:59]
	v_pk_mul_f32 v[62:63], v[62:63], v[0:1]
	v_pk_mul_f32 v[66:67], v[66:67], v[64:65]
	v_pk_mul_f32 v[68:69], v[68:69], v[2:3]
	v_pk_mul_f32 v[60:61], v[60:61], s[10:11] op_sel_hi:[1,0]
	v_pk_mul_f32 v[62:63], v[62:63], s[10:11] op_sel_hi:[1,0]
	v_pk_mul_f32 v[66:67], v[66:67], s[10:11] op_sel_hi:[1,0]
	v_pk_mul_f32 v[68:69], v[68:69], s[10:11] op_sel_hi:[1,0]
	v_exp_f32_e32 v60, v60
	v_exp_f32_e32 v61, v61
	v_exp_f32_e32 v62, v62
	v_exp_f32_e32 v63, v63
	v_exp_f32_e32 v66, v66
	v_exp_f32_e32 v67, v67
	v_exp_f32_e32 v68, v68
	v_exp_f32_e32 v69, v69
	v_pk_add_f32 v[60:61], v[60:61], 1.0 op_sel_hi:[1,0]
	v_pk_add_f32 v[62:63], v[62:63], 1.0 op_sel_hi:[1,0]
	v_pk_add_f32 v[66:67], v[66:67], 1.0 op_sel_hi:[1,0]
	v_pk_add_f32 v[68:69], v[68:69], 1.0 op_sel_hi:[1,0]
	v_rcp_f32_e32 v60, v60
	v_rcp_f32_e32 v61, v61
	v_rcp_f32_e32 v70, v62
	v_rcp_f32_e32 v71, v63
	v_rcp_f32_e32 v66, v66
	v_rcp_f32_e32 v67, v67
	v_rcp_f32_e32 v68, v68
	v_rcp_f32_e32 v69, v69
	v_pk_mul_f32 v[62:63], v[60:61], v[58:59]
	v_pk_mul_f32 v[60:61], v[70:71], v[0:1]
	v_pk_mul_f32 v[58:59], v[66:67], v[64:65]
	v_pk_mul_f32 v[64:65], v[68:69], v[2:3]
	v_cvt_pk_bf16_f32 v137, v62, v63
	v_cvt_pk_bf16_f32 v136, v60, v61
	v_cvt_pk_bf16_f32 v135, v58, v59
	s_nop 0
	v_cvt_pk_bf16_f32 v133, v64, v65
	s_waitcnt vmcnt(8)
	v_mov_b32_e32 v0, v196
	v_mov_b32_e32 v1, v197
	v_mov_b32_e32 v2, v198
	v_mov_b32_e32 v3, v199
	v_lshlrev_b32_e32 v66, 16, v0
	v_and_b32_e32 v67, 0xffff0000, v0
	v_lshlrev_b32_e32 v0, 16, v1
	v_and_b32_e32 v1, 0xffff0000, v1
	v_lshlrev_b32_e32 v72, 16, v2
	v_and_b32_e32 v73, 0xffff0000, v2
	v_lshlrev_b32_e32 v2, 16, v3
	v_and_b32_e32 v3, 0xffff0000, v3
	v_pk_mul_f32 v[68:69], v[66:67], v[66:67]
	v_pk_mul_f32 v[70:71], v[0:1], v[0:1]
	v_pk_mul_f32 v[74:75], v[72:73], v[72:73]
	v_pk_mul_f32 v[76:77], v[2:3], v[2:3]
	v_pk_fma_f32 v[68:69], v[68:69], s[42:43], 1.0 op_sel_hi:[1,0,0]
	v_pk_fma_f32 v[70:71], v[70:71], s[42:43], 1.0 op_sel_hi:[1,0,0]
	v_pk_fma_f32 v[74:75], v[74:75], s[42:43], 1.0 op_sel_hi:[1,0,0]
	v_pk_fma_f32 v[76:77], v[76:77], s[42:43], 1.0 op_sel_hi:[1,0,0]
	v_pk_mul_f32 v[68:69], v[68:69], v[66:67]
	v_pk_mul_f32 v[70:71], v[70:71], v[0:1]
	v_pk_mul_f32 v[74:75], v[74:75], v[72:73]
	v_pk_mul_f32 v[76:77], v[76:77], v[2:3]
	v_pk_mul_f32 v[68:69], v[68:69], s[10:11] op_sel_hi:[1,0]
	v_pk_mul_f32 v[70:71], v[70:71], s[10:11] op_sel_hi:[1,0]
	v_pk_mul_f32 v[74:75], v[74:75], s[10:11] op_sel_hi:[1,0]
	v_pk_mul_f32 v[76:77], v[76:77], s[10:11] op_sel_hi:[1,0]
	v_exp_f32_e32 v68, v68
	v_exp_f32_e32 v69, v69
	v_exp_f32_e32 v70, v70
	v_exp_f32_e32 v71, v71
	v_exp_f32_e32 v74, v74
	v_exp_f32_e32 v75, v75
	v_exp_f32_e32 v76, v76
	v_exp_f32_e32 v77, v77
	v_pk_add_f32 v[68:69], v[68:69], 1.0 op_sel_hi:[1,0]
	v_pk_add_f32 v[70:71], v[70:71], 1.0 op_sel_hi:[1,0]
	v_pk_add_f32 v[74:75], v[74:75], 1.0 op_sel_hi:[1,0]
	v_pk_add_f32 v[76:77], v[76:77], 1.0 op_sel_hi:[1,0]
	v_rcp_f32_e32 v68, v68
	v_rcp_f32_e32 v69, v69
	v_rcp_f32_e32 v78, v70
	v_rcp_f32_e32 v79, v71
	v_rcp_f32_e32 v74, v74
	v_rcp_f32_e32 v75, v75
	v_rcp_f32_e32 v76, v76
	v_rcp_f32_e32 v77, v77
	v_pk_mul_f32 v[70:71], v[68:69], v[66:67]
	v_pk_mul_f32 v[68:69], v[78:79], v[0:1]
	v_pk_mul_f32 v[66:67], v[74:75], v[72:73]
	v_pk_mul_f32 v[72:73], v[76:77], v[2:3]
	v_cvt_pk_bf16_f32 v142, v70, v71
	v_cvt_pk_bf16_f32 v140, v68, v69
	v_cvt_pk_bf16_f32 v139, v66, v67
	s_nop 0
	v_cvt_pk_bf16_f32 v138, v72, v73
	s_waitcnt vmcnt(7)
	v_mov_b32_e32 v0, v200
	v_mov_b32_e32 v1, v201
	v_mov_b32_e32 v2, v202
	v_mov_b32_e32 v3, v203
	v_lshlrev_b32_e32 v74, 16, v0
	v_and_b32_e32 v75, 0xffff0000, v0
	v_lshlrev_b32_e32 v0, 16, v1
	v_and_b32_e32 v1, 0xffff0000, v1
	v_lshlrev_b32_e32 v80, 16, v2
	v_and_b32_e32 v81, 0xffff0000, v2
	v_lshlrev_b32_e32 v2, 16, v3
	v_and_b32_e32 v3, 0xffff0000, v3
	v_pk_mul_f32 v[76:77], v[74:75], v[74:75]
	v_pk_mul_f32 v[78:79], v[0:1], v[0:1]
	v_pk_mul_f32 v[82:83], v[80:81], v[80:81]
	v_pk_mul_f32 v[84:85], v[2:3], v[2:3]
	v_pk_fma_f32 v[76:77], v[76:77], s[42:43], 1.0 op_sel_hi:[1,0,0]
	v_pk_fma_f32 v[78:79], v[78:79], s[42:43], 1.0 op_sel_hi:[1,0,0]
	v_pk_fma_f32 v[82:83], v[82:83], s[42:43], 1.0 op_sel_hi:[1,0,0]
	v_pk_fma_f32 v[84:85], v[84:85], s[42:43], 1.0 op_sel_hi:[1,0,0]
	v_pk_mul_f32 v[76:77], v[76:77], v[74:75]
	v_pk_mul_f32 v[78:79], v[78:79], v[0:1]
	v_pk_mul_f32 v[82:83], v[82:83], v[80:81]
	v_pk_mul_f32 v[84:85], v[84:85], v[2:3]
	v_pk_mul_f32 v[76:77], v[76:77], s[10:11] op_sel_hi:[1,0]
	v_pk_mul_f32 v[78:79], v[78:79], s[10:11] op_sel_hi:[1,0]
	v_pk_mul_f32 v[82:83], v[82:83], s[10:11] op_sel_hi:[1,0]
	v_pk_mul_f32 v[84:85], v[84:85], s[10:11] op_sel_hi:[1,0]
	v_exp_f32_e32 v76, v76
	v_exp_f32_e32 v77, v77
	v_exp_f32_e32 v78, v78
	v_exp_f32_e32 v79, v79
	v_exp_f32_e32 v82, v82
	v_exp_f32_e32 v83, v83
	v_exp_f32_e32 v84, v84
	v_exp_f32_e32 v85, v85
	v_pk_add_f32 v[76:77], v[76:77], 1.0 op_sel_hi:[1,0]
	v_pk_add_f32 v[78:79], v[78:79], 1.0 op_sel_hi:[1,0]
	v_pk_add_f32 v[82:83], v[82:83], 1.0 op_sel_hi:[1,0]
	v_pk_add_f32 v[84:85], v[84:85], 1.0 op_sel_hi:[1,0]
	v_rcp_f32_e32 v76, v76
	v_rcp_f32_e32 v77, v77
	v_rcp_f32_e32 v86, v78
	v_rcp_f32_e32 v87, v79
	v_rcp_f32_e32 v82, v82
	v_rcp_f32_e32 v83, v83
	v_rcp_f32_e32 v84, v84
	v_rcp_f32_e32 v85, v85
	v_pk_mul_f32 v[78:79], v[76:77], v[74:75]
	v_pk_mul_f32 v[76:77], v[86:87], v[0:1]
	v_pk_mul_f32 v[74:75], v[82:83], v[80:81]
	v_pk_mul_f32 v[80:81], v[84:85], v[2:3]
	v_cvt_pk_bf16_f32 v146, v78, v79
	v_cvt_pk_bf16_f32 v144, v76, v77
	v_cvt_pk_bf16_f32 v143, v74, v75
	s_nop 0
	v_cvt_pk_bf16_f32 v141, v80, v81
	s_waitcnt vmcnt(6)
	v_mov_b32_e32 v0, v204
	v_mov_b32_e32 v1, v205
	v_mov_b32_e32 v2, v206
	v_mov_b32_e32 v3, v207
	v_lshlrev_b32_e32 v82, 16, v0
	v_and_b32_e32 v83, 0xffff0000, v0
	v_lshlrev_b32_e32 v0, 16, v1
	v_and_b32_e32 v1, 0xffff0000, v1
	v_lshlrev_b32_e32 v84, 16, v2
	v_and_b32_e32 v85, 0xffff0000, v2
	v_lshlrev_b32_e32 v2, 16, v3
	v_and_b32_e32 v3, 0xffff0000, v3
	v_pk_mul_f32 v[86:87], v[82:83], v[82:83]
	v_pk_mul_f32 v[88:89], v[0:1], v[0:1]
	v_pk_mul_f32 v[90:91], v[84:85], v[84:85]
	v_pk_mul_f32 v[92:93], v[2:3], v[2:3]
	v_pk_fma_f32 v[86:87], v[86:87], s[42:43], 1.0 op_sel_hi:[1,0,0]
	v_pk_fma_f32 v[88:89], v[88:89], s[42:43], 1.0 op_sel_hi:[1,0,0]
	v_pk_fma_f32 v[90:91], v[90:91], s[42:43], 1.0 op_sel_hi:[1,0,0]
	v_pk_fma_f32 v[92:93], v[92:93], s[42:43], 1.0 op_sel_hi:[1,0,0]
	v_pk_mul_f32 v[86:87], v[86:87], v[82:83]
	v_pk_mul_f32 v[88:89], v[88:89], v[0:1]
	v_pk_mul_f32 v[90:91], v[90:91], v[84:85]
	v_pk_mul_f32 v[92:93], v[92:93], v[2:3]
	v_pk_mul_f32 v[86:87], v[86:87], s[10:11] op_sel_hi:[1,0]
	v_pk_mul_f32 v[88:89], v[88:89], s[10:11] op_sel_hi:[1,0]
	v_pk_mul_f32 v[90:91], v[90:91], s[10:11] op_sel_hi:[1,0]
	v_pk_mul_f32 v[92:93], v[92:93], s[10:11] op_sel_hi:[1,0]
	v_exp_f32_e32 v86, v86
	v_exp_f32_e32 v87, v87
	v_exp_f32_e32 v88, v88
	v_exp_f32_e32 v89, v89
	v_exp_f32_e32 v90, v90
	v_exp_f32_e32 v91, v91
	v_exp_f32_e32 v92, v92
	v_exp_f32_e32 v93, v93
	v_pk_add_f32 v[86:87], v[86:87], 1.0 op_sel_hi:[1,0]
	v_pk_add_f32 v[88:89], v[88:89], 1.0 op_sel_hi:[1,0]
	v_pk_add_f32 v[90:91], v[90:91], 1.0 op_sel_hi:[1,0]
	v_pk_add_f32 v[92:93], v[92:93], 1.0 op_sel_hi:[1,0]
	v_rcp_f32_e32 v86, v86
	v_rcp_f32_e32 v87, v87
	v_rcp_f32_e32 v88, v88
	v_rcp_f32_e32 v89, v89
	v_rcp_f32_e32 v94, v90
	v_rcp_f32_e32 v95, v91
	v_rcp_f32_e32 v92, v92
	v_rcp_f32_e32 v93, v93
	v_pk_mul_f32 v[90:91], v[86:87], v[82:83]
	v_pk_mul_f32 v[86:87], v[88:89], v[0:1]
	v_pk_mul_f32 v[84:85], v[94:95], v[84:85]
	v_pk_mul_f32 v[82:83], v[92:93], v[2:3]
	v_cvt_pk_bf16_f32 v149, v90, v91
	v_cvt_pk_bf16_f32 v148, v86, v87
	v_cvt_pk_bf16_f32 v147, v84, v85
	s_nop 0
	v_cvt_pk_bf16_f32 v145, v82, v83
	s_waitcnt vmcnt(5)
	v_mov_b32_e32 v0, v208
	v_mov_b32_e32 v1, v209
	v_mov_b32_e32 v2, v210
	v_mov_b32_e32 v3, v211
	v_lshlrev_b32_e32 v88, 16, v0
	v_and_b32_e32 v89, 0xffff0000, v0
	v_lshlrev_b32_e32 v0, 16, v1
	v_and_b32_e32 v1, 0xffff0000, v1
	v_lshlrev_b32_e32 v92, 16, v2
	v_and_b32_e32 v93, 0xffff0000, v2
	v_lshlrev_b32_e32 v2, 16, v3
	v_and_b32_e32 v3, 0xffff0000, v3
	v_pk_mul_f32 v[94:95], v[88:89], v[88:89]
	v_pk_mul_f32 v[96:97], v[0:1], v[0:1]
	v_pk_mul_f32 v[98:99], v[92:93], v[92:93]
	v_pk_mul_f32 v[100:101], v[2:3], v[2:3]
	v_pk_fma_f32 v[94:95], v[94:95], s[42:43], 1.0 op_sel_hi:[1,0,0]
	v_pk_fma_f32 v[96:97], v[96:97], s[42:43], 1.0 op_sel_hi:[1,0,0]
	v_pk_fma_f32 v[98:99], v[98:99], s[42:43], 1.0 op_sel_hi:[1,0,0]
	v_pk_fma_f32 v[100:101], v[100:101], s[42:43], 1.0 op_sel_hi:[1,0,0]
	v_pk_mul_f32 v[94:95], v[94:95], v[88:89]
	v_pk_mul_f32 v[96:97], v[96:97], v[0:1]
	v_pk_mul_f32 v[98:99], v[98:99], v[92:93]
	v_pk_mul_f32 v[100:101], v[100:101], v[2:3]
	v_pk_mul_f32 v[94:95], v[94:95], s[10:11] op_sel_hi:[1,0]
	v_pk_mul_f32 v[96:97], v[96:97], s[10:11] op_sel_hi:[1,0]
	v_pk_mul_f32 v[98:99], v[98:99], s[10:11] op_sel_hi:[1,0]
	v_pk_mul_f32 v[100:101], v[100:101], s[10:11] op_sel_hi:[1,0]
	v_exp_f32_e32 v94, v94
	v_exp_f32_e32 v95, v95
	v_exp_f32_e32 v96, v96
	v_exp_f32_e32 v97, v97
	v_exp_f32_e32 v98, v98
	v_exp_f32_e32 v99, v99
	v_exp_f32_e32 v100, v100
	v_exp_f32_e32 v101, v101
	v_pk_add_f32 v[94:95], v[94:95], 1.0 op_sel_hi:[1,0]
	v_pk_add_f32 v[96:97], v[96:97], 1.0 op_sel_hi:[1,0]
	v_pk_add_f32 v[98:99], v[98:99], 1.0 op_sel_hi:[1,0]
	v_pk_add_f32 v[100:101], v[100:101], 1.0 op_sel_hi:[1,0]
	v_rcp_f32_e32 v94, v94
	v_rcp_f32_e32 v95, v95
	v_rcp_f32_e32 v102, v96
	v_rcp_f32_e32 v103, v97
	v_rcp_f32_e32 v98, v98
	v_rcp_f32_e32 v99, v99
	v_rcp_f32_e32 v100, v100
	v_rcp_f32_e32 v101, v101
	v_pk_mul_f32 v[96:97], v[94:95], v[88:89]
	v_pk_mul_f32 v[94:95], v[102:103], v[0:1]
	v_pk_mul_f32 v[92:93], v[98:99], v[92:93]
	v_pk_mul_f32 v[98:99], v[100:101], v[2:3]
	v_cvt_pk_bf16_f32 v154, v96, v97
	v_cvt_pk_bf16_f32 v152, v94, v95
	v_cvt_pk_bf16_f32 v151, v92, v93
	v_mov_b32_e32 v89, 0
	v_cvt_pk_bf16_f32 v150, v98, v99
	v_mov_b32_e32 v88, v17
	v_pk_add_f32 v[6:7], v[6:7], v[88:89]
	v_mov_b32_e32 v17, v22
	v_pk_add_f32 v[6:7], v[10:11], v[6:7]
	v_pk_mul_f32 v[10:11], v[20:21], v[20:21]
	s_waitcnt vmcnt(4)
	v_mov_b32_e32 v0, v212
	v_mov_b32_e32 v1, v213
	v_mov_b32_e32 v2, v214
	v_mov_b32_e32 v3, v215
	v_lshlrev_b32_e32 v100, 16, v0
	v_and_b32_e32 v101, 0xffff0000, v0
	v_lshlrev_b32_e32 v0, 16, v1
	v_and_b32_e32 v1, 0xffff0000, v1
	v_lshlrev_b32_e32 v106, 16, v2
	v_and_b32_e32 v107, 0xffff0000, v2
	v_lshlrev_b32_e32 v2, 16, v3
	v_and_b32_e32 v3, 0xffff0000, v3
	v_pk_mul_f32 v[102:103], v[100:101], v[100:101]
	v_pk_mul_f32 v[104:105], v[0:1], v[0:1]
	v_pk_mul_f32 v[156:157], v[106:107], v[106:107]
	v_pk_mul_f32 v[158:159], v[2:3], v[2:3]
	v_pk_fma_f32 v[102:103], v[102:103], s[42:43], 1.0 op_sel_hi:[1,0,0]
	v_pk_fma_f32 v[104:105], v[104:105], s[42:43], 1.0 op_sel_hi:[1,0,0]
	v_pk_fma_f32 v[156:157], v[156:157], s[42:43], 1.0 op_sel_hi:[1,0,0]
	v_pk_fma_f32 v[158:159], v[158:159], s[42:43], 1.0 op_sel_hi:[1,0,0]
	v_pk_mul_f32 v[102:103], v[102:103], v[100:101]
	v_pk_mul_f32 v[104:105], v[104:105], v[0:1]
	v_pk_mul_f32 v[156:157], v[156:157], v[106:107]
	v_pk_mul_f32 v[158:159], v[158:159], v[2:3]
	v_pk_mul_f32 v[102:103], v[102:103], s[10:11] op_sel_hi:[1,0]
	v_pk_mul_f32 v[104:105], v[104:105], s[10:11] op_sel_hi:[1,0]
	v_pk_mul_f32 v[156:157], v[156:157], s[10:11] op_sel_hi:[1,0]
	v_pk_mul_f32 v[158:159], v[158:159], s[10:11] op_sel_hi:[1,0]
	v_exp_f32_e32 v102, v102
	v_exp_f32_e32 v103, v103
	v_exp_f32_e32 v104, v104
	v_exp_f32_e32 v105, v105
	v_exp_f32_e32 v156, v156
	v_exp_f32_e32 v157, v157
	v_exp_f32_e32 v158, v158
	v_exp_f32_e32 v159, v159
	v_pk_add_f32 v[102:103], v[102:103], 1.0 op_sel_hi:[1,0]
	v_pk_add_f32 v[104:105], v[104:105], 1.0 op_sel_hi:[1,0]
	v_pk_add_f32 v[156:157], v[156:157], 1.0 op_sel_hi:[1,0]
	v_pk_add_f32 v[158:159], v[158:159], 1.0 op_sel_hi:[1,0]
	v_rcp_f32_e32 v102, v102
	v_rcp_f32_e32 v103, v103
	v_rcp_f32_e32 v160, v104
	v_rcp_f32_e32 v161, v105
	v_rcp_f32_e32 v156, v156
	v_rcp_f32_e32 v157, v157
	v_rcp_f32_e32 v158, v158
	v_rcp_f32_e32 v159, v159
	v_pk_mul_f32 v[104:105], v[102:103], v[100:101]
	v_pk_mul_f32 v[102:103], v[160:161], v[0:1]
	v_pk_mul_f32 v[100:101], v[156:157], v[106:107]
	v_pk_mul_f32 v[106:107], v[158:159], v[2:3]
	v_cvt_pk_bf16_f32 v157, v104, v105
	v_cvt_pk_bf16_f32 v156, v102, v103
	v_cvt_pk_bf16_f32 v155, v100, v101
	v_pk_mul_f32 v[160:161], v[8:9], v[8:9]
	v_cvt_pk_bf16_f32 v153, v106, v107
	v_mov_b32_e32 v166, v160
	v_mov_b32_e32 v8, v161
	v_pk_add_f32 v[8:9], v[166:167], v[8:9]
	v_mov_b32_e32 v161, v20
	v_pk_add_f32 v[6:7], v[8:9], v[6:7]
	v_pk_mul_f32 v[8:9], v[22:23], v[22:23]
	v_pk_add_f32 v[6:7], v[12:13], v[6:7]
	v_mov_b32_e32 v16, v8
	v_mov_b32_e32 v22, v9
	v_pk_mul_f32 v[12:13], v[18:19], v[18:19]
	v_mov_b32_e32 v160, v10
	v_mov_b32_e32 v20, v11
	v_pk_add_f32 v[8:9], v[16:17], v[22:23]
	v_mov_b32_e32 v162, v12
	v_mov_b32_e32 v18, v13
	v_pk_add_f32 v[10:11], v[160:161], v[20:21]
	v_pk_add_f32 v[6:7], v[6:7], v[8:9]
	v_pk_add_f32 v[12:13], v[162:163], v[18:19]
	v_pk_add_f32 v[6:7], v[10:11], v[6:7]
	v_pk_mul_f32 v[8:9], v[30:31], v[30:31]
	v_pk_add_f32 v[6:7], v[12:13], v[6:7]
	v_mov_b32_e32 v11, v30
	v_pk_mul_f32 v[12:13], v[28:29], v[28:29]
	v_mov_b32_e32 v10, v8
	v_mov_b32_e32 v30, v9
	v_pk_add_f32 v[6:7], v[14:15], v[6:7]
	v_mov_b32_e32 v15, v28
	v_pk_mul_f32 v[16:17], v[26:27], v[26:27]
	v_mov_b32_e32 v14, v12
	v_mov_b32_e32 v28, v13
	v_pk_add_f32 v[8:9], v[10:11], v[30:31]
	v_pk_mul_f32 v[18:19], v[32:33], v[32:33]
	v_mov_b32_e32 v21, v26
	v_mov_b32_e32 v20, v16
	v_mov_b32_e32 v26, v17
	v_pk_add_f32 v[10:11], v[14:15], v[28:29]
	v_pk_add_f32 v[6:7], v[6:7], v[8:9]
	v_mov_b32_e32 v23, v32
	v_mov_b32_e32 v22, v18
	v_mov_b32_e32 v32, v19
	v_pk_add_f32 v[12:13], v[20:21], v[26:27]
	v_pk_add_f32 v[6:7], v[10:11], v[6:7]
	v_pk_add_f32 v[14:15], v[22:23], v[32:33]
	v_pk_add_f32 v[6:7], v[12:13], v[6:7]
	v_pk_mul_f32 v[16:17], v[38:39], v[38:39]
	v_pk_add_f32 v[14:15], v[14:15], v[6:7]
	v_mov_b32_e32 v31, v38
	v_mov_b32_e32 v30, v16
	v_mov_b32_e32 v38, v17
	v_pk_mul_f32 v[26:27], v[34:35], v[34:35]
	v_mov_b32_e32 v33, v36
	v_mov_b32_e32 v32, v24
	v_mov_b32_e32 v36, v25
	v_pk_add_f32 v[16:17], v[30:31], v[38:39]
	v_pk_mul_f32 v[28:29], v[40:41], v[40:41]
	v_mov_b32_e32 v161, v34
	v_mov_b32_e32 v160, v26
	v_mov_b32_e32 v34, v27
	v_pk_add_f32 v[24:25], v[32:33], v[36:37]
	v_pk_add_f32 v[14:15], v[14:15], v[16:17]
	v_mov_b32_e32 v163, v40
	v_mov_b32_e32 v162, v28
	v_mov_b32_e32 v40, v29
	v_pk_add_f32 v[26:27], v[160:161], v[34:35]
	v_pk_add_f32 v[14:15], v[24:25], v[14:15]
	v_pk_mul_f32 v[16:17], v[46:47], v[46:47]
	v_pk_add_f32 v[28:29], v[162:163], v[40:41]
	v_pk_add_f32 v[14:15], v[26:27], v[14:15]
	v_pk_mul_f32 v[24:25], v[44:45], v[44:45]
	v_mov_b32_e32 v31, v46
	v_mov_b32_e32 v30, v16
	v_mov_b32_e32 v46, v17
	v_pk_add_f32 v[14:15], v[28:29], v[14:15]
	v_pk_mul_f32 v[26:27], v[42:43], v[42:43]
	v_mov_b32_e32 v33, v44
	v_mov_b32_e32 v32, v24
	v_mov_b32_e32 v44, v25
	v_pk_add_f32 v[16:17], v[30:31], v[46:47]
	v_pk_mul_f32 v[28:29], v[48:49], v[48:49]
	s_waitcnt vmcnt(3)
	v_mov_b32_e32 v0, v216
	v_mov_b32_e32 v1, v217
	v_mov_b32_e32 v2, v218
	v_mov_b32_e32 v3, v219
	v_lshlrev_b32_e32 v6, 16, v0
	v_and_b32_e32 v7, 0xffff0000, v0
	v_lshlrev_b32_e32 v0, 16, v1
	v_and_b32_e32 v1, 0xffff0000, v1
	v_lshlrev_b32_e32 v10, 16, v2
	v_and_b32_e32 v11, 0xffff0000, v2
	v_lshlrev_b32_e32 v12, 16, v3
	v_and_b32_e32 v13, 0xffff0000, v3
	v_pk_mul_f32 v[2:3], v[6:7], v[6:7]
	v_pk_mul_f32 v[8:9], v[0:1], v[0:1]
	v_pk_mul_f32 v[18:19], v[10:11], v[10:11]
	v_pk_mul_f32 v[20:21], v[12:13], v[12:13]
	v_pk_fma_f32 v[2:3], v[2:3], s[42:43], 1.0 op_sel_hi:[1,0,0]
	v_pk_fma_f32 v[8:9], v[8:9], s[42:43], 1.0 op_sel_hi:[1,0,0]
	v_pk_fma_f32 v[18:19], v[18:19], s[42:43], 1.0 op_sel_hi:[1,0,0]
	v_pk_fma_f32 v[20:21], v[20:21], s[42:43], 1.0 op_sel_hi:[1,0,0]
	v_pk_mul_f32 v[2:3], v[2:3], v[6:7]
	v_pk_mul_f32 v[8:9], v[8:9], v[0:1]
	v_pk_mul_f32 v[18:19], v[18:19], v[10:11]
	v_pk_mul_f32 v[20:21], v[20:21], v[12:13]
	v_pk_mul_f32 v[2:3], v[2:3], s[10:11] op_sel_hi:[1,0]
	v_pk_mul_f32 v[8:9], v[8:9], s[10:11] op_sel_hi:[1,0]
	v_pk_mul_f32 v[18:19], v[18:19], s[10:11] op_sel_hi:[1,0]
	v_pk_mul_f32 v[20:21], v[20:21], s[10:11] op_sel_hi:[1,0]
	v_exp_f32_e32 v2, v2
	v_exp_f32_e32 v3, v3
	v_exp_f32_e32 v8, v8
	v_exp_f32_e32 v9, v9
	v_exp_f32_e32 v18, v18
	v_exp_f32_e32 v19, v19
	v_exp_f32_e32 v20, v20
	v_exp_f32_e32 v21, v21
	v_pk_add_f32 v[2:3], v[2:3], 1.0 op_sel_hi:[1,0]
	v_pk_add_f32 v[8:9], v[8:9], 1.0 op_sel_hi:[1,0]
	v_pk_add_f32 v[18:19], v[18:19], 1.0 op_sel_hi:[1,0]
	v_pk_add_f32 v[20:21], v[20:21], 1.0 op_sel_hi:[1,0]
	v_rcp_f32_e32 v2, v2
	v_rcp_f32_e32 v3, v3
	v_rcp_f32_e32 v22, v8
	v_rcp_f32_e32 v23, v9
	v_rcp_f32_e32 v18, v18
	v_rcp_f32_e32 v19, v19
	v_rcp_f32_e32 v20, v20
	v_rcp_f32_e32 v21, v21
	v_pk_mul_f32 v[8:9], v[2:3], v[6:7]
	v_pk_mul_f32 v[6:7], v[22:23], v[0:1]
	v_pk_mul_f32 v[2:3], v[18:19], v[10:11]
	v_pk_mul_f32 v[0:1], v[20:21], v[12:13]
	v_cvt_pk_bf16_f32 v22, v8, v9
	v_cvt_pk_bf16_f32 v20, v6, v7
	v_cvt_pk_bf16_f32 v19, v2, v3
	v_mov_b32_e32 v35, v42
	v_cvt_pk_bf16_f32 v18, v0, v1
	v_mov_b32_e32 v34, v26
	v_mov_b32_e32 v42, v27
	v_pk_add_f32 v[24:25], v[32:33], v[44:45]
	v_pk_add_f32 v[14:15], v[14:15], v[16:17]
	v_mov_b32_e32 v37, v48
	v_mov_b32_e32 v36, v28
	v_mov_b32_e32 v48, v29
	v_pk_add_f32 v[26:27], v[34:35], v[42:43]
	v_pk_add_f32 v[14:15], v[24:25], v[14:15]
	v_pk_mul_f32 v[16:17], v[54:55], v[54:55]
	v_pk_add_f32 v[28:29], v[36:37], v[48:49]
	v_pk_add_f32 v[14:15], v[26:27], v[14:15]
	v_mov_b32_e32 v25, v54
	v_pk_mul_f32 v[26:27], v[52:53], v[52:53]
	v_mov_b32_e32 v24, v16
	v_mov_b32_e32 v54, v17
	v_pk_add_f32 v[14:15], v[28:29], v[14:15]
	v_pk_mul_f32 v[28:29], v[50:51], v[50:51]
	v_mov_b32_e32 v33, v52
	v_mov_b32_e32 v32, v26
	v_mov_b32_e32 v52, v27
	v_pk_add_f32 v[16:17], v[24:25], v[54:55]
	v_pk_mul_f32 v[30:31], v[56:57], v[56:57]
	v_mov_b32_e32 v35, v50
	v_mov_b32_e32 v34, v28
	v_mov_b32_e32 v50, v29
	v_pk_add_f32 v[24:25], v[32:33], v[52:53]
	v_pk_add_f32 v[14:15], v[14:15], v[16:17]
	v_mov_b32_e32 v37, v56
	v_mov_b32_e32 v36, v30
	v_mov_b32_e32 v56, v31
	v_pk_add_f32 v[26:27], v[34:35], v[50:51]
	v_pk_add_f32 v[14:15], v[24:25], v[14:15]
	v_pk_add_f32 v[28:29], v[36:37], v[56:57]
	v_pk_add_f32 v[14:15], v[26:27], v[14:15]
	v_pk_mul_f32 v[16:17], v[60:61], v[60:61]
	v_pk_add_f32 v[32:33], v[28:29], v[14:15]
	v_pk_mul_f32 v[14:15], v[62:63], v[62:63]
	v_mov_b32_e32 v39, v62
	v_mov_b32_e32 v38, v14
	v_mov_b32_e32 v62, v15
	v_mov_b32_e32 v41, v60
	v_mov_b32_e32 v40, v16
	v_mov_b32_e32 v60, v17
	v_pk_mul_f32 v[34:35], v[58:59], v[58:59]
	v_pk_mul_f32 v[36:37], v[64:65], v[64:65]
	v_mov_b32_e32 v43, v58
	v_mov_b32_e32 v42, v34
	v_mov_b32_e32 v58, v35
	v_pk_add_f32 v[34:35], v[38:39], v[62:63]
	v_mov_b32_e32 v45, v64
	v_mov_b32_e32 v44, v36
	v_mov_b32_e32 v64, v37
	v_pk_add_f32 v[36:37], v[40:41], v[60:61]
	v_pk_add_f32 v[32:33], v[32:33], v[34:35]
	v_pk_add_f32 v[38:39], v[42:43], v[58:59]
	v_pk_add_f32 v[32:33], v[36:37], v[32:33]
	v_pk_add_f32 v[40:41], v[44:45], v[64:65]
	v_pk_add_f32 v[32:33], v[38:39], v[32:33]
	v_pk_mul_f32 v[34:35], v[70:71], v[70:71]
	v_pk_add_f32 v[32:33], v[40:41], v[32:33]
	v_pk_mul_f32 v[36:37], v[68:69], v[68:69]
	v_mov_b32_e32 v41, v70
	v_mov_b32_e32 v40, v34
	v_mov_b32_e32 v70, v35
	v_pk_mul_f32 v[38:39], v[66:67], v[66:67]
	v_mov_b32_e32 v43, v68
	v_mov_b32_e32 v42, v36
	v_mov_b32_e32 v68, v37
	v_pk_add_f32 v[34:35], v[40:41], v[70:71]
	v_mov_b32_e32 v45, v66
	v_mov_b32_e32 v44, v38
	v_mov_b32_e32 v66, v39
	v_pk_add_f32 v[36:37], v[42:43], v[68:69]
	v_pk_add_f32 v[32:33], v[32:33], v[34:35]
	v_mov_b32_e32 v49, v72
	v_pk_add_f32 v[38:39], v[44:45], v[66:67]
	v_pk_add_f32 v[32:33], v[36:37], v[32:33]
	v_pk_mul_f32 v[34:35], v[78:79], v[78:79]
	s_waitcnt vmcnt(2)
	v_mov_b32_e32 v10, v220
	v_mov_b32_e32 v11, v221
	v_mov_b32_e32 v12, v222
	v_mov_b32_e32 v13, v223
	v_lshlrev_b32_e32 v14, 16, v10
	v_and_b32_e32 v15, 0xffff0000, v10
	v_lshlrev_b32_e32 v10, 16, v11
	v_and_b32_e32 v11, 0xffff0000, v11
	v_lshlrev_b32_e32 v24, 16, v12
	v_and_b32_e32 v25, 0xffff0000, v12
	v_lshlrev_b32_e32 v26, 16, v13
	v_and_b32_e32 v27, 0xffff0000, v13
	v_pk_mul_f32 v[12:13], v[14:15], v[14:15]
	v_pk_mul_f32 v[16:17], v[10:11], v[10:11]
	v_pk_mul_f32 v[28:29], v[24:25], v[24:25]
	v_pk_mul_f32 v[30:31], v[26:27], v[26:27]
	v_pk_fma_f32 v[12:13], v[12:13], s[42:43], 1.0 op_sel_hi:[1,0,0]
	v_pk_fma_f32 v[16:17], v[16:17], s[42:43], 1.0 op_sel_hi:[1,0,0]
	v_pk_fma_f32 v[28:29], v[28:29], s[42:43], 1.0 op_sel_hi:[1,0,0]
	v_pk_fma_f32 v[30:31], v[30:31], s[42:43], 1.0 op_sel_hi:[1,0,0]
	v_pk_mul_f32 v[12:13], v[12:13], v[14:15]
	v_pk_mul_f32 v[16:17], v[16:17], v[10:11]
	v_pk_mul_f32 v[28:29], v[28:29], v[24:25]
	v_pk_mul_f32 v[30:31], v[30:31], v[26:27]
	v_pk_mul_f32 v[12:13], v[12:13], s[10:11] op_sel_hi:[1,0]
	v_pk_mul_f32 v[16:17], v[16:17], s[10:11] op_sel_hi:[1,0]
	v_pk_mul_f32 v[28:29], v[28:29], s[10:11] op_sel_hi:[1,0]
	v_pk_mul_f32 v[30:31], v[30:31], s[10:11] op_sel_hi:[1,0]
	v_exp_f32_e32 v12, v12
	v_exp_f32_e32 v13, v13
	v_exp_f32_e32 v16, v16
	v_exp_f32_e32 v17, v17
	v_exp_f32_e32 v28, v28
	v_exp_f32_e32 v29, v29
	v_exp_f32_e32 v30, v30
	v_exp_f32_e32 v31, v31
	v_pk_add_f32 v[12:13], v[12:13], 1.0 op_sel_hi:[1,0]
	v_pk_add_f32 v[16:17], v[16:17], 1.0 op_sel_hi:[1,0]
	v_pk_add_f32 v[28:29], v[28:29], 1.0 op_sel_hi:[1,0]
	v_pk_add_f32 v[30:31], v[30:31], 1.0 op_sel_hi:[1,0]
	v_rcp_f32_e32 v12, v12
	v_rcp_f32_e32 v13, v13
	v_rcp_f32_e32 v46, v16
	v_rcp_f32_e32 v47, v17
	v_rcp_f32_e32 v28, v28
	v_rcp_f32_e32 v29, v29
	v_rcp_f32_e32 v30, v30
	v_rcp_f32_e32 v31, v31
	v_pk_mul_f32 v[16:17], v[12:13], v[14:15]
	v_pk_mul_f32 v[14:15], v[46:47], v[10:11]
	v_pk_mul_f32 v[12:13], v[28:29], v[24:25]
	v_pk_mul_f32 v[10:11], v[30:31], v[26:27]
	v_cvt_pk_bf16_f32 v26, v16, v17
	v_cvt_pk_bf16_f32 v24, v14, v15
	v_cvt_pk_bf16_f32 v23, v12, v13
	v_pk_mul_f32 v[46:47], v[72:73], v[72:73]
	v_cvt_pk_bf16_f32 v21, v10, v11
	v_mov_b32_e32 v48, v46
	v_mov_b32_e32 v72, v47
	v_pk_add_f32 v[40:41], v[48:49], v[72:73]
	v_pk_add_f32 v[32:33], v[38:39], v[32:33]
	v_pk_mul_f32 v[36:37], v[76:77], v[76:77]
	v_mov_b32_e32 v43, v78
	v_mov_b32_e32 v42, v34
	v_mov_b32_e32 v78, v35
	v_pk_add_f32 v[32:33], v[40:41], v[32:33]
	v_pk_mul_f32 v[38:39], v[74:75], v[74:75]
	v_mov_b32_e32 v45, v76
	v_mov_b32_e32 v44, v36
	v_mov_b32_e32 v76, v37
	v_pk_add_f32 v[34:35], v[42:43], v[78:79]
	v_pk_mul_f32 v[40:41], v[80:81], v[80:81]
	v_mov_b32_e32 v47, v74
	v_mov_b32_e32 v46, v38
	v_mov_b32_e32 v74, v39
	v_pk_add_f32 v[36:37], v[44:45], v[76:77]
	v_pk_add_f32 v[32:33], v[32:33], v[34:35]
	v_mov_b32_e32 v49, v80
	v_mov_b32_e32 v48, v40
	v_mov_b32_e32 v80, v41
	v_pk_add_f32 v[38:39], v[46:47], v[74:75]
	v_pk_add_f32 v[32:33], v[36:37], v[32:33]
	v_pk_add_f32 v[40:41], v[48:49], v[80:81]
	v_pk_add_f32 v[32:33], v[38:39], v[32:33]
	v_pk_mul_f32 v[36:37], v[86:87], v[86:87]
	v_pk_add_f32 v[34:35], v[40:41], v[32:33]
	v_pk_mul_f32 v[32:33], v[90:91], v[90:91]
	v_pk_mul_f32 v[38:39], v[84:85], v[84:85]
	v_mov_b32_e32 v43, v90
	v_mov_b32_e32 v42, v32
	v_mov_b32_e32 v90, v33
	v_pk_mul_f32 v[40:41], v[82:83], v[82:83]
	v_mov_b32_e32 v45, v86
	v_mov_b32_e32 v47, v84
	v_mov_b32_e32 v44, v36
	v_mov_b32_e32 v86, v37
	v_mov_b32_e32 v46, v38
	v_mov_b32_e32 v84, v39
	v_pk_add_f32 v[36:37], v[42:43], v[90:91]
	v_mov_b32_e32 v49, v82
	v_mov_b32_e32 v48, v40
	v_mov_b32_e32 v82, v41
	v_pk_add_f32 v[38:39], v[44:45], v[86:87]
	v_pk_add_f32 v[40:41], v[46:47], v[84:85]
	v_pk_add_f32 v[34:35], v[34:35], v[36:37]
	v_pk_mul_f32 v[36:37], v[94:95], v[94:95]
	v_pk_add_f32 v[34:35], v[38:39], v[34:35]
	v_mov_b32_e32 v39, v96
	v_pk_add_f32 v[34:35], v[40:41], v[34:35]
	v_mov_b32_e32 v41, v94
	v_mov_b32_e32 v40, v36
	v_mov_b32_e32 v94, v37
	v_pk_mul_f32 v[54:55], v[98:99], v[98:99]
	v_pk_add_f32 v[36:37], v[40:41], v[94:95]
	v_mov_b32_e32 v57, v98
	v_mov_b32_e32 v56, v54
	v_mov_b32_e32 v98, v55
	v_pk_add_f32 v[40:41], v[56:57], v[98:99]
	v_mov_b32_e32 v55, v100
	v_mov_b32_e32 v57, v106
	v_mov_b32_e32 v158, s22
	v_pk_mul_f32 v[58:59], v[10:11], v[10:11]
	v_mov_b32_e32 v61, v12
	v_mov_b32_e32 v63, v10
	v_mov_b32_e32 v62, v58
	v_mov_b32_e32 v10, v59
	v_pk_add_f32 v[10:11], v[62:63], v[10:11]
	v_mov_b32_e32 v76, 0
	v_mov_b32_e32 v77, 0
	v_mov_b32_e32 v78, 0
	v_mov_b32_e32 v79, 0
	v_mov_b32_e32 v72, 0
	v_mov_b32_e32 v73, 0
	v_mov_b32_e32 v74, 0
	v_mov_b32_e32 v75, 0
	s_waitcnt vmcnt(1)
	v_mov_b32_e32 v28, v228
	v_mov_b32_e32 v29, v229
	v_mov_b32_e32 v30, v230
	v_mov_b32_e32 v31, v231
	v_lshlrev_b32_e32 v32, 16, v28
	v_and_b32_e32 v33, 0xffff0000, v28
	v_lshlrev_b32_e32 v28, 16, v29
	v_and_b32_e32 v29, 0xffff0000, v29
	v_lshlrev_b32_e32 v42, 16, v30
	v_and_b32_e32 v43, 0xffff0000, v30
	v_lshlrev_b32_e32 v30, 16, v31
	v_and_b32_e32 v31, 0xffff0000, v31
	v_pk_mul_f32 v[44:45], v[32:33], v[32:33]
	v_pk_mul_f32 v[46:47], v[28:29], v[28:29]
	v_pk_mul_f32 v[50:51], v[42:43], v[42:43]
	v_pk_mul_f32 v[52:53], v[30:31], v[30:31]
	v_pk_fma_f32 v[44:45], v[44:45], s[42:43], 1.0 op_sel_hi:[1,0,0]
	v_pk_fma_f32 v[46:47], v[46:47], s[42:43], 1.0 op_sel_hi:[1,0,0]
	v_pk_fma_f32 v[50:51], v[50:51], s[42:43], 1.0 op_sel_hi:[1,0,0]
	v_pk_fma_f32 v[52:53], v[52:53], s[42:43], 1.0 op_sel_hi:[1,0,0]
	v_pk_mul_f32 v[44:45], v[44:45], v[32:33]
	v_pk_mul_f32 v[46:47], v[46:47], v[28:29]
	v_pk_mul_f32 v[50:51], v[50:51], v[42:43]
	v_pk_mul_f32 v[52:53], v[52:53], v[30:31]
	v_pk_mul_f32 v[44:45], v[44:45], s[10:11] op_sel_hi:[1,0]
	v_pk_mul_f32 v[46:47], v[46:47], s[10:11] op_sel_hi:[1,0]
	v_pk_mul_f32 v[50:51], v[50:51], s[10:11] op_sel_hi:[1,0]
	v_pk_mul_f32 v[52:53], v[52:53], s[10:11] op_sel_hi:[1,0]
	v_exp_f32_e32 v44, v44
	v_exp_f32_e32 v45, v45
	v_exp_f32_e32 v46, v46
	v_exp_f32_e32 v47, v47
	v_exp_f32_e32 v50, v50
	v_exp_f32_e32 v51, v51
	v_exp_f32_e32 v52, v52
	v_exp_f32_e32 v53, v53
	v_pk_add_f32 v[44:45], v[44:45], 1.0 op_sel_hi:[1,0]
	v_pk_add_f32 v[46:47], v[46:47], 1.0 op_sel_hi:[1,0]
	v_pk_add_f32 v[50:51], v[50:51], 1.0 op_sel_hi:[1,0]
	v_pk_add_f32 v[52:53], v[52:53], 1.0 op_sel_hi:[1,0]
	v_rcp_f32_e32 v44, v44
	v_rcp_f32_e32 v45, v45
	v_rcp_f32_e32 v46, v46
	v_rcp_f32_e32 v47, v47
	v_rcp_f32_e32 v50, v50
	v_rcp_f32_e32 v51, v51
	v_rcp_f32_e32 v52, v52
	v_rcp_f32_e32 v53, v53
	v_pk_mul_f32 v[44:45], v[44:45], v[32:33]
	v_pk_mul_f32 v[46:47], v[46:47], v[28:29]
	v_pk_mul_f32 v[42:43], v[50:51], v[42:43]
	v_pk_mul_f32 v[50:51], v[52:53], v[30:31]
	v_cvt_pk_bf16_f32 v29, v44, v45
	v_cvt_pk_bf16_f32 v28, v46, v47
	v_cvt_pk_bf16_f32 v27, v42, v43
	v_mov_b32_e32 v53, v92
	v_cvt_pk_bf16_f32 v25, v50, v51
	v_pk_add_f32 v[4:5], v[48:49], v[82:83]
	v_pk_mul_f32 v[48:49], v[92:93], v[92:93]
	v_pk_add_f32 v[4:5], v[4:5], v[34:35]
	v_pk_mul_f32 v[34:35], v[96:97], v[96:97]
	v_mov_b32_e32 v52, v48
	v_mov_b32_e32 v38, v34
	v_mov_b32_e32 v96, v35
	v_pk_add_f32 v[34:35], v[38:39], v[96:97]
	v_mov_b32_e32 v92, v49
	v_pk_add_f32 v[4:5], v[4:5], v[34:35]
	v_pk_add_f32 v[38:39], v[52:53], v[92:93]
	v_pk_add_f32 v[4:5], v[36:37], v[4:5]
	v_pk_mul_f32 v[34:35], v[104:105], v[104:105]
	v_pk_add_f32 v[4:5], v[38:39], v[4:5]
	v_pk_mul_f32 v[36:37], v[102:103], v[102:103]
	v_mov_b32_e32 v49, v104
	v_mov_b32_e32 v48, v34
	v_mov_b32_e32 v104, v35
	v_pk_add_f32 v[4:5], v[40:41], v[4:5]
	v_pk_mul_f32 v[38:39], v[100:101], v[100:101]
	v_mov_b32_e32 v53, v102
	v_mov_b32_e32 v52, v36
	v_mov_b32_e32 v102, v37
	v_pk_add_f32 v[34:35], v[48:49], v[104:105]
	v_pk_mul_f32 v[40:41], v[106:107], v[106:107]
	v_mov_b32_e32 v54, v38
	v_mov_b32_e32 v100, v39
	v_pk_add_f32 v[36:37], v[52:53], v[102:103]
	v_pk_add_f32 v[4:5], v[4:5], v[34:35]
	v_mov_b32_e32 v56, v40
	v_mov_b32_e32 v106, v41
	v_pk_add_f32 v[38:39], v[54:55], v[100:101]
	v_pk_add_f32 v[4:5], v[36:37], v[4:5]
	v_pk_mul_f32 v[34:35], v[8:9], v[8:9]
	v_pk_add_f32 v[40:41], v[56:57], v[106:107]
	v_pk_add_f32 v[4:5], v[38:39], v[4:5]
	v_pk_mul_f32 v[36:37], v[6:7], v[6:7]
	v_mov_b32_e32 v49, v8
	v_mov_b32_e32 v48, v34
	v_mov_b32_e32 v8, v35
	v_pk_add_f32 v[4:5], v[40:41], v[4:5]
	v_pk_mul_f32 v[38:39], v[2:3], v[2:3]
	v_mov_b32_e32 v53, v6
	v_mov_b32_e32 v52, v36
	v_mov_b32_e32 v6, v37
	v_pk_add_f32 v[8:9], v[48:49], v[8:9]
	v_pk_mul_f32 v[40:41], v[0:1], v[0:1]
	v_mov_b32_e32 v55, v2
	v_mov_b32_e32 v54, v38
	v_mov_b32_e32 v2, v39
	v_pk_add_f32 v[6:7], v[52:53], v[6:7]
	v_pk_add_f32 v[4:5], v[4:5], v[8:9]
	v_mov_b32_e32 v57, v0
	v_mov_b32_e32 v56, v40
	v_mov_b32_e32 v0, v41
	v_pk_add_f32 v[2:3], v[54:55], v[2:3]
	v_pk_add_f32 v[4:5], v[6:7], v[4:5]
	v_pk_add_f32 v[0:1], v[56:57], v[0:1]
	v_pk_add_f32 v[2:3], v[2:3], v[4:5]
	v_pk_mul_f32 v[8:9], v[16:17], v[16:17]
	v_pk_add_f32 v[0:1], v[0:1], v[2:3]
	v_mov_b32_e32 v35, v16
	v_pk_mul_f32 v[52:53], v[14:15], v[14:15]
	v_mov_b32_e32 v34, v8
	v_mov_b32_e32 v16, v9
	v_mov_b32_e32 v55, v14
	v_pk_mul_f32 v[56:57], v[12:13], v[12:13]
	v_mov_b32_e32 v54, v52
	v_mov_b32_e32 v14, v53
	v_pk_add_f32 v[8:9], v[34:35], v[16:17]
	v_mov_b32_e32 v60, v56
	v_mov_b32_e32 v12, v57
	v_pk_add_f32 v[14:15], v[54:55], v[14:15]
	v_pk_add_f32 v[0:1], v[0:1], v[8:9]
	v_pk_add_f32 v[12:13], v[60:61], v[12:13]
	v_pk_add_f32 v[0:1], v[14:15], v[0:1]
	v_pk_mul_f32 v[8:9], v[44:45], v[44:45]
	v_pk_add_f32 v[0:1], v[12:13], v[0:1]
	v_mov_b32_e32 v17, v44
	s_waitcnt vmcnt(0)
	v_mov_b32_e32 v30, v232
	v_mov_b32_e32 v31, v233
	v_mov_b32_e32 v32, v234
	v_mov_b32_e32 v33, v235
	v_lshlrev_b32_e32 v2, 16, v30
	v_and_b32_e32 v3, 0xffff0000, v30
	v_lshlrev_b32_e32 v4, 16, v31
	v_and_b32_e32 v5, 0xffff0000, v31
	v_lshlrev_b32_e32 v6, 16, v32
	v_and_b32_e32 v7, 0xffff0000, v32
	v_lshlrev_b32_e32 v30, 16, v33
	v_and_b32_e32 v31, 0xffff0000, v33
	v_pk_mul_f32 v[32:33], v[2:3], v[2:3]
	v_pk_mul_f32 v[36:37], v[4:5], v[4:5]
	v_pk_mul_f32 v[38:39], v[6:7], v[6:7]
	v_pk_mul_f32 v[40:41], v[30:31], v[30:31]
	v_pk_fma_f32 v[32:33], v[32:33], s[42:43], 1.0 op_sel_hi:[1,0,0]
	v_pk_fma_f32 v[36:37], v[36:37], s[42:43], 1.0 op_sel_hi:[1,0,0]
	v_pk_fma_f32 v[38:39], v[38:39], s[42:43], 1.0 op_sel_hi:[1,0,0]
	v_pk_fma_f32 v[40:41], v[40:41], s[42:43], 1.0 op_sel_hi:[1,0,0]
	v_pk_mul_f32 v[32:33], v[32:33], v[2:3]
	v_pk_mul_f32 v[36:37], v[36:37], v[4:5]
	v_pk_mul_f32 v[38:39], v[38:39], v[6:7]
	v_pk_mul_f32 v[40:41], v[40:41], v[30:31]
	v_pk_mul_f32 v[32:33], v[32:33], s[10:11] op_sel_hi:[1,0]
	v_pk_mul_f32 v[36:37], v[36:37], s[10:11] op_sel_hi:[1,0]
	v_pk_mul_f32 v[38:39], v[38:39], s[10:11] op_sel_hi:[1,0]
	v_pk_mul_f32 v[40:41], v[40:41], s[10:11] op_sel_hi:[1,0]
	v_exp_f32_e32 v32, v32
	v_exp_f32_e32 v33, v33
	v_exp_f32_e32 v36, v36
	v_exp_f32_e32 v37, v37
	v_exp_f32_e32 v38, v38
	v_exp_f32_e32 v39, v39
	v_exp_f32_e32 v40, v40
	v_exp_f32_e32 v41, v41
	v_pk_add_f32 v[32:33], v[32:33], 1.0 op_sel_hi:[1,0]
	v_pk_add_f32 v[36:37], v[36:37], 1.0 op_sel_hi:[1,0]
	v_pk_add_f32 v[38:39], v[38:39], 1.0 op_sel_hi:[1,0]
	v_pk_add_f32 v[40:41], v[40:41], 1.0 op_sel_hi:[1,0]
	v_rcp_f32_e32 v32, v32
	v_rcp_f32_e32 v33, v33
	v_rcp_f32_e32 v36, v36
	v_rcp_f32_e32 v37, v37
	v_rcp_f32_e32 v38, v38
	v_rcp_f32_e32 v39, v39
	v_rcp_f32_e32 v40, v40
	v_rcp_f32_e32 v41, v41
	v_pk_mul_f32 v[32:33], v[32:33], v[2:3]
	v_pk_mul_f32 v[36:37], v[36:37], v[4:5]
	v_pk_mul_f32 v[38:39], v[38:39], v[6:7]
	v_pk_mul_f32 v[30:31], v[40:41], v[30:31]
	v_cvt_pk_bf16_f32 v6, v32, v33
	v_cvt_pk_bf16_f32 v5, v36, v37
	v_cvt_pk_bf16_f32 v4, v38, v39
	v_pk_add_f32 v[0:1], v[10:11], v[0:1]
	v_cvt_pk_bf16_f32 v3, v30, v31
	s_waitcnt lgkmcnt(0)
	global_load_dwordx2 v[172:173], v158, s[12:13] offset:2048
	global_load_dwordx2 v[174:175], v158, s[14:15] offset:2048
	global_load_dwordx2 v[176:177], v158, s[12:13] offset:2056
	global_load_dwordx2 v[178:179], v158, s[14:15] offset:2056
	global_load_dwordx2 v[180:181], v158, s[12:13] offset:2064
	global_load_dwordx2 v[182:183], v158, s[14:15] offset:2064
	global_load_dwordx2 v[184:185], v158, s[12:13] offset:2072
	global_load_dwordx2 v[186:187], v158, s[14:15] offset:2072
	global_load_dwordx2 v[188:189], v158, s[12:13] offset:2080
	global_load_dwordx2 v[190:191], v158, s[14:15] offset:2080
	global_load_dwordx2 v[192:193], v158, s[12:13] offset:2088
	global_load_dwordx2 v[194:195], v158, s[14:15] offset:2088
	global_load_dwordx2 v[196:197], v158, s[12:13] offset:2096
	global_load_dwordx2 v[198:199], v158, s[14:15] offset:2096
	global_load_dwordx2 v[200:201], v158, s[12:13] offset:2104
	global_load_dwordx2 v[202:203], v158, s[14:15] offset:2104
	global_load_dwordx2 v[204:205], v158, s[12:13] offset:2112
	global_load_dwordx2 v[206:207], v158, s[14:15] offset:2112
	global_load_dwordx2 v[208:209], v158, s[12:13] offset:2120
	global_load_dwordx2 v[210:211], v158, s[14:15] offset:2120
	global_load_dwordx2 v[212:213], v158, s[12:13] offset:2128
	global_load_dwordx2 v[214:215], v158, s[14:15] offset:2128
	global_load_dwordx2 v[216:217], v158, s[12:13] offset:2136
	global_load_dwordx2 v[218:219], v158, s[14:15] offset:2136
	global_load_dwordx2 v[220:221], v158, s[12:13] offset:2144
	global_load_dwordx2 v[222:223], v158, s[14:15] offset:2144
	global_load_dwordx2 v[228:229], v158, s[12:13] offset:2152
	global_load_dwordx2 v[230:231], v158, s[14:15] offset:2152
	global_load_dwordx2 v[232:233], v158, s[12:13] offset:2160
	global_load_dwordx2 v[234:235], v158, s[14:15] offset:2160
	global_load_dwordx2 v[236:237], v158, s[12:13] offset:2168
	global_load_dwordx2 v[238:239], v158, s[14:15] offset:2168
	v_pk_mul_f32 v[10:11], v[46:47], v[46:47]
	v_mov_b32_e32 v16, v8
	v_mov_b32_e32 v44, v9
	v_pk_mul_f32 v[12:13], v[42:43], v[42:43]
	v_mov_b32_e32 v35, v46
	v_mov_b32_e32 v34, v10
	v_mov_b32_e32 v46, v11
	v_pk_add_f32 v[8:9], v[16:17], v[44:45]
	v_pk_mul_f32 v[14:15], v[50:51], v[50:51]
	v_mov_b32_e32 v53, v42
	v_mov_b32_e32 v52, v12
	v_mov_b32_e32 v42, v13
	v_pk_add_f32 v[10:11], v[34:35], v[46:47]
	v_pk_add_f32 v[0:1], v[0:1], v[8:9]
	v_mov_b32_e32 v55, v50
	v_mov_b32_e32 v54, v14
	v_mov_b32_e32 v50, v15
	v_pk_add_f32 v[12:13], v[52:53], v[42:43]
	v_pk_add_f32 v[0:1], v[10:11], v[0:1]
	v_pk_mul_f32 v[8:9], v[32:33], v[32:33]
	v_pk_add_f32 v[14:15], v[54:55], v[50:51]
	v_pk_add_f32 v[0:1], v[12:13], v[0:1]
	v_pk_mul_f32 v[10:11], v[36:37], v[36:37]
	v_mov_b32_e32 v17, v32
	v_mov_b32_e32 v16, v8
	v_mov_b32_e32 v32, v9
	v_pk_add_f32 v[0:1], v[14:15], v[0:1]
	v_pk_mul_f32 v[12:13], v[38:39], v[38:39]
	v_mov_b32_e32 v35, v36
	v_mov_b32_e32 v34, v10
	v_mov_b32_e32 v36, v11
	v_pk_add_f32 v[8:9], v[16:17], v[32:33]
	v_pk_mul_f32 v[14:15], v[30:31], v[30:31]
	v_mov_b32_e32 v43, v38
	v_mov_b32_e32 v42, v12
	v_mov_b32_e32 v38, v13
	v_pk_add_f32 v[10:11], v[34:35], v[36:37]
	v_pk_add_f32 v[0:1], v[0:1], v[8:9]
	v_mov_b32_e32 v45, v30
	v_mov_b32_e32 v44, v14
	v_mov_b32_e32 v30, v15
	v_pk_add_f32 v[12:13], v[42:43], v[38:39]
	v_pk_add_f32 v[0:1], v[10:11], v[0:1]
	v_pk_add_f32 v[14:15], v[44:45], v[30:31]
	v_pk_add_f32 v[0:1], v[12:13], v[0:1]
	v_lshlrev_b32_e32 v8, 16, v114
	v_pk_add_f32 v[0:1], v[14:15], v[0:1]
	v_and_b32_e32 v9, 0xffff0000, v114
	v_pk_mul_f32 v[0:1], v[0:1], s[44:45] op_sel_hi:[1,0]
	v_lshlrev_b32_e32 v12, 16, v112
	v_fma_f32 v2, -v1, v1, v0
	v_max_f32_e32 v2, 0, v2
	v_add_f32_e32 v2, 0x3727c5ac, v2
	v_rsq_f32_e32 v2, v2
	v_pk_add_f32 v[8:9], v[8:9], v[0:1] op_sel:[0,1] neg_lo:[0,1] neg_hi:[0,1]
	v_and_b32_e32 v13, 0xffff0000, v112
	s_mul_i32 s45, s45, 0x8a00
	v_pk_mul_f32 v[8:9], v[8:9], v[2:3] op_sel_hi:[1,0]
	v_pk_add_f32 v[12:13], v[12:13], v[0:1] op_sel:[0,1] neg_lo:[0,1] neg_hi:[0,1]
	s_add_i32 s26, s45, 0
	v_pk_mul_f32 v[12:13], v[12:13], v[2:3] op_sel_hi:[1,0]
	v_lshl_add_u32 v7, v109, 1, s26
	s_bfe_u32 s10, s11, 0x10006
	v_and_b32_e32 v15, 0xffff0000, v3
	s_and_b32 s11, 64, s11
	s_cmp_eq_u32 s10, 0
	s_waitcnt vmcnt(30)
	v_pk_fma_f32 v[8:9], v[172:173], v[8:9], v[174:175]
	s_nop 0
	v_cvt_pk_bf16_f32 v14, v8, v9
	ds_write_b16 v7, v14
	ds_write_b16_d16_hi v7, v14 offset:272
	s_waitcnt vmcnt(28)
	v_pk_fma_f32 v[8:9], v[176:177], v[12:13], v[178:179]
	s_nop 0
	v_cvt_pk_bf16_f32 v14, v8, v9
	v_lshlrev_b32_e32 v12, 16, v111
	v_and_b32_e32 v13, 0xffff0000, v111
	v_pk_add_f32 v[12:13], v[12:13], v[0:1] op_sel:[0,1] neg_lo:[0,1] neg_hi:[0,1]
	ds_write_b16 v7, v14 offset:544
	ds_write_b16_d16_hi v7, v14 offset:816
	v_pk_mul_f32 v[12:13], v[12:13], v[2:3] op_sel_hi:[1,0]
	s_waitcnt vmcnt(26)
	v_pk_fma_f32 v[8:9], v[180:181], v[12:13], v[182:183]
	s_nop 0
	v_cvt_pk_bf16_f32 v14, v8, v9
	v_lshlrev_b32_e32 v12, 16, v110
	v_and_b32_e32 v13, 0xffff0000, v110
	v_pk_add_f32 v[12:13], v[12:13], v[0:1] op_sel:[0,1] neg_lo:[0,1] neg_hi:[0,1]
	ds_write_b16 v7, v14 offset:1088
	ds_write_b16_d16_hi v7, v14 offset:1360
	v_pk_mul_f32 v[12:13], v[12:13], v[2:3] op_sel_hi:[1,0]
	s_waitcnt vmcnt(24)
	v_pk_fma_f32 v[8:9], v[184:185], v[12:13], v[186:187]
	s_nop 0
	v_cvt_pk_bf16_f32 v14, v8, v9
	v_lshlrev_b32_e32 v12, 16, v117
	v_and_b32_e32 v13, 0xffff0000, v117
	v_pk_add_f32 v[12:13], v[12:13], v[0:1] op_sel:[0,1] neg_lo:[0,1] neg_hi:[0,1]
	ds_write_b16 v7, v14 offset:1632
	ds_write_b16_d16_hi v7, v14 offset:1904
	v_pk_mul_f32 v[12:13], v[12:13], v[2:3] op_sel_hi:[1,0]
	s_waitcnt vmcnt(22)
	v_pk_fma_f32 v[8:9], v[188:189], v[12:13], v[190:191]
	s_nop 0
	v_cvt_pk_bf16_f32 v14, v8, v9
	v_lshlrev_b32_e32 v12, 16, v116
	v_and_b32_e32 v13, 0xffff0000, v116
	v_pk_add_f32 v[12:13], v[12:13], v[0:1] op_sel:[0,1] neg_lo:[0,1] neg_hi:[0,1]
	ds_write_b16 v7, v14 offset:2176
	ds_write_b16_d16_hi v7, v14 offset:2448
	v_pk_mul_f32 v[12:13], v[12:13], v[2:3] op_sel_hi:[1,0]
	s_waitcnt vmcnt(20)
	v_pk_fma_f32 v[8:9], v[12:13], v[192:193], v[194:195]
	s_nop 0
	v_cvt_pk_bf16_f32 v14, v8, v9
	v_lshlrev_b32_e32 v12, 16, v115
	v_and_b32_e32 v13, 0xffff0000, v115
	v_pk_add_f32 v[12:13], v[12:13], v[0:1] op_sel:[0,1] neg_lo:[0,1] neg_hi:[0,1]
	ds_write_b16 v7, v14 offset:2720
	ds_write_b16_d16_hi v7, v14 offset:2992
	v_pk_mul_f32 v[12:13], v[12:13], v[2:3] op_sel_hi:[1,0]
	v_bfe_u32 v115, v108, 5, 1
	v_lshlrev_b32_e32 v88, 5, v115
	s_waitcnt vmcnt(18)
	v_pk_fma_f32 v[8:9], v[12:13], v[196:197], v[198:199]
	s_nop 0
	v_cvt_pk_bf16_f32 v14, v8, v9
	v_lshlrev_b32_e32 v12, 16, v113
	v_and_b32_e32 v13, 0xffff0000, v113
	v_pk_add_f32 v[12:13], v[12:13], v[0:1] op_sel:[0,1] neg_lo:[0,1] neg_hi:[0,1]
	ds_write_b16 v7, v14 offset:3264
	ds_write_b16_d16_hi v7, v14 offset:3536
	v_pk_mul_f32 v[12:13], v[12:13], v[2:3] op_sel_hi:[1,0]
	s_waitcnt vmcnt(16)
	v_pk_fma_f32 v[8:9], v[12:13], v[200:201], v[202:203]
	s_nop 0
	v_cvt_pk_bf16_f32 v14, v8, v9
	global_load_dwordx2 v[172:173], v158, s[12:13] offset:2176
	global_load_dwordx2 v[174:175], v158, s[14:15] offset:2176
	global_load_dwordx2 v[176:177], v158, s[12:13] offset:2184
	global_load_dwordx2 v[178:179], v158, s[14:15] offset:2184
	global_load_dwordx2 v[180:181], v158, s[12:13] offset:2192
	global_load_dwordx2 v[182:183], v158, s[14:15] offset:2192
	global_load_dwordx2 v[184:185], v158, s[12:13] offset:2200
	global_load_dwordx2 v[186:187], v158, s[14:15] offset:2200
	global_load_dwordx2 v[188:189], v158, s[12:13] offset:2208
	global_load_dwordx2 v[190:191], v158, s[14:15] offset:2208
	global_load_dwordx2 v[192:193], v158, s[12:13] offset:2216
	global_load_dwordx2 v[194:195], v158, s[14:15] offset:2216
	global_load_dwordx2 v[196:197], v158, s[12:13] offset:2224
	global_load_dwordx2 v[198:199], v158, s[14:15] offset:2224
	global_load_dwordx2 v[200:201], v158, s[12:13] offset:2232
	global_load_dwordx2 v[202:203], v158, s[14:15] offset:2232
	v_lshlrev_b32_e32 v12, 16, v122
	v_and_b32_e32 v13, 0xffff0000, v122
	v_pk_add_f32 v[12:13], v[12:13], v[0:1] op_sel:[0,1] neg_lo:[0,1] neg_hi:[0,1]
	ds_write_b16 v7, v14 offset:3808
	ds_write_b16_d16_hi v7, v14 offset:4080
	v_pk_mul_f32 v[12:13], v[12:13], v[2:3] op_sel_hi:[1,0]
	s_waitcnt vmcnt(30)
	v_pk_fma_f32 v[8:9], v[12:13], v[204:205], v[206:207]
	s_nop 0
	v_cvt_pk_bf16_f32 v14, v8, v9
	v_lshlrev_b32_e32 v12, 16, v120
	v_and_b32_e32 v13, 0xffff0000, v120
	v_pk_add_f32 v[12:13], v[12:13], v[0:1] op_sel:[0,1] neg_lo:[0,1] neg_hi:[0,1]
	ds_write_b16 v7, v14 offset:4352
	ds_write_b16_d16_hi v7, v14 offset:4624
	v_pk_mul_f32 v[12:13], v[12:13], v[2:3] op_sel_hi:[1,0]
	s_waitcnt vmcnt(28)
	v_pk_fma_f32 v[8:9], v[12:13], v[208:209], v[210:211]
	s_nop 0
	v_cvt_pk_bf16_f32 v14, v8, v9
	v_lshlrev_b32_e32 v12, 16, v119
	v_and_b32_e32 v13, 0xffff0000, v119
	v_pk_add_f32 v[12:13], v[12:13], v[0:1] op_sel:[0,1] neg_lo:[0,1] neg_hi:[0,1]
	ds_write_b16 v7, v14 offset:4896
	ds_write_b16_d16_hi v7, v14 offset:5168
	v_pk_mul_f32 v[12:13], v[12:13], v[2:3] op_sel_hi:[1,0]
	s_waitcnt vmcnt(26)
	v_pk_fma_f32 v[8:9], v[12:13], v[212:213], v[214:215]
	s_nop 0
	v_cvt_pk_bf16_f32 v14, v8, v9
	v_lshlrev_b32_e32 v12, 16, v118
	v_and_b32_e32 v13, 0xffff0000, v118
	v_pk_add_f32 v[12:13], v[12:13], v[0:1] op_sel:[0,1] neg_lo:[0,1] neg_hi:[0,1]
	ds_write_b16 v7, v14 offset:5440
	ds_write_b16_d16_hi v7, v14 offset:5712
	v_pk_mul_f32 v[12:13], v[12:13], v[2:3] op_sel_hi:[1,0]
	v_and_b32_e32 v118, 31, v108
	s_waitcnt vmcnt(24)
	v_pk_fma_f32 v[8:9], v[12:13], v[216:217], v[218:219]
	s_nop 0
	v_cvt_pk_bf16_f32 v14, v8, v9
	v_lshlrev_b32_e32 v12, 16, v126
	v_and_b32_e32 v13, 0xffff0000, v126
	v_pk_add_f32 v[12:13], v[12:13], v[0:1] op_sel:[0,1] neg_lo:[0,1] neg_hi:[0,1]
	ds_write_b16 v7, v14 offset:5984
	ds_write_b16_d16_hi v7, v14 offset:6256
	v_pk_mul_f32 v[12:13], v[12:13], v[2:3] op_sel_hi:[1,0]
	s_waitcnt vmcnt(22)
	v_pk_fma_f32 v[8:9], v[12:13], v[220:221], v[222:223]
	s_nop 0
	v_cvt_pk_bf16_f32 v14, v8, v9
	v_lshlrev_b32_e32 v12, 16, v124
	v_and_b32_e32 v13, 0xffff0000, v124
	v_pk_add_f32 v[12:13], v[12:13], v[0:1] op_sel:[0,1] neg_lo:[0,1] neg_hi:[0,1]
	ds_write_b16 v7, v14 offset:6528
	ds_write_b16_d16_hi v7, v14 offset:6800
	v_pk_mul_f32 v[12:13], v[12:13], v[2:3] op_sel_hi:[1,0]
	v_lshl_or_b32 v124, s10, 5, v118
	s_waitcnt vmcnt(20)
	v_pk_fma_f32 v[8:9], v[12:13], v[228:229], v[230:231]
	s_nop 0
	v_cvt_pk_bf16_f32 v14, v8, v9
	v_lshlrev_b32_e32 v12, 16, v123
	v_and_b32_e32 v13, 0xffff0000, v123
	v_pk_add_f32 v[12:13], v[12:13], v[0:1] op_sel:[0,1] neg_lo:[0,1] neg_hi:[0,1]
	ds_write_b16 v7, v14 offset:7072
	ds_write_b16_d16_hi v7, v14 offset:7344
	v_pk_mul_f32 v[12:13], v[12:13], v[2:3] op_sel_hi:[1,0]
	s_waitcnt vmcnt(18)
	v_pk_fma_f32 v[8:9], v[12:13], v[232:233], v[234:235]
	s_nop 0
	v_cvt_pk_bf16_f32 v14, v8, v9
	v_lshlrev_b32_e32 v12, 16, v121
	v_and_b32_e32 v13, 0xffff0000, v121
	v_pk_add_f32 v[12:13], v[12:13], v[0:1] op_sel:[0,1] neg_lo:[0,1] neg_hi:[0,1]
	ds_write_b16 v7, v14 offset:7616
	ds_write_b16_d16_hi v7, v14 offset:7888
	v_pk_mul_f32 v[12:13], v[12:13], v[2:3] op_sel_hi:[1,0]
	s_waitcnt vmcnt(16)
	v_pk_fma_f32 v[8:9], v[12:13], v[236:237], v[238:239]
	s_nop 0
	v_cvt_pk_bf16_f32 v14, v8, v9
	global_load_dwordx2 v[204:205], v158, s[12:13] offset:2240
	global_load_dwordx2 v[206:207], v158, s[14:15] offset:2240
	global_load_dwordx2 v[208:209], v158, s[12:13] offset:2248
	global_load_dwordx2 v[210:211], v158, s[14:15] offset:2248
	global_load_dwordx2 v[212:213], v158, s[12:13] offset:2256
	global_load_dwordx2 v[214:215], v158, s[14:15] offset:2256
	global_load_dwordx2 v[216:217], v158, s[12:13] offset:2264
	global_load_dwordx2 v[218:219], v158, s[14:15] offset:2264
	global_load_dwordx2 v[220:221], v158, s[12:13] offset:2272
	global_load_dwordx2 v[222:223], v158, s[14:15] offset:2272
	global_load_dwordx2 v[228:229], v158, s[12:13] offset:2280
	global_load_dwordx2 v[230:231], v158, s[14:15] offset:2280
	global_load_dwordx2 v[232:233], v158, s[12:13] offset:2288
	global_load_dwordx2 v[234:235], v158, s[14:15] offset:2288
	global_load_dwordx2 v[236:237], v158, s[12:13] offset:2296
	global_load_dwordx2 v[238:239], v158, s[14:15] offset:2296
	v_lshlrev_b32_e32 v12, 16, v129
	v_and_b32_e32 v13, 0xffff0000, v129
	v_pk_add_f32 v[12:13], v[12:13], v[0:1] op_sel:[0,1] neg_lo:[0,1] neg_hi:[0,1]
	ds_write_b16 v7, v14 offset:8160
	ds_write_b16_d16_hi v7, v14 offset:8432
	v_pk_mul_f32 v[12:13], v[12:13], v[2:3] op_sel_hi:[1,0]
	s_waitcnt vmcnt(30)
	v_pk_fma_f32 v[8:9], v[12:13], v[172:173], v[174:175]
	s_nop 0
	v_cvt_pk_bf16_f32 v14, v8, v9
	v_lshlrev_b32_e32 v12, 16, v128
	v_and_b32_e32 v13, 0xffff0000, v128
	v_pk_add_f32 v[12:13], v[12:13], v[0:1] op_sel:[0,1] neg_lo:[0,1] neg_hi:[0,1]
	ds_write_b16 v7, v14 offset:8704
	ds_write_b16_d16_hi v7, v14 offset:8976
	v_pk_mul_f32 v[12:13], v[12:13], v[2:3] op_sel_hi:[1,0]
	s_waitcnt vmcnt(28)
	v_pk_fma_f32 v[8:9], v[12:13], v[176:177], v[178:179]
	s_nop 0
	v_cvt_pk_bf16_f32 v14, v8, v9
	v_lshlrev_b32_e32 v12, 16, v127
	v_and_b32_e32 v13, 0xffff0000, v127
	v_pk_add_f32 v[12:13], v[12:13], v[0:1] op_sel:[0,1] neg_lo:[0,1] neg_hi:[0,1]
	ds_write_b16 v7, v14 offset:9248
	ds_write_b16_d16_hi v7, v14 offset:9520
	v_pk_mul_f32 v[12:13], v[12:13], v[2:3] op_sel_hi:[1,0]
	s_waitcnt vmcnt(26)
	v_pk_fma_f32 v[8:9], v[12:13], v[180:181], v[182:183]
	s_nop 0
	v_cvt_pk_bf16_f32 v14, v8, v9
	v_lshlrev_b32_e32 v12, 16, v125
	v_and_b32_e32 v13, 0xffff0000, v125
	v_pk_add_f32 v[12:13], v[12:13], v[0:1] op_sel:[0,1] neg_lo:[0,1] neg_hi:[0,1]
	ds_write_b16 v7, v14 offset:9792
	ds_write_b16_d16_hi v7, v14 offset:10064
	v_pk_mul_f32 v[12:13], v[12:13], v[2:3] op_sel_hi:[1,0]
	s_waitcnt vmcnt(24)
	v_pk_fma_f32 v[8:9], v[12:13], v[184:185], v[186:187]
	s_nop 0
	v_cvt_pk_bf16_f32 v14, v8, v9
	v_lshlrev_b32_e32 v12, 16, v134
	v_and_b32_e32 v13, 0xffff0000, v134
	v_pk_add_f32 v[12:13], v[12:13], v[0:1] op_sel:[0,1] neg_lo:[0,1] neg_hi:[0,1]
	ds_write_b16 v7, v14 offset:10336
	ds_write_b16_d16_hi v7, v14 offset:10608
	v_pk_mul_f32 v[12:13], v[12:13], v[2:3] op_sel_hi:[1,0]
	s_waitcnt vmcnt(22)
	v_pk_fma_f32 v[8:9], v[12:13], v[188:189], v[190:191]
	s_nop 0
	v_cvt_pk_bf16_f32 v14, v8, v9
	v_lshlrev_b32_e32 v12, 16, v132
	v_and_b32_e32 v13, 0xffff0000, v132
	v_pk_add_f32 v[12:13], v[12:13], v[0:1] op_sel:[0,1] neg_lo:[0,1] neg_hi:[0,1]
	ds_write_b16 v7, v14 offset:10880
	ds_write_b16_d16_hi v7, v14 offset:11152
	v_pk_mul_f32 v[12:13], v[12:13], v[2:3] op_sel_hi:[1,0]
	s_waitcnt vmcnt(20)
	v_pk_fma_f32 v[8:9], v[12:13], v[192:193], v[194:195]
	s_nop 0
	v_cvt_pk_bf16_f32 v14, v8, v9
	v_lshlrev_b32_e32 v12, 16, v131
	v_and_b32_e32 v13, 0xffff0000, v131
	v_pk_add_f32 v[12:13], v[12:13], v[0:1] op_sel:[0,1] neg_lo:[0,1] neg_hi:[0,1]
	ds_write_b16 v7, v14 offset:11424
	ds_write_b16_d16_hi v7, v14 offset:11696
	v_pk_mul_f32 v[12:13], v[12:13], v[2:3] op_sel_hi:[1,0]
	s_waitcnt vmcnt(18)
	v_pk_fma_f32 v[8:9], v[12:13], v[196:197], v[198:199]
	s_nop 0
	v_cvt_pk_bf16_f32 v14, v8, v9
	v_lshlrev_b32_e32 v12, 16, v130
	v_and_b32_e32 v13, 0xffff0000, v130
	v_pk_add_f32 v[12:13], v[12:13], v[0:1] op_sel:[0,1] neg_lo:[0,1] neg_hi:[0,1]
	ds_write_b16 v7, v14 offset:11968
	ds_write_b16_d16_hi v7, v14 offset:12240
	v_pk_mul_f32 v[12:13], v[12:13], v[2:3] op_sel_hi:[1,0]
	s_waitcnt vmcnt(16)
	v_pk_fma_f32 v[8:9], v[12:13], v[200:201], v[202:203]
	s_nop 0
	v_cvt_pk_bf16_f32 v14, v8, v9
	global_load_dwordx2 v[172:173], v158, s[12:13] offset:2304
	global_load_dwordx2 v[174:175], v158, s[14:15] offset:2304
	global_load_dwordx2 v[176:177], v158, s[12:13] offset:2312
	global_load_dwordx2 v[178:179], v158, s[14:15] offset:2312
	global_load_dwordx2 v[180:181], v158, s[12:13] offset:2320
	global_load_dwordx2 v[182:183], v158, s[14:15] offset:2320
	global_load_dwordx2 v[184:185], v158, s[12:13] offset:2328
	global_load_dwordx2 v[186:187], v158, s[14:15] offset:2328
	global_load_dwordx2 v[188:189], v158, s[12:13] offset:2336
	global_load_dwordx2 v[190:191], v158, s[14:15] offset:2336
	global_load_dwordx2 v[192:193], v158, s[12:13] offset:2344
	global_load_dwordx2 v[194:195], v158, s[14:15] offset:2344
	global_load_dwordx2 v[196:197], v158, s[12:13] offset:2352
	global_load_dwordx2 v[198:199], v158, s[14:15] offset:2352
	global_load_dwordx2 v[200:201], v158, s[12:13] offset:2360
	global_load_dwordx2 v[202:203], v158, s[14:15] offset:2360
	v_lshlrev_b32_e32 v12, 16, v137
	v_and_b32_e32 v13, 0xffff0000, v137
	v_pk_add_f32 v[12:13], v[12:13], v[0:1] op_sel:[0,1] neg_lo:[0,1] neg_hi:[0,1]
	ds_write_b16 v7, v14 offset:12512
	ds_write_b16_d16_hi v7, v14 offset:12784
	v_pk_mul_f32 v[12:13], v[12:13], v[2:3] op_sel_hi:[1,0]
	s_waitcnt vmcnt(30)
	v_pk_fma_f32 v[8:9], v[12:13], v[204:205], v[206:207]
	s_nop 0
	v_cvt_pk_bf16_f32 v14, v8, v9
	v_lshlrev_b32_e32 v12, 16, v136
	v_and_b32_e32 v13, 0xffff0000, v136
	v_pk_add_f32 v[12:13], v[12:13], v[0:1] op_sel:[0,1] neg_lo:[0,1] neg_hi:[0,1]
	ds_write_b16 v7, v14 offset:13056
	ds_write_b16_d16_hi v7, v14 offset:13328
	v_pk_mul_f32 v[12:13], v[12:13], v[2:3] op_sel_hi:[1,0]
	s_waitcnt vmcnt(28)
	v_pk_fma_f32 v[8:9], v[12:13], v[208:209], v[210:211]
	s_nop 0
	v_cvt_pk_bf16_f32 v14, v8, v9
	v_lshlrev_b32_e32 v12, 16, v135
	v_and_b32_e32 v13, 0xffff0000, v135
	v_pk_add_f32 v[12:13], v[12:13], v[0:1] op_sel:[0,1] neg_lo:[0,1] neg_hi:[0,1]
	ds_write_b16 v7, v14 offset:13600
	ds_write_b16_d16_hi v7, v14 offset:13872
	v_pk_mul_f32 v[12:13], v[12:13], v[2:3] op_sel_hi:[1,0]
	s_waitcnt vmcnt(26)
	v_pk_fma_f32 v[8:9], v[12:13], v[212:213], v[214:215]
	s_nop 0
	v_cvt_pk_bf16_f32 v14, v8, v9
	v_lshlrev_b32_e32 v12, 16, v133
	v_and_b32_e32 v13, 0xffff0000, v133
	v_pk_add_f32 v[12:13], v[12:13], v[0:1] op_sel:[0,1] neg_lo:[0,1] neg_hi:[0,1]
	ds_write_b16 v7, v14 offset:14144
	ds_write_b16_d16_hi v7, v14 offset:14416
	v_pk_mul_f32 v[12:13], v[12:13], v[2:3] op_sel_hi:[1,0]
	s_waitcnt vmcnt(24)
	v_pk_fma_f32 v[8:9], v[12:13], v[216:217], v[218:219]
	s_nop 0
	v_cvt_pk_bf16_f32 v14, v8, v9
	v_lshlrev_b32_e32 v12, 16, v142
	v_and_b32_e32 v13, 0xffff0000, v142
	v_pk_add_f32 v[12:13], v[12:13], v[0:1] op_sel:[0,1] neg_lo:[0,1] neg_hi:[0,1]
	ds_write_b16 v7, v14 offset:14688
	ds_write_b16_d16_hi v7, v14 offset:14960
	v_pk_mul_f32 v[12:13], v[12:13], v[2:3] op_sel_hi:[1,0]
	s_waitcnt vmcnt(22)
	v_pk_fma_f32 v[8:9], v[12:13], v[220:221], v[222:223]
	s_nop 0
	v_cvt_pk_bf16_f32 v14, v8, v9
	v_lshlrev_b32_e32 v12, 16, v140
	v_and_b32_e32 v13, 0xffff0000, v140
	v_pk_add_f32 v[12:13], v[12:13], v[0:1] op_sel:[0,1] neg_lo:[0,1] neg_hi:[0,1]
	ds_write_b16 v7, v14 offset:15232
	ds_write_b16_d16_hi v7, v14 offset:15504
	v_pk_mul_f32 v[12:13], v[12:13], v[2:3] op_sel_hi:[1,0]
	s_waitcnt vmcnt(20)
	v_pk_fma_f32 v[8:9], v[12:13], v[228:229], v[230:231]
	s_nop 0
	v_cvt_pk_bf16_f32 v14, v8, v9
	v_lshlrev_b32_e32 v12, 16, v139
	v_and_b32_e32 v13, 0xffff0000, v139
	v_pk_add_f32 v[12:13], v[12:13], v[0:1] op_sel:[0,1] neg_lo:[0,1] neg_hi:[0,1]
	ds_write_b16 v7, v14 offset:15776
	ds_write_b16_d16_hi v7, v14 offset:16048
	v_pk_mul_f32 v[12:13], v[12:13], v[2:3] op_sel_hi:[1,0]
	s_waitcnt vmcnt(18)
	v_pk_fma_f32 v[8:9], v[12:13], v[232:233], v[234:235]
	s_nop 0
	v_cvt_pk_bf16_f32 v14, v8, v9
	v_lshlrev_b32_e32 v12, 16, v138
	v_and_b32_e32 v13, 0xffff0000, v138
	v_pk_add_f32 v[12:13], v[12:13], v[0:1] op_sel:[0,1] neg_lo:[0,1] neg_hi:[0,1]
	ds_write_b16 v7, v14 offset:16320
	ds_write_b16_d16_hi v7, v14 offset:16592
	v_pk_mul_f32 v[12:13], v[12:13], v[2:3] op_sel_hi:[1,0]
	s_waitcnt vmcnt(16)
	v_pk_fma_f32 v[8:9], v[12:13], v[236:237], v[238:239]
	s_nop 0
	v_cvt_pk_bf16_f32 v14, v8, v9
	global_load_dwordx2 v[204:205], v158, s[12:13] offset:2368
	global_load_dwordx2 v[206:207], v158, s[14:15] offset:2368
	global_load_dwordx2 v[208:209], v158, s[12:13] offset:2376
	global_load_dwordx2 v[210:211], v158, s[14:15] offset:2376
	global_load_dwordx2 v[212:213], v158, s[12:13] offset:2384
	global_load_dwordx2 v[214:215], v158, s[14:15] offset:2384
	global_load_dwordx2 v[216:217], v158, s[12:13] offset:2392
	global_load_dwordx2 v[218:219], v158, s[14:15] offset:2392
	global_load_dwordx2 v[220:221], v158, s[12:13] offset:2400
	global_load_dwordx2 v[222:223], v158, s[14:15] offset:2400
	global_load_dwordx2 v[228:229], v158, s[12:13] offset:2408
	global_load_dwordx2 v[230:231], v158, s[14:15] offset:2408
	global_load_dwordx2 v[232:233], v158, s[12:13] offset:2416
	global_load_dwordx2 v[234:235], v158, s[14:15] offset:2416
	global_load_dwordx2 v[236:237], v158, s[12:13] offset:2424
	global_load_dwordx2 v[238:239], v158, s[14:15] offset:2424
	v_lshlrev_b32_e32 v12, 16, v146
	v_and_b32_e32 v13, 0xffff0000, v146
	v_pk_add_f32 v[12:13], v[12:13], v[0:1] op_sel:[0,1] neg_lo:[0,1] neg_hi:[0,1]
	ds_write_b16 v7, v14 offset:16864
	ds_write_b16_d16_hi v7, v14 offset:17136
	v_pk_mul_f32 v[12:13], v[12:13], v[2:3] op_sel_hi:[1,0]
	s_waitcnt vmcnt(30)
	v_pk_fma_f32 v[8:9], v[12:13], v[172:173], v[174:175]
	s_nop 0
	v_cvt_pk_bf16_f32 v14, v8, v9
	v_lshlrev_b32_e32 v12, 16, v144
	v_and_b32_e32 v13, 0xffff0000, v144
	v_pk_add_f32 v[12:13], v[12:13], v[0:1] op_sel:[0,1] neg_lo:[0,1] neg_hi:[0,1]
	ds_write_b16 v7, v14 offset:17408
	ds_write_b16_d16_hi v7, v14 offset:17680
	v_pk_mul_f32 v[12:13], v[12:13], v[2:3] op_sel_hi:[1,0]
	s_waitcnt vmcnt(28)
	v_pk_fma_f32 v[8:9], v[12:13], v[176:177], v[178:179]
	s_nop 0
	v_cvt_pk_bf16_f32 v14, v8, v9
	v_lshlrev_b32_e32 v12, 16, v143
	v_and_b32_e32 v13, 0xffff0000, v143
	v_pk_add_f32 v[12:13], v[12:13], v[0:1] op_sel:[0,1] neg_lo:[0,1] neg_hi:[0,1]
	ds_write_b16 v7, v14 offset:17952
	ds_write_b16_d16_hi v7, v14 offset:18224
	v_pk_mul_f32 v[12:13], v[12:13], v[2:3] op_sel_hi:[1,0]
	s_waitcnt vmcnt(26)
	v_pk_fma_f32 v[8:9], v[12:13], v[180:181], v[182:183]
	s_nop 0
	v_cvt_pk_bf16_f32 v14, v8, v9
	v_lshlrev_b32_e32 v12, 16, v141
	v_and_b32_e32 v13, 0xffff0000, v141
	v_pk_add_f32 v[12:13], v[12:13], v[0:1] op_sel:[0,1] neg_lo:[0,1] neg_hi:[0,1]
	ds_write_b16 v7, v14 offset:18496
	ds_write_b16_d16_hi v7, v14 offset:18768
	v_pk_mul_f32 v[12:13], v[12:13], v[2:3] op_sel_hi:[1,0]
	s_waitcnt vmcnt(24)
	v_pk_fma_f32 v[8:9], v[12:13], v[184:185], v[186:187]
	s_nop 0
	v_cvt_pk_bf16_f32 v14, v8, v9
	v_lshlrev_b32_e32 v12, 16, v149
	v_and_b32_e32 v13, 0xffff0000, v149
	v_pk_add_f32 v[12:13], v[12:13], v[0:1] op_sel:[0,1] neg_lo:[0,1] neg_hi:[0,1]
	ds_write_b16 v7, v14 offset:19040
	ds_write_b16_d16_hi v7, v14 offset:19312
	v_pk_mul_f32 v[12:13], v[12:13], v[2:3] op_sel_hi:[1,0]
	s_waitcnt vmcnt(22)
	v_pk_fma_f32 v[8:9], v[12:13], v[188:189], v[190:191]
	s_nop 0
	v_cvt_pk_bf16_f32 v14, v8, v9
	v_lshlrev_b32_e32 v12, 16, v148
	v_and_b32_e32 v13, 0xffff0000, v148
	v_pk_add_f32 v[12:13], v[12:13], v[0:1] op_sel:[0,1] neg_lo:[0,1] neg_hi:[0,1]
	ds_write_b16 v7, v14 offset:19584
	ds_write_b16_d16_hi v7, v14 offset:19856
	v_pk_mul_f32 v[12:13], v[12:13], v[2:3] op_sel_hi:[1,0]
	s_waitcnt vmcnt(20)
	v_pk_fma_f32 v[8:9], v[12:13], v[192:193], v[194:195]
	s_nop 0
	v_cvt_pk_bf16_f32 v14, v8, v9
	v_lshlrev_b32_e32 v12, 16, v147
	v_and_b32_e32 v13, 0xffff0000, v147
	v_pk_add_f32 v[12:13], v[12:13], v[0:1] op_sel:[0,1] neg_lo:[0,1] neg_hi:[0,1]
	ds_write_b16 v7, v14 offset:20128
	ds_write_b16_d16_hi v7, v14 offset:20400
	v_pk_mul_f32 v[12:13], v[12:13], v[2:3] op_sel_hi:[1,0]
	s_waitcnt vmcnt(18)
	v_pk_fma_f32 v[8:9], v[12:13], v[196:197], v[198:199]
	s_nop 0
	v_cvt_pk_bf16_f32 v14, v8, v9
	v_lshlrev_b32_e32 v12, 16, v145
	v_and_b32_e32 v13, 0xffff0000, v145
	v_pk_add_f32 v[12:13], v[12:13], v[0:1] op_sel:[0,1] neg_lo:[0,1] neg_hi:[0,1]
	ds_write_b16 v7, v14 offset:20672
	ds_write_b16_d16_hi v7, v14 offset:20944
	v_pk_mul_f32 v[12:13], v[12:13], v[2:3] op_sel_hi:[1,0]
	s_waitcnt vmcnt(16)
	v_pk_fma_f32 v[8:9], v[12:13], v[200:201], v[202:203]
	s_nop 0
	v_cvt_pk_bf16_f32 v14, v8, v9
	global_load_dwordx2 v[172:173], v158, s[12:13] offset:2432
	global_load_dwordx2 v[174:175], v158, s[14:15] offset:2432
	global_load_dwordx2 v[176:177], v158, s[12:13] offset:2440
	global_load_dwordx2 v[178:179], v158, s[14:15] offset:2440
	global_load_dwordx2 v[180:181], v158, s[12:13] offset:2448
	global_load_dwordx2 v[182:183], v158, s[14:15] offset:2448
	global_load_dwordx2 v[184:185], v158, s[12:13] offset:2456
	global_load_dwordx2 v[186:187], v158, s[14:15] offset:2456
	global_load_dwordx2 v[188:189], v158, s[12:13] offset:2464
	global_load_dwordx2 v[190:191], v158, s[14:15] offset:2464
	global_load_dwordx2 v[192:193], v158, s[12:13] offset:2472
	global_load_dwordx2 v[194:195], v158, s[14:15] offset:2472
	global_load_dwordx2 v[196:197], v158, s[12:13] offset:2480
	global_load_dwordx2 v[198:199], v158, s[14:15] offset:2480
	global_load_dwordx2 v[200:201], v158, s[12:13] offset:2488
	global_load_dwordx2 v[202:203], v158, s[14:15] offset:2488
	v_lshlrev_b32_e32 v12, 16, v154
	v_and_b32_e32 v13, 0xffff0000, v154
	v_pk_add_f32 v[12:13], v[12:13], v[0:1] op_sel:[0,1] neg_lo:[0,1] neg_hi:[0,1]
	ds_write_b16 v7, v14 offset:21216
	ds_write_b16_d16_hi v7, v14 offset:21488
	v_pk_mul_f32 v[12:13], v[12:13], v[2:3] op_sel_hi:[1,0]
	s_waitcnt vmcnt(30)
	v_pk_fma_f32 v[8:9], v[12:13], v[204:205], v[206:207]
	s_nop 0
	v_cvt_pk_bf16_f32 v14, v8, v9
	v_lshlrev_b32_e32 v12, 16, v152
	v_and_b32_e32 v13, 0xffff0000, v152
	v_pk_add_f32 v[12:13], v[12:13], v[0:1] op_sel:[0,1] neg_lo:[0,1] neg_hi:[0,1]
	ds_write_b16 v7, v14 offset:21760
	ds_write_b16_d16_hi v7, v14 offset:22032
	v_pk_mul_f32 v[12:13], v[12:13], v[2:3] op_sel_hi:[1,0]
	s_waitcnt vmcnt(28)
	v_pk_fma_f32 v[8:9], v[12:13], v[208:209], v[210:211]
	s_nop 0
	v_cvt_pk_bf16_f32 v14, v8, v9
	v_lshlrev_b32_e32 v12, 16, v151
	v_and_b32_e32 v13, 0xffff0000, v151
	v_pk_add_f32 v[12:13], v[12:13], v[0:1] op_sel:[0,1] neg_lo:[0,1] neg_hi:[0,1]
	ds_write_b16 v7, v14 offset:22304
	ds_write_b16_d16_hi v7, v14 offset:22576
	v_pk_mul_f32 v[12:13], v[12:13], v[2:3] op_sel_hi:[1,0]
	s_waitcnt vmcnt(26)
	v_pk_fma_f32 v[8:9], v[12:13], v[212:213], v[214:215]
	s_nop 0
	v_cvt_pk_bf16_f32 v14, v8, v9
	v_lshlrev_b32_e32 v12, 16, v150
	v_and_b32_e32 v13, 0xffff0000, v150
	v_pk_add_f32 v[12:13], v[12:13], v[0:1] op_sel:[0,1] neg_lo:[0,1] neg_hi:[0,1]
	ds_write_b16 v7, v14 offset:22848
	ds_write_b16_d16_hi v7, v14 offset:23120
	v_pk_mul_f32 v[12:13], v[12:13], v[2:3] op_sel_hi:[1,0]
	s_waitcnt vmcnt(24)
	v_pk_fma_f32 v[8:9], v[12:13], v[216:217], v[218:219]
	s_nop 0
	v_cvt_pk_bf16_f32 v14, v8, v9
	v_lshlrev_b32_e32 v12, 16, v157
	v_and_b32_e32 v13, 0xffff0000, v157
	v_pk_add_f32 v[12:13], v[12:13], v[0:1] op_sel:[0,1] neg_lo:[0,1] neg_hi:[0,1]
	ds_write_b16 v7, v14 offset:23392
	ds_write_b16_d16_hi v7, v14 offset:23664
	v_pk_mul_f32 v[12:13], v[12:13], v[2:3] op_sel_hi:[1,0]
	s_waitcnt vmcnt(22)
	v_pk_fma_f32 v[8:9], v[12:13], v[220:221], v[222:223]
	s_nop 0
	v_cvt_pk_bf16_f32 v14, v8, v9
	v_lshlrev_b32_e32 v12, 16, v156
	v_and_b32_e32 v13, 0xffff0000, v156
	v_pk_add_f32 v[12:13], v[12:13], v[0:1] op_sel:[0,1] neg_lo:[0,1] neg_hi:[0,1]
	ds_write_b16 v7, v14 offset:23936
	ds_write_b16_d16_hi v7, v14 offset:24208
	v_pk_mul_f32 v[12:13], v[12:13], v[2:3] op_sel_hi:[1,0]
	s_waitcnt vmcnt(20)
	v_pk_fma_f32 v[8:9], v[12:13], v[228:229], v[230:231]
	s_nop 0
	v_cvt_pk_bf16_f32 v14, v8, v9
	v_lshlrev_b32_e32 v12, 16, v155
	v_and_b32_e32 v13, 0xffff0000, v155
	v_pk_add_f32 v[12:13], v[12:13], v[0:1] op_sel:[0,1] neg_lo:[0,1] neg_hi:[0,1]
	ds_write_b16 v7, v14 offset:24480
	ds_write_b16_d16_hi v7, v14 offset:24752
	v_pk_mul_f32 v[12:13], v[12:13], v[2:3] op_sel_hi:[1,0]
	s_waitcnt vmcnt(18)
	v_pk_fma_f32 v[8:9], v[12:13], v[232:233], v[234:235]
	s_nop 0
	v_cvt_pk_bf16_f32 v14, v8, v9
	v_lshlrev_b32_e32 v12, 16, v153
	v_and_b32_e32 v13, 0xffff0000, v153
	v_pk_add_f32 v[12:13], v[12:13], v[0:1] op_sel:[0,1] neg_lo:[0,1] neg_hi:[0,1]
	ds_write_b16 v7, v14 offset:25024
	ds_write_b16_d16_hi v7, v14 offset:25296
	v_pk_mul_f32 v[12:13], v[12:13], v[2:3] op_sel_hi:[1,0]
	s_waitcnt vmcnt(16)
	v_pk_fma_f32 v[8:9], v[12:13], v[236:237], v[238:239]
	s_nop 0
	v_cvt_pk_bf16_f32 v14, v8, v9
	global_load_dwordx2 v[204:205], v158, s[12:13] offset:2496
	global_load_dwordx2 v[206:207], v158, s[14:15] offset:2496
	global_load_dwordx2 v[208:209], v158, s[12:13] offset:2504
	global_load_dwordx2 v[210:211], v158, s[14:15] offset:2504
	global_load_dwordx2 v[212:213], v158, s[12:13] offset:2512
	global_load_dwordx2 v[214:215], v158, s[14:15] offset:2512
	global_load_dwordx2 v[216:217], v158, s[12:13] offset:2520
	global_load_dwordx2 v[218:219], v158, s[14:15] offset:2520
	global_load_dwordx2 v[220:221], v158, s[12:13] offset:2528
	global_load_dwordx2 v[222:223], v158, s[14:15] offset:2528
	global_load_dwordx2 v[228:229], v158, s[12:13] offset:2536
	global_load_dwordx2 v[230:231], v158, s[14:15] offset:2536
	global_load_dwordx2 v[232:233], v158, s[12:13] offset:2544
	global_load_dwordx2 v[234:235], v158, s[14:15] offset:2544
	global_load_dwordx2 v[236:237], v158, s[12:13] offset:2552
	global_load_dwordx2 v[238:239], v158, s[14:15] offset:2552
	v_lshlrev_b32_e32 v12, 16, v22
	v_and_b32_e32 v13, 0xffff0000, v22
	v_pk_add_f32 v[12:13], v[12:13], v[0:1] op_sel:[0,1] neg_lo:[0,1] neg_hi:[0,1]
	ds_write_b16 v7, v14 offset:25568
	ds_write_b16_d16_hi v7, v14 offset:25840
	v_pk_mul_f32 v[12:13], v[12:13], v[2:3] op_sel_hi:[1,0]
	s_waitcnt vmcnt(30)
	v_pk_fma_f32 v[8:9], v[12:13], v[172:173], v[174:175]
	s_nop 0
	v_cvt_pk_bf16_f32 v14, v8, v9
	v_lshlrev_b32_e32 v12, 16, v20
	v_and_b32_e32 v13, 0xffff0000, v20
	v_pk_add_f32 v[12:13], v[12:13], v[0:1] op_sel:[0,1] neg_lo:[0,1] neg_hi:[0,1]
	ds_write_b16 v7, v14 offset:26112
	ds_write_b16_d16_hi v7, v14 offset:26384
	v_pk_mul_f32 v[12:13], v[12:13], v[2:3] op_sel_hi:[1,0]
	s_waitcnt vmcnt(28)
	v_pk_fma_f32 v[8:9], v[12:13], v[176:177], v[178:179]
	s_nop 0
	v_cvt_pk_bf16_f32 v14, v8, v9
	v_lshlrev_b32_e32 v12, 16, v19
	v_and_b32_e32 v13, 0xffff0000, v19
	v_pk_add_f32 v[12:13], v[12:13], v[0:1] op_sel:[0,1] neg_lo:[0,1] neg_hi:[0,1]
	ds_write_b16 v7, v14 offset:26656
	ds_write_b16_d16_hi v7, v14 offset:26928
	v_pk_mul_f32 v[12:13], v[12:13], v[2:3] op_sel_hi:[1,0]
	s_waitcnt vmcnt(26)
	v_pk_fma_f32 v[8:9], v[12:13], v[180:181], v[182:183]
	s_nop 0
	v_cvt_pk_bf16_f32 v14, v8, v9
	v_lshlrev_b32_e32 v12, 16, v18
	v_and_b32_e32 v13, 0xffff0000, v18
	v_pk_add_f32 v[12:13], v[12:13], v[0:1] op_sel:[0,1] neg_lo:[0,1] neg_hi:[0,1]
	ds_write_b16 v7, v14 offset:27200
	ds_write_b16_d16_hi v7, v14 offset:27472
	v_pk_mul_f32 v[12:13], v[12:13], v[2:3] op_sel_hi:[1,0]
	s_waitcnt vmcnt(24)
	v_pk_fma_f32 v[8:9], v[12:13], v[184:185], v[186:187]
	s_nop 0
	v_cvt_pk_bf16_f32 v14, v8, v9
	v_lshlrev_b32_e32 v12, 16, v26
	v_and_b32_e32 v13, 0xffff0000, v26
	v_pk_add_f32 v[12:13], v[12:13], v[0:1] op_sel:[0,1] neg_lo:[0,1] neg_hi:[0,1]
	ds_write_b16 v7, v14 offset:27744
	ds_write_b16_d16_hi v7, v14 offset:28016
	v_pk_mul_f32 v[12:13], v[12:13], v[2:3] op_sel_hi:[1,0]
	s_waitcnt vmcnt(22)
	v_pk_fma_f32 v[8:9], v[12:13], v[188:189], v[190:191]
	s_nop 0
	v_cvt_pk_bf16_f32 v14, v8, v9
	v_lshlrev_b32_e32 v12, 16, v24
	v_and_b32_e32 v13, 0xffff0000, v24
	v_pk_add_f32 v[12:13], v[12:13], v[0:1] op_sel:[0,1] neg_lo:[0,1] neg_hi:[0,1]
	ds_write_b16 v7, v14 offset:28288
	ds_write_b16_d16_hi v7, v14 offset:28560
	v_pk_mul_f32 v[12:13], v[12:13], v[2:3] op_sel_hi:[1,0]
	s_waitcnt vmcnt(20)
	v_pk_fma_f32 v[8:9], v[12:13], v[192:193], v[194:195]
	s_nop 0
	v_cvt_pk_bf16_f32 v14, v8, v9
	v_lshlrev_b32_e32 v12, 16, v23
	v_and_b32_e32 v13, 0xffff0000, v23
	v_pk_add_f32 v[12:13], v[12:13], v[0:1] op_sel:[0,1] neg_lo:[0,1] neg_hi:[0,1]
	ds_write_b16 v7, v14 offset:28832
	ds_write_b16_d16_hi v7, v14 offset:29104
	v_pk_mul_f32 v[12:13], v[12:13], v[2:3] op_sel_hi:[1,0]
	s_waitcnt vmcnt(18)
	v_pk_fma_f32 v[8:9], v[12:13], v[196:197], v[198:199]
	s_nop 0
	v_cvt_pk_bf16_f32 v14, v8, v9
	v_lshlrev_b32_e32 v12, 16, v21
	v_and_b32_e32 v13, 0xffff0000, v21
	v_pk_add_f32 v[12:13], v[12:13], v[0:1] op_sel:[0,1] neg_lo:[0,1] neg_hi:[0,1]
	ds_write_b16 v7, v14 offset:29376
	ds_write_b16_d16_hi v7, v14 offset:29648
	v_pk_mul_f32 v[12:13], v[12:13], v[2:3] op_sel_hi:[1,0]
	s_waitcnt vmcnt(16)
	v_pk_fma_f32 v[8:9], v[12:13], v[200:201], v[202:203]
	s_nop 0
	v_cvt_pk_bf16_f32 v14, v8, v9
	v_lshlrev_b32_e32 v12, 16, v29
	v_and_b32_e32 v13, 0xffff0000, v29
	v_pk_add_f32 v[12:13], v[12:13], v[0:1] op_sel:[0,1] neg_lo:[0,1] neg_hi:[0,1]
	ds_write_b16 v7, v14 offset:29920
	ds_write_b16_d16_hi v7, v14 offset:30192
	v_pk_mul_f32 v[12:13], v[12:13], v[2:3] op_sel_hi:[1,0]
	s_waitcnt vmcnt(14)
	v_pk_fma_f32 v[8:9], v[12:13], v[204:205], v[206:207]
	s_nop 0
	v_cvt_pk_bf16_f32 v14, v8, v9
	v_lshlrev_b32_e32 v12, 16, v28
	v_and_b32_e32 v13, 0xffff0000, v28
	v_pk_add_f32 v[12:13], v[12:13], v[0:1] op_sel:[0,1] neg_lo:[0,1] neg_hi:[0,1]
	ds_write_b16 v7, v14 offset:30464
	ds_write_b16_d16_hi v7, v14 offset:30736
	v_pk_mul_f32 v[12:13], v[12:13], v[2:3] op_sel_hi:[1,0]
	s_waitcnt vmcnt(12)
	v_pk_fma_f32 v[8:9], v[12:13], v[208:209], v[210:211]
	s_nop 0
	v_cvt_pk_bf16_f32 v14, v8, v9
	v_lshlrev_b32_e32 v12, 16, v27
	v_and_b32_e32 v13, 0xffff0000, v27
	v_pk_add_f32 v[12:13], v[12:13], v[0:1] op_sel:[0,1] neg_lo:[0,1] neg_hi:[0,1]
	ds_write_b16 v7, v14 offset:31008
	ds_write_b16_d16_hi v7, v14 offset:31280
	v_pk_mul_f32 v[12:13], v[12:13], v[2:3] op_sel_hi:[1,0]
	s_waitcnt vmcnt(10)
	v_pk_fma_f32 v[8:9], v[12:13], v[212:213], v[214:215]
	s_nop 0
	v_cvt_pk_bf16_f32 v14, v8, v9
	v_lshlrev_b32_e32 v12, 16, v25
	v_and_b32_e32 v13, 0xffff0000, v25
	v_pk_add_f32 v[12:13], v[12:13], v[0:1] op_sel:[0,1] neg_lo:[0,1] neg_hi:[0,1]
	ds_write_b16 v7, v14 offset:31552
	ds_write_b16_d16_hi v7, v14 offset:31824
	v_pk_mul_f32 v[12:13], v[12:13], v[2:3] op_sel_hi:[1,0]
	s_waitcnt vmcnt(8)
	v_pk_fma_f32 v[8:9], v[12:13], v[216:217], v[218:219]
	s_nop 0
	v_cvt_pk_bf16_f32 v14, v8, v9
	v_lshlrev_b32_e32 v12, 16, v6
	v_and_b32_e32 v13, 0xffff0000, v6
	v_pk_add_f32 v[12:13], v[12:13], v[0:1] op_sel:[0,1] neg_lo:[0,1] neg_hi:[0,1]
	ds_write_b16 v7, v14 offset:32096
	ds_write_b16_d16_hi v7, v14 offset:32368
	v_pk_mul_f32 v[12:13], v[12:13], v[2:3] op_sel_hi:[1,0]
	v_lshlrev_b32_e32 v14, 16, v3
	s_waitcnt vmcnt(6)
	v_pk_fma_f32 v[8:9], v[12:13], v[220:221], v[222:223]
	s_nop 0
	v_cvt_pk_bf16_f32 v6, v8, v9
	v_lshlrev_b32_e32 v12, 16, v5
	v_and_b32_e32 v13, 0xffff0000, v5
	v_pk_add_f32 v[12:13], v[12:13], v[0:1] op_sel:[0,1] neg_lo:[0,1] neg_hi:[0,1]
	ds_write_b16 v7, v6 offset:32640
	ds_write_b16_d16_hi v7, v6 offset:32912
	v_pk_mul_f32 v[12:13], v[12:13], v[2:3] op_sel_hi:[1,0]
	s_waitcnt vmcnt(4)
	v_pk_fma_f32 v[8:9], v[12:13], v[228:229], v[230:231]
	s_nop 0
	v_cvt_pk_bf16_f32 v6, v8, v9
	v_lshlrev_b32_e32 v12, 16, v4
	v_and_b32_e32 v13, 0xffff0000, v4
	v_pk_add_f32 v[4:5], v[12:13], v[0:1] op_sel:[0,1] neg_lo:[0,1] neg_hi:[0,1]
	ds_write_b16 v7, v6 offset:33184
	ds_write_b16_d16_hi v7, v6 offset:33456
	v_pk_mul_f32 v[4:5], v[4:5], v[2:3] op_sel_hi:[1,0]
	v_pk_add_f32 v[0:1], v[14:15], v[0:1] op_sel:[0,1] neg_lo:[0,1] neg_hi:[0,1]
	s_waitcnt vmcnt(2)
	v_pk_fma_f32 v[4:5], v[4:5], v[232:233], v[234:235]
	s_nop 0
	v_cvt_pk_bf16_f32 v6, v4, v5
	s_mov_b64 s[12:13], 0x40000
	v_or_b32_e32 v10, s43, v124
	v_lshl_add_u64 v[8:9], s[16:17], 0, v[88:89]
	v_pk_mul_f32 v[0:1], v[0:1], v[2:3] op_sel_hi:[1,0]
	v_lshlrev_b32_e32 v88, 9, v10
	v_lshl_add_u64 v[90:91], v[8:9], 0, s[12:13]
	v_lshl_add_u64 v[8:9], v[90:91], 0, v[88:89]
	ds_write_b16 v7, v6 offset:33728
	ds_write_b16_d16_hi v7, v6 offset:34000
	s_cselect_b64 s[14:15], -1, 0
	s_cmp_lg_u32 s11, 0
	s_cselect_b64 s[12:13], -1, 0
	s_and_b64 vcc, exec, s[14:15]
	s_waitcnt vmcnt(0)
	v_pk_fma_f32 v[0:1], v[0:1], v[236:237], v[238:239]
	s_nop 0
	v_cvt_pk_bf16_f32 v0, v0, v1
	ds_write_b16 v7, v0 offset:34272
	ds_write_b16_d16_hi v7, v0 offset:34544
	s_waitcnt lgkmcnt(0)
	s_barrier
	global_load_dwordx4 v[0:3], v[8:9], off offset:16
	global_load_dwordx4 v[4:7], v[8:9], off
	global_load_dwordx4 v[80:83], v[8:9], off offset:80
	global_load_dwordx4 v[84:87], v[8:9], off offset:64
	s_cbranch_vccnz .LBB0_1274
	global_load_dwordx4 v[76:79], v[8:9], off offset:128
	global_load_dwordx4 v[72:75], v[8:9], off offset:144
